# K-loop load segments: ds_reads issued first, scalar setup and LDS-DMA loads after (on top of VALU-free saddr segments)
# baseline (speedup 1.0000x reference)
; #define PG8_STAGE(bufoff, gbase, voff) do { _Pragma("unroll") for (int _i = 0; _i < 2; ++_i) \
;         __builtin_amdgcn_global_load_lds((const unsigned*)((const char*)(gbase) + (voff)[_i]), (PG8_LAS unsigned*)(lds + (bufoff) + ldsw + _i * 8192), 16, 0, 0); } while (0)
; #define PG8_LDA(dst, b, h) do { _Pragma("unroll") for (int m = 0; m < 4; ++m) _Pragma("unroll") for (int k = 0; k < 2; ++k) dst[m][k] = *(const PG8_LAS bf16x8*)(lds + PG8_SA(b, h) + aoff + m * 2048 + k * 1024); } while (0)
; #define PG8_LDB(dst, b, h) do { _Pragma("unroll") for (int n = 0; n < 2; ++n) _Pragma("unroll") for (int k = 0; k < 2; ++k) dst[n][k] = *(const PG8_LAS bf16x8*)(lds + PG8_SB(b, h) + boff + n * 2048 + k * 1024); } while (0)
; #define PG8_MMA(ai, bj, At, Bt) do { __builtin_amdgcn_s_setprio(1); _Pragma("unroll") for (int m = 0; m < 4; ++m) _Pragma("unroll") for (int n = 0; n < 2; ++n) _Pragma("unroll") for (int k = 0; k < 2; ++k) \
;         acc[ai][bj][m][n] = __builtin_amdgcn_mfma_f32_16x16x32_bf16(Bt[n][k], At[m][k], acc[ai][bj][m][n], 0, 0, 0); __builtin_amdgcn_s_setprio(0); } while (0)
; #define PG8_WAIT_V(n) asm volatile("s_waitcnt vmcnt(" #n ")" ::: "memory")
; #define PG8_WAIT_L(n) asm volatile("s_waitcnt lgkmcnt(" #n ")" ::: "memory")
; #define PG8_BAR __builtin_amdgcn_s_barrier()
; #define PG8_SCHED __builtin_amdgcn_sched_barrier(0)
; template <class Epi, class Sched, bool ALIGN_EPI = false, bool SP2 = false>
; __device__ __forceinline__ void gemm_phase(PG8_LAS unsigned char* lds, const Gemm g, const Sched& S, const Epi& E, const int wave0) {
;     ...
;             PG8_LDB(B0, 0, 0); PG8_LDB(B1, 0, 1); PG8_SCHED; PG8_LDA(At, 0, 0); PG8_STAGE(PG8_SA(1, 1), a1 + hstepA, voffA);
;             PG8_WAIT_V(8); PG8_WAIT_L(0); PG8_BAR; PG8_MMA(0, 0, At, B0); PG8_MMA(0, 1, At, B1); PG8_BAR; PG8_SCHED;
;             PG8_LDA(At, 0, 1); PG8_STAGE(PG8_SB(0, 0), b2, voffB); PG8_STAGE(PG8_SB(0, 1), b2 + hstepB, voffB); PG8_STAGE(PG8_SA(0, 0), a2, voffA);
;             PG8_WAIT_V(8); PG8_WAIT_L(0); PG8_BAR; PG8_MMA(1, 0, At, B0); PG8_MMA(1, 1, At, B1); PG8_BAR; PG8_SCHED;
.LBB0_316:
	ds_read_b128 v[144:147], v252
	ds_read_b128 v[148:151], v252 offset:1024
	ds_read_b128 v[152:155], v252 offset:2048
	ds_read_b128 v[156:159], v252 offset:3072
	ds_read_b128 v[178:181], v253
	ds_read_b128 v[182:185], v253 offset:1024
	ds_read_b128 v[186:189], v253 offset:2048
	ds_read_b128 v[190:193], v253 offset:3072
	ds_read_b128 v[194:197], v143
	ds_read_b128 v[208:211], v143 offset:1024
	ds_read_b128 v[212:215], v143 offset:2048
	ds_read_b128 v[216:219], v143 offset:3072
	ds_read_b128 v[220:223], v143 offset:4096
	ds_read_b128 v[224:227], v143 offset:5120
	ds_read_b128 v[228:231], v143 offset:6144
	ds_read_b128 v[232:235], v143 offset:7168
	s_add_u32 s16, s0, 0xfff80080
	s_addc_u32 s17, s1, -1
	s_add_i32 s38, 0, 0x10000
	s_cmp_eq_u32 s37, 28
	s_cselect_b32 s19, s11, s17
	s_cselect_b32 s18, s33, s16
	s_cselect_b32 s17, s9, s36
	s_cselect_b32 s16, s34, s35
	s_add_i32 s40, 0, 0x14000
	s_add_i32 m0, s23, 0xc000
	s_nop 0
	global_load_lds_dwordx4 v136, s[0:1]
	s_add_i32 m0, s23, 0xe000
	s_nop 0
	global_load_lds_dwordx4 v138, s[0:1]
	s_waitcnt vmcnt(8)
	s_waitcnt lgkmcnt(0)
	s_barrier
	s_setprio 1
	s_waitcnt lgkmcnt(0)
	v_mfma_f32_16x16x32_bf16 v[126:129], v[144:147], v[194:197], v[126:129]
	v_mfma_f32_16x16x32_bf16 v[122:125], v[152:155], v[194:197], v[122:125]
	v_mfma_f32_16x16x32_bf16 v[118:121], v[144:147], v[212:215], v[118:121]
	v_mfma_f32_16x16x32_bf16 v[114:117], v[152:155], v[212:215], v[114:117]
	v_mfma_f32_16x16x32_bf16 v[102:105], v[144:147], v[220:223], v[102:105]
	v_mfma_f32_16x16x32_bf16 v[98:101], v[152:155], v[220:223], v[98:101]
	v_mfma_f32_16x16x32_bf16 v[86:89], v[144:147], v[228:231], v[86:89]
	v_mfma_f32_16x16x32_bf16 v[82:85], v[152:155], v[228:231], v[82:85]
	v_mfma_f32_16x16x32_bf16 v[126:129], v[148:151], v[208:211], v[126:129]
	v_mfma_f32_16x16x32_bf16 v[122:125], v[156:159], v[208:211], v[122:125]
	v_mfma_f32_16x16x32_bf16 v[118:121], v[148:151], v[216:219], v[118:121]
	v_mfma_f32_16x16x32_bf16 v[114:117], v[156:159], v[216:219], v[114:117]
	v_mfma_f32_16x16x32_bf16 v[102:105], v[148:151], v[224:227], v[102:105]
	v_mfma_f32_16x16x32_bf16 v[98:101], v[156:159], v[224:227], v[98:101]
	v_mfma_f32_16x16x32_bf16 v[86:89], v[148:151], v[232:235], v[86:89]
	v_mfma_f32_16x16x32_bf16 v[82:85], v[156:159], v[232:235], v[82:85]
	s_setprio 0
	s_setprio 1
	v_mfma_f32_16x16x32_bf16 v[110:113], v[178:181], v[194:197], v[110:113]
	v_mfma_f32_16x16x32_bf16 v[106:109], v[186:189], v[194:197], v[106:109]
	v_mfma_f32_16x16x32_bf16 v[94:97], v[178:181], v[212:215], v[94:97]
	v_mfma_f32_16x16x32_bf16 v[90:93], v[186:189], v[212:215], v[90:93]
	v_mfma_f32_16x16x32_bf16 v[78:81], v[178:181], v[220:223], v[78:81]
	v_mfma_f32_16x16x32_bf16 v[74:77], v[186:189], v[220:223], v[74:77]
	v_mfma_f32_16x16x32_bf16 v[70:73], v[178:181], v[228:231], v[70:73]
	v_mfma_f32_16x16x32_bf16 v[66:69], v[186:189], v[228:231], v[66:69]
	v_mfma_f32_16x16x32_bf16 v[110:113], v[182:185], v[208:211], v[110:113]
	v_mfma_f32_16x16x32_bf16 v[106:109], v[190:193], v[208:211], v[106:109]
	v_mfma_f32_16x16x32_bf16 v[94:97], v[182:185], v[216:219], v[94:97]
	v_mfma_f32_16x16x32_bf16 v[90:93], v[190:193], v[216:219], v[90:93]
	v_mfma_f32_16x16x32_bf16 v[78:81], v[182:185], v[224:227], v[78:81]
	v_mfma_f32_16x16x32_bf16 v[74:77], v[190:193], v[224:227], v[74:77]
	v_mfma_f32_16x16x32_bf16 v[70:73], v[182:185], v[232:235], v[70:73]
	v_mfma_f32_16x16x32_bf16 v[66:69], v[190:193], v[232:235], v[66:69]
	s_setprio 0
	s_barrier
	ds_read_b128 v[194:197], v143 offset:16384
	ds_read_b128 v[208:211], v143 offset:17408
	ds_read_b128 v[212:215], v143 offset:18432
	ds_read_b128 v[216:219], v143 offset:19456
	ds_read_b128 v[220:223], v143 offset:20480
	ds_read_b128 v[224:227], v143 offset:21504
	ds_read_b128 v[228:231], v143 offset:22528
	ds_read_b128 v[232:235], v143 offset:23552
	s_add_i32 s38, s38, s22
	s_mov_b32 m0, s38
	s_nop 0
	global_load_lds_dwordx4 v64, s[16:17]
	s_add_i32 m0, s38, 0x2000
	s_add_u32 s38, s16, 0x80000
	s_addc_u32 s39, s17, 0
	s_add_i32 s40, s40, s22
	global_load_lds_dwordx4 v130, s[16:17]
	s_mov_b32 m0, s40
	s_mov_b64 s[100:101], s[18:19]
	global_load_lds_dwordx4 v64, s[38:39]
	s_add_i32 m0, s40, 0x2000
	s_nop 0
	global_load_lds_dwordx4 v130, s[38:39]
	s_mov_b32 m0, s23
	s_nop 0
	global_load_lds_dwordx4 v134, s[18:19]
	s_mov_b32 m0, s24
	s_nop 0
	global_load_lds_dwordx4 v132, s[18:19]
	s_waitcnt vmcnt(8)
	s_waitcnt lgkmcnt(0)
	s_barrier
	s_setprio 1
	s_waitcnt lgkmcnt(0)
	v_mfma_f32_16x16x32_bf16 v[60:63], v[144:147], v[194:197], v[60:63]
	v_mfma_f32_16x16x32_bf16 v[56:59], v[152:155], v[194:197], v[56:59]
	v_mfma_f32_16x16x32_bf16 v[52:55], v[144:147], v[212:215], v[52:55]
	v_mfma_f32_16x16x32_bf16 v[48:51], v[152:155], v[212:215], v[48:51]
	v_mfma_f32_16x16x32_bf16 v[36:39], v[144:147], v[220:223], v[36:39]
	v_mfma_f32_16x16x32_bf16 v[32:35], v[152:155], v[220:223], v[32:35]
	v_mfma_f32_16x16x32_bf16 v[20:23], v[144:147], v[228:231], v[20:23]
	v_mfma_f32_16x16x32_bf16 v[16:19], v[152:155], v[228:231], v[16:19]
	v_mfma_f32_16x16x32_bf16 v[60:63], v[148:151], v[208:211], v[60:63]
	v_mfma_f32_16x16x32_bf16 v[56:59], v[156:159], v[208:211], v[56:59]
	v_mfma_f32_16x16x32_bf16 v[52:55], v[148:151], v[216:219], v[52:55]
	v_mfma_f32_16x16x32_bf16 v[48:51], v[156:159], v[216:219], v[48:51]
	v_mfma_f32_16x16x32_bf16 v[36:39], v[148:151], v[224:227], v[36:39]
	v_mfma_f32_16x16x32_bf16 v[32:35], v[156:159], v[224:227], v[32:35]
	v_mfma_f32_16x16x32_bf16 v[20:23], v[148:151], v[232:235], v[20:23]
	v_mfma_f32_16x16x32_bf16 v[16:19], v[156:159], v[232:235], v[16:19]
	s_setprio 0
	s_setprio 1
	v_mfma_f32_16x16x32_bf16 v[44:47], v[178:181], v[194:197], v[44:47]
	v_mfma_f32_16x16x32_bf16 v[40:43], v[186:189], v[194:197], v[40:43]
	v_mfma_f32_16x16x32_bf16 v[28:31], v[178:181], v[212:215], v[28:31]
	v_mfma_f32_16x16x32_bf16 v[24:27], v[186:189], v[212:215], v[24:27]
	v_mfma_f32_16x16x32_bf16 v[12:15], v[178:181], v[220:223], v[12:15]
	v_mfma_f32_16x16x32_bf16 v[8:11], v[186:189], v[220:223], v[8:11]
	v_mfma_f32_16x16x32_bf16 v[4:7], v[178:181], v[228:231], v[4:7]
	v_mfma_f32_16x16x32_bf16 v[0:3], v[186:189], v[228:231], v[0:3]
	v_mfma_f32_16x16x32_bf16 v[44:47], v[182:185], v[208:211], v[44:47]
	v_mfma_f32_16x16x32_bf16 v[40:43], v[190:193], v[208:211], v[40:43]
	v_mfma_f32_16x16x32_bf16 v[28:31], v[182:185], v[216:219], v[28:31]
	v_mfma_f32_16x16x32_bf16 v[24:27], v[190:193], v[216:219], v[24:27]
	v_mfma_f32_16x16x32_bf16 v[12:15], v[182:185], v[224:227], v[12:15]
	v_mfma_f32_16x16x32_bf16 v[8:11], v[190:193], v[224:227], v[8:11]
	v_mfma_f32_16x16x32_bf16 v[4:7], v[182:185], v[232:235], v[4:7]
	v_mfma_f32_16x16x32_bf16 v[0:3], v[190:193], v[232:235], v[0:3]
	s_setprio 0
	s_barrier
; #define PG8_STAGE(bufoff, gbase, voff) do { _Pragma("unroll") for (int _i = 0; _i < 2; ++_i) \
;         __builtin_amdgcn_global_load_lds((const unsigned*)((const char*)(gbase) + (voff)[_i]), (PG8_LAS unsigned*)(lds + (bufoff) + ldsw + _i * 8192), 16, 0, 0); } while (0)
; #define PG8_LDA(dst, b, h) do { _Pragma("unroll") for (int m = 0; m < 4; ++m) _Pragma("unroll") for (int k = 0; k < 2; ++k) dst[m][k] = *(const PG8_LAS bf16x8*)(lds + PG8_SA(b, h) + aoff + m * 2048 + k * 1024); } while (0)
; #define PG8_LDB(dst, b, h) do { _Pragma("unroll") for (int n = 0; n < 2; ++n) _Pragma("unroll") for (int k = 0; k < 2; ++k) dst[n][k] = *(const PG8_LAS bf16x8*)(lds + PG8_SB(b, h) + boff + n * 2048 + k * 1024); } while (0)
; #define PG8_MMA(ai, bj, At, Bt) do { __builtin_amdgcn_s_setprio(1); _Pragma("unroll") for (int m = 0; m < 4; ++m) _Pragma("unroll") for (int n = 0; n < 2; ++n) _Pragma("unroll") for (int k = 0; k < 2; ++k) \
;         acc[ai][bj][m][n] = __builtin_amdgcn_mfma_f32_16x16x32_bf16(Bt[n][k], At[m][k], acc[ai][bj][m][n], 0, 0, 0); __builtin_amdgcn_s_setprio(0); } while (0)
; #define PG8_WAIT_V(n) asm volatile("s_waitcnt vmcnt(" #n ")" ::: "memory")
; #define PG8_WAIT_L(n) asm volatile("s_waitcnt lgkmcnt(" #n ")" ::: "memory")
; #define PG8_BAR __builtin_amdgcn_s_barrier()
; #define PG8_SCHED __builtin_amdgcn_sched_barrier(0)
; template <class Epi, class Sched, bool ALIGN_EPI = false, bool SP2 = false>
; __device__ __forceinline__ void gemm_phase(PG8_LAS unsigned char* lds, const Gemm g, const Sched& S, const Epi& E, const int wave0) {
;     ...
;             PG8_LDB(B0, 1, 0); PG8_LDB(B1, 1, 1); PG8_SCHED; PG8_LDA(At, 1, 0); PG8_STAGE(PG8_SA(0, 1), a2 + hstepA, voffA);
;             PG8_WAIT_V(8); PG8_WAIT_L(0); PG8_BAR; PG8_MMA(0, 0, At, B0); PG8_MMA(0, 1, At, B1); PG8_BAR; PG8_SCHED;
;             PG8_LDA(At, 1, 1); PG8_STAGE(PG8_SB(1, 0), b3, voffB); PG8_STAGE(PG8_SB(1, 1), b3 + hstepB, voffB); PG8_STAGE(PG8_SA(1, 0), a3, voffA);
;             PG8_WAIT_V(8); PG8_WAIT_L(0); PG8_BAR; PG8_MMA(1, 0, At, B0); PG8_MMA(1, 1, At, B1); PG8_BAR; PG8_SCHED;
	ds_read_b128 v[144:147], v254
	ds_read_b128 v[148:151], v254 offset:1024
	ds_read_b128 v[152:155], v254 offset:2048
	ds_read_b128 v[156:159], v254 offset:3072
	ds_read_b128 v[178:181], v255
	ds_read_b128 v[182:185], v255 offset:1024
	ds_read_b128 v[186:189], v255 offset:2048
	ds_read_b128 v[190:193], v255 offset:3072
	ds_read_b128 v[194:197], v143 offset:32768
	ds_read_b128 v[208:211], v143 offset:33792
	ds_read_b128 v[212:215], v143 offset:34816
	ds_read_b128 v[216:219], v143 offset:35840
	ds_read_b128 v[220:223], v143 offset:36864
	ds_read_b128 v[224:227], v143 offset:37888
	ds_read_b128 v[228:231], v143 offset:38912
	ds_read_b128 v[232:235], v143 offset:39936
	s_add_i32 s38, 0, 0x18000
	s_add_i32 s39, 0, 0x1c000
	s_add_u32 s18, s18, 0x80000
	s_addc_u32 s19, s19, 0
	s_mov_b32 m0, s25
	s_nop 0
	global_load_lds_dwordx4 v134, s[18:19]
	s_mov_b32 m0, s26
	s_nop 0
	global_load_lds_dwordx4 v132, s[18:19]
	s_waitcnt vmcnt(8)
	s_waitcnt lgkmcnt(0)
	s_barrier
	s_setprio 1
	s_waitcnt lgkmcnt(0)
	v_mfma_f32_16x16x32_bf16 v[126:129], v[144:147], v[194:197], v[126:129]
	v_mfma_f32_16x16x32_bf16 v[122:125], v[152:155], v[194:197], v[122:125]
	v_mfma_f32_16x16x32_bf16 v[118:121], v[144:147], v[212:215], v[118:121]
	v_mfma_f32_16x16x32_bf16 v[114:117], v[152:155], v[212:215], v[114:117]
	v_mfma_f32_16x16x32_bf16 v[102:105], v[144:147], v[220:223], v[102:105]
	v_mfma_f32_16x16x32_bf16 v[98:101], v[152:155], v[220:223], v[98:101]
	v_mfma_f32_16x16x32_bf16 v[86:89], v[144:147], v[228:231], v[86:89]
	v_mfma_f32_16x16x32_bf16 v[82:85], v[152:155], v[228:231], v[82:85]
	v_mfma_f32_16x16x32_bf16 v[126:129], v[148:151], v[208:211], v[126:129]
	v_mfma_f32_16x16x32_bf16 v[122:125], v[156:159], v[208:211], v[122:125]
	v_mfma_f32_16x16x32_bf16 v[118:121], v[148:151], v[216:219], v[118:121]
	v_mfma_f32_16x16x32_bf16 v[114:117], v[156:159], v[216:219], v[114:117]
	v_mfma_f32_16x16x32_bf16 v[102:105], v[148:151], v[224:227], v[102:105]
	v_mfma_f32_16x16x32_bf16 v[98:101], v[156:159], v[224:227], v[98:101]
	v_mfma_f32_16x16x32_bf16 v[86:89], v[148:151], v[232:235], v[86:89]
	v_mfma_f32_16x16x32_bf16 v[82:85], v[156:159], v[232:235], v[82:85]
	s_setprio 0
	s_setprio 1
	v_mfma_f32_16x16x32_bf16 v[110:113], v[178:181], v[194:197], v[110:113]
	v_mfma_f32_16x16x32_bf16 v[106:109], v[186:189], v[194:197], v[106:109]
	v_mfma_f32_16x16x32_bf16 v[94:97], v[178:181], v[212:215], v[94:97]
	v_mfma_f32_16x16x32_bf16 v[90:93], v[186:189], v[212:215], v[90:93]
	v_mfma_f32_16x16x32_bf16 v[78:81], v[178:181], v[220:223], v[78:81]
	v_mfma_f32_16x16x32_bf16 v[74:77], v[186:189], v[220:223], v[74:77]
	v_mfma_f32_16x16x32_bf16 v[70:73], v[178:181], v[228:231], v[70:73]
	v_mfma_f32_16x16x32_bf16 v[66:69], v[186:189], v[228:231], v[66:69]
	v_mfma_f32_16x16x32_bf16 v[110:113], v[182:185], v[208:211], v[110:113]
	v_mfma_f32_16x16x32_bf16 v[106:109], v[190:193], v[208:211], v[106:109]
	v_mfma_f32_16x16x32_bf16 v[94:97], v[182:185], v[216:219], v[94:97]
	v_mfma_f32_16x16x32_bf16 v[90:93], v[190:193], v[216:219], v[90:93]
	v_mfma_f32_16x16x32_bf16 v[78:81], v[182:185], v[224:227], v[78:81]
	v_mfma_f32_16x16x32_bf16 v[74:77], v[190:193], v[224:227], v[74:77]
	v_mfma_f32_16x16x32_bf16 v[70:73], v[182:185], v[232:235], v[70:73]
	v_mfma_f32_16x16x32_bf16 v[66:69], v[190:193], v[232:235], v[66:69]
	s_setprio 0
	s_barrier
	ds_read_b128 v[194:197], v143 offset:49152
	ds_read_b128 v[208:211], v143 offset:50176
	ds_read_b128 v[212:215], v143 offset:51200
	ds_read_b128 v[216:219], v143 offset:52224
	ds_read_b128 v[220:223], v143 offset:53248
	ds_read_b128 v[224:227], v143 offset:54272
	ds_read_b128 v[228:231], v143 offset:55296
	ds_read_b128 v[232:235], v143 offset:56320
	s_add_i32 s18, s38, s22
	s_add_u32 s42, s16, 0x80
	s_addc_u32 s43, s17, 0
	s_mov_b32 m0, s18
	s_nop 0
	global_load_lds_dwordx4 v64, s[42:43]
	s_add_i32 m0, s18, 0x2000
	s_add_u32 s16, s16, 0x80080
	s_addc_u32 s17, s17, 0
	s_add_i32 s18, s39, s22
	global_load_lds_dwordx4 v130, s[42:43]
	s_mov_b32 m0, s18
	s_nop 0
	global_load_lds_dwordx4 v64, s[16:17]
	s_add_i32 m0, s18, 0x2000
	s_nop 0
	global_load_lds_dwordx4 v130, s[16:17]
	s_add_u32 s100, s100, 0x80
	s_addc_u32 s101, s101, 0
	s_mov_b32 m0, s27
	s_nop 0
	global_load_lds_dwordx4 v134, s[100:101]
	s_mov_b32 m0, s28
	s_nop 0
	global_load_lds_dwordx4 v132, s[100:101]
	s_waitcnt vmcnt(8)
	s_waitcnt lgkmcnt(0)
	s_barrier
	s_setprio 1
	s_waitcnt lgkmcnt(0)
	v_mfma_f32_16x16x32_bf16 v[60:63], v[144:147], v[194:197], v[60:63]
	v_mfma_f32_16x16x32_bf16 v[56:59], v[152:155], v[194:197], v[56:59]
	v_mfma_f32_16x16x32_bf16 v[52:55], v[144:147], v[212:215], v[52:55]
	v_mfma_f32_16x16x32_bf16 v[48:51], v[152:155], v[212:215], v[48:51]
	v_mfma_f32_16x16x32_bf16 v[36:39], v[144:147], v[220:223], v[36:39]
	v_mfma_f32_16x16x32_bf16 v[32:35], v[152:155], v[220:223], v[32:35]
	v_mfma_f32_16x16x32_bf16 v[20:23], v[144:147], v[228:231], v[20:23]
	v_mfma_f32_16x16x32_bf16 v[16:19], v[152:155], v[228:231], v[16:19]
	v_mfma_f32_16x16x32_bf16 v[60:63], v[148:151], v[208:211], v[60:63]
	v_mfma_f32_16x16x32_bf16 v[56:59], v[156:159], v[208:211], v[56:59]
	v_mfma_f32_16x16x32_bf16 v[52:55], v[148:151], v[216:219], v[52:55]
	v_mfma_f32_16x16x32_bf16 v[48:51], v[156:159], v[216:219], v[48:51]
	v_mfma_f32_16x16x32_bf16 v[36:39], v[148:151], v[224:227], v[36:39]
	v_mfma_f32_16x16x32_bf16 v[32:35], v[156:159], v[224:227], v[32:35]
	v_mfma_f32_16x16x32_bf16 v[20:23], v[148:151], v[232:235], v[20:23]
	v_mfma_f32_16x16x32_bf16 v[16:19], v[156:159], v[232:235], v[16:19]
	s_setprio 0
	s_setprio 1
	v_mfma_f32_16x16x32_bf16 v[44:47], v[178:181], v[194:197], v[44:47]
	v_mfma_f32_16x16x32_bf16 v[40:43], v[186:189], v[194:197], v[40:43]
	v_mfma_f32_16x16x32_bf16 v[28:31], v[178:181], v[212:215], v[28:31]
	v_mfma_f32_16x16x32_bf16 v[24:27], v[186:189], v[212:215], v[24:27]
	v_mfma_f32_16x16x32_bf16 v[12:15], v[178:181], v[220:223], v[12:15]
	v_mfma_f32_16x16x32_bf16 v[8:11], v[186:189], v[220:223], v[8:11]
	v_mfma_f32_16x16x32_bf16 v[4:7], v[178:181], v[228:231], v[4:7]
	v_mfma_f32_16x16x32_bf16 v[0:3], v[186:189], v[228:231], v[0:3]
	v_mfma_f32_16x16x32_bf16 v[44:47], v[182:185], v[208:211], v[44:47]
	v_mfma_f32_16x16x32_bf16 v[40:43], v[190:193], v[208:211], v[40:43]
	v_mfma_f32_16x16x32_bf16 v[28:31], v[182:185], v[216:219], v[28:31]
	v_mfma_f32_16x16x32_bf16 v[24:27], v[190:193], v[216:219], v[24:27]
	v_mfma_f32_16x16x32_bf16 v[12:15], v[182:185], v[224:227], v[12:15]
	v_mfma_f32_16x16x32_bf16 v[8:11], v[190:193], v[224:227], v[8:11]
	v_mfma_f32_16x16x32_bf16 v[4:7], v[182:185], v[232:235], v[4:7]
	v_mfma_f32_16x16x32_bf16 v[0:3], v[190:193], v[232:235], v[0:3]
	s_setprio 0
	s_barrier
	s_add_i32 s37, s37, 2
	s_add_u32 s0, s0, 0x100
	s_addc_u32 s1, s1, 0
	s_add_u32 s35, s35, 0x100
	s_addc_u32 s36, s36, 0
	s_cmp_gt_u32 s37, 29
	s_cbranch_scc0 .LBB0_316
	s_mov_b64 s[42:43], 0x80
	s_and_b64 vcc, exec, s[6:7]
	s_mov_b64 s[34:35], 0x45000
	s_cbranch_vccz .LBB0_319
	s_barrier

; #define PG8_STAGE(bufoff, gbase, voff) do { _Pragma("unroll") for (int _i = 0; _i < 2; ++_i) \
;         __builtin_amdgcn_global_load_lds((const unsigned*)((const char*)(gbase) + (voff)[_i]), (PG8_LAS unsigned*)(lds + (bufoff) + ldsw + _i * 8192), 16, 0, 0); } while (0)
; #define PG8_LDA(dst, b, h) do { _Pragma("unroll") for (int m = 0; m < 4; ++m) _Pragma("unroll") for (int k = 0; k < 2; ++k) dst[m][k] = *(const PG8_LAS bf16x8*)(lds + PG8_SA(b, h) + aoff + m * 2048 + k * 1024); } while (0)
; #define PG8_LDB(dst, b, h) do { _Pragma("unroll") for (int n = 0; n < 2; ++n) _Pragma("unroll") for (int k = 0; k < 2; ++k) dst[n][k] = *(const PG8_LAS bf16x8*)(lds + PG8_SB(b, h) + boff + n * 2048 + k * 1024); } while (0)
; #define PG8_MMA(ai, bj, At, Bt) do { __builtin_amdgcn_s_setprio(1); _Pragma("unroll") for (int m = 0; m < 4; ++m) _Pragma("unroll") for (int n = 0; n < 2; ++n) _Pragma("unroll") for (int k = 0; k < 2; ++k) \
;         acc[ai][bj][m][n] = __builtin_amdgcn_mfma_f32_16x16x32_bf16(Bt[n][k], At[m][k], acc[ai][bj][m][n], 0, 0, 0); __builtin_amdgcn_s_setprio(0); } while (0)
; #define PG8_WAIT_V(n) asm volatile("s_waitcnt vmcnt(" #n ")" ::: "memory")
; #define PG8_WAIT_L(n) asm volatile("s_waitcnt lgkmcnt(" #n ")" ::: "memory")
; #define PG8_BAR __builtin_amdgcn_s_barrier()
; #define PG8_SCHED __builtin_amdgcn_sched_barrier(0)
; template <class Epi, class Sched, bool ALIGN_EPI = false, bool SP2 = false>
; __device__ __forceinline__ void gemm_phase(PG8_LAS unsigned char* lds, const Gemm g, const Sched& S, const Epi& E, const int wave0) {
;     ...
;             PG8_LDB(B0, 0, 0); PG8_LDB(B1, 0, 1); PG8_SCHED; PG8_LDA(At, 0, 0); PG8_STAGE(PG8_SA(1, 1), a1 + hstepA, voffA);
;             PG8_WAIT_V(8); PG8_WAIT_L(0); PG8_BAR; PG8_MMA(0, 0, At, B0); PG8_MMA(0, 1, At, B1); PG8_BAR; PG8_SCHED;
;             PG8_LDA(At, 0, 1); PG8_STAGE(PG8_SB(0, 0), b2, voffB); PG8_STAGE(PG8_SB(0, 1), b2 + hstepB, voffB); PG8_STAGE(PG8_SA(0, 0), a2, voffA);
;             PG8_WAIT_V(8); PG8_WAIT_L(0); PG8_BAR; PG8_MMA(1, 0, At, B0); PG8_MMA(1, 1, At, B1); PG8_BAR; PG8_SCHED;
.LBB0_1178:
	ds_read_b128 v[130:133], v252
	ds_read_b128 v[134:137], v252 offset:1024
	ds_read_b128 v[148:151], v252 offset:2048
	ds_read_b128 v[152:155], v252 offset:3072
	ds_read_b128 v[178:181], v253
	ds_read_b128 v[182:185], v253 offset:1024
	ds_read_b128 v[186:189], v253 offset:2048
	ds_read_b128 v[190:193], v253 offset:3072
	ds_read_b128 v[194:197], v159
	ds_read_b128 v[208:211], v159 offset:1024
	ds_read_b128 v[212:215], v159 offset:2048
	ds_read_b128 v[216:219], v159 offset:3072
	ds_read_b128 v[220:223], v159 offset:4096
	ds_read_b128 v[224:227], v159 offset:5120
	ds_read_b128 v[228:231], v159 offset:6144
	ds_read_b128 v[232:235], v159 offset:7168
	s_add_u32 s2, s0, 0xfffc0080
	s_addc_u32 s3, s1, -1
	s_add_i32 s31, 0, 0x10000
	s_cmp_eq_u32 s19, 12
	s_cselect_b32 s17, s45, s3
	s_cselect_b32 s16, s44, s2
	s_cselect_b32 s3, s9, s18
	s_cselect_b32 s2, s11, s13
	s_add_i32 s33, 0, 0x14000
	s_add_i32 m0, s23, 0xc000
	s_nop 0
	global_load_lds_dwordx4 v144, s[0:1]
	s_add_i32 m0, s23, 0xe000
	s_nop 0
	global_load_lds_dwordx4 v146, s[0:1]
	s_waitcnt vmcnt(8)
	s_waitcnt lgkmcnt(0)
	s_barrier
	s_setprio 1
	s_waitcnt lgkmcnt(0)
	v_mfma_f32_16x16x32_bf16 v[126:129], v[130:133], v[194:197], v[126:129]
	v_mfma_f32_16x16x32_bf16 v[122:125], v[148:151], v[194:197], v[122:125]
	v_mfma_f32_16x16x32_bf16 v[110:113], v[130:133], v[212:215], v[110:113]
	v_mfma_f32_16x16x32_bf16 v[106:109], v[148:151], v[212:215], v[106:109]
	v_mfma_f32_16x16x32_bf16 v[94:97], v[130:133], v[220:223], v[94:97]
	v_mfma_f32_16x16x32_bf16 v[90:93], v[148:151], v[220:223], v[90:93]
	v_mfma_f32_16x16x32_bf16 v[78:81], v[130:133], v[228:231], v[78:81]
	v_mfma_f32_16x16x32_bf16 v[74:77], v[148:151], v[228:231], v[74:77]
	v_mfma_f32_16x16x32_bf16 v[126:129], v[134:137], v[208:211], v[126:129]
	v_mfma_f32_16x16x32_bf16 v[122:125], v[152:155], v[208:211], v[122:125]
	v_mfma_f32_16x16x32_bf16 v[110:113], v[134:137], v[216:219], v[110:113]
	v_mfma_f32_16x16x32_bf16 v[106:109], v[152:155], v[216:219], v[106:109]
	v_mfma_f32_16x16x32_bf16 v[94:97], v[134:137], v[224:227], v[94:97]
	v_mfma_f32_16x16x32_bf16 v[90:93], v[152:155], v[224:227], v[90:93]
	v_mfma_f32_16x16x32_bf16 v[78:81], v[134:137], v[232:235], v[78:81]
	v_mfma_f32_16x16x32_bf16 v[74:77], v[152:155], v[232:235], v[74:77]
	s_setprio 0
	s_setprio 1
	v_mfma_f32_16x16x32_bf16 v[118:121], v[178:181], v[194:197], v[118:121]
	v_mfma_f32_16x16x32_bf16 v[114:117], v[186:189], v[194:197], v[114:117]
	v_mfma_f32_16x16x32_bf16 v[102:105], v[178:181], v[212:215], v[102:105]
	v_mfma_f32_16x16x32_bf16 v[98:101], v[186:189], v[212:215], v[98:101]
	v_mfma_f32_16x16x32_bf16 v[86:89], v[178:181], v[220:223], v[86:89]
	v_mfma_f32_16x16x32_bf16 v[82:85], v[186:189], v[220:223], v[82:85]
	v_mfma_f32_16x16x32_bf16 v[70:73], v[178:181], v[228:231], v[70:73]
	v_mfma_f32_16x16x32_bf16 v[66:69], v[186:189], v[228:231], v[66:69]
	v_mfma_f32_16x16x32_bf16 v[118:121], v[182:185], v[208:211], v[118:121]
	v_mfma_f32_16x16x32_bf16 v[114:117], v[190:193], v[208:211], v[114:117]
	v_mfma_f32_16x16x32_bf16 v[102:105], v[182:185], v[216:219], v[102:105]
	v_mfma_f32_16x16x32_bf16 v[98:101], v[190:193], v[216:219], v[98:101]
	v_mfma_f32_16x16x32_bf16 v[86:89], v[182:185], v[224:227], v[86:89]
	v_mfma_f32_16x16x32_bf16 v[82:85], v[190:193], v[224:227], v[82:85]
	v_mfma_f32_16x16x32_bf16 v[70:73], v[182:185], v[232:235], v[70:73]
	v_mfma_f32_16x16x32_bf16 v[66:69], v[190:193], v[232:235], v[66:69]
	s_setprio 0
	s_barrier
	ds_read_b128 v[194:197], v159 offset:16384
	ds_read_b128 v[208:211], v159 offset:17408
	ds_read_b128 v[212:215], v159 offset:18432
	ds_read_b128 v[216:219], v159 offset:19456
	ds_read_b128 v[220:223], v159 offset:20480
	ds_read_b128 v[224:227], v159 offset:21504
	ds_read_b128 v[228:231], v159 offset:22528
	ds_read_b128 v[232:235], v159 offset:23552
	s_add_i32 s31, s31, s22
	s_mov_b32 m0, s31
	s_nop 0
	global_load_lds_dwordx4 v64, s[2:3]
	s_add_i32 m0, s31, 0x2000
	s_add_u32 s34, s2, 0x40000
	s_addc_u32 s35, s3, 0
	s_add_i32 s31, s33, s22
	global_load_lds_dwordx4 v138, s[2:3]
	s_mov_b32 m0, s31
	s_mov_b64 s[100:101], s[16:17]
	global_load_lds_dwordx4 v64, s[34:35]
	s_add_i32 m0, s31, 0x2000
	s_nop 0
	global_load_lds_dwordx4 v138, s[34:35]
	s_mov_b32 m0, s23
	s_nop 0
	global_load_lds_dwordx4 v142, s[16:17]
	s_mov_b32 m0, s24
	s_nop 0
	global_load_lds_dwordx4 v140, s[16:17]
	s_waitcnt vmcnt(8)
	s_waitcnt lgkmcnt(0)
	s_barrier
	s_setprio 1
	s_waitcnt lgkmcnt(0)
	v_mfma_f32_16x16x32_bf16 v[60:63], v[130:133], v[194:197], v[60:63]
	v_mfma_f32_16x16x32_bf16 v[56:59], v[148:151], v[194:197], v[56:59]
	v_mfma_f32_16x16x32_bf16 v[44:47], v[130:133], v[212:215], v[44:47]
	v_mfma_f32_16x16x32_bf16 v[40:43], v[148:151], v[212:215], v[40:43]
	v_mfma_f32_16x16x32_bf16 v[28:31], v[130:133], v[220:223], v[28:31]
	v_mfma_f32_16x16x32_bf16 v[24:27], v[148:151], v[220:223], v[24:27]
	v_mfma_f32_16x16x32_bf16 v[12:15], v[130:133], v[228:231], v[12:15]
	v_mfma_f32_16x16x32_bf16 v[8:11], v[148:151], v[228:231], v[8:11]
	v_mfma_f32_16x16x32_bf16 v[60:63], v[134:137], v[208:211], v[60:63]
	v_mfma_f32_16x16x32_bf16 v[56:59], v[152:155], v[208:211], v[56:59]
	v_mfma_f32_16x16x32_bf16 v[44:47], v[134:137], v[216:219], v[44:47]
	v_mfma_f32_16x16x32_bf16 v[40:43], v[152:155], v[216:219], v[40:43]
	v_mfma_f32_16x16x32_bf16 v[28:31], v[134:137], v[224:227], v[28:31]
	v_mfma_f32_16x16x32_bf16 v[24:27], v[152:155], v[224:227], v[24:27]
	v_mfma_f32_16x16x32_bf16 v[12:15], v[134:137], v[232:235], v[12:15]
	v_mfma_f32_16x16x32_bf16 v[8:11], v[152:155], v[232:235], v[8:11]
	s_setprio 0
	s_setprio 1
	v_mfma_f32_16x16x32_bf16 v[52:55], v[178:181], v[194:197], v[52:55]
	v_mfma_f32_16x16x32_bf16 v[48:51], v[186:189], v[194:197], v[48:51]
	v_mfma_f32_16x16x32_bf16 v[36:39], v[178:181], v[212:215], v[36:39]
	v_mfma_f32_16x16x32_bf16 v[32:35], v[186:189], v[212:215], v[32:35]
	v_mfma_f32_16x16x32_bf16 v[20:23], v[178:181], v[220:223], v[20:23]
	v_mfma_f32_16x16x32_bf16 v[16:19], v[186:189], v[220:223], v[16:19]
	v_mfma_f32_16x16x32_bf16 v[4:7], v[178:181], v[228:231], v[4:7]
	v_mfma_f32_16x16x32_bf16 v[0:3], v[186:189], v[228:231], v[0:3]
	v_mfma_f32_16x16x32_bf16 v[52:55], v[182:185], v[208:211], v[52:55]
	v_mfma_f32_16x16x32_bf16 v[48:51], v[190:193], v[208:211], v[48:51]
	v_mfma_f32_16x16x32_bf16 v[36:39], v[182:185], v[216:219], v[36:39]
	v_mfma_f32_16x16x32_bf16 v[32:35], v[190:193], v[216:219], v[32:35]
	v_mfma_f32_16x16x32_bf16 v[20:23], v[182:185], v[224:227], v[20:23]
	v_mfma_f32_16x16x32_bf16 v[16:19], v[190:193], v[224:227], v[16:19]
	v_mfma_f32_16x16x32_bf16 v[4:7], v[182:185], v[232:235], v[4:7]
	v_mfma_f32_16x16x32_bf16 v[0:3], v[190:193], v[232:235], v[0:3]
	s_setprio 0
	s_barrier
; #define PG8_STAGE(bufoff, gbase, voff) do { _Pragma("unroll") for (int _i = 0; _i < 2; ++_i) \
;         __builtin_amdgcn_global_load_lds((const unsigned*)((const char*)(gbase) + (voff)[_i]), (PG8_LAS unsigned*)(lds + (bufoff) + ldsw + _i * 8192), 16, 0, 0); } while (0)
; #define PG8_LDA(dst, b, h) do { _Pragma("unroll") for (int m = 0; m < 4; ++m) _Pragma("unroll") for (int k = 0; k < 2; ++k) dst[m][k] = *(const PG8_LAS bf16x8*)(lds + PG8_SA(b, h) + aoff + m * 2048 + k * 1024); } while (0)
; #define PG8_LDB(dst, b, h) do { _Pragma("unroll") for (int n = 0; n < 2; ++n) _Pragma("unroll") for (int k = 0; k < 2; ++k) dst[n][k] = *(const PG8_LAS bf16x8*)(lds + PG8_SB(b, h) + boff + n * 2048 + k * 1024); } while (0)
; #define PG8_MMA(ai, bj, At, Bt) do { __builtin_amdgcn_s_setprio(1); _Pragma("unroll") for (int m = 0; m < 4; ++m) _Pragma("unroll") for (int n = 0; n < 2; ++n) _Pragma("unroll") for (int k = 0; k < 2; ++k) \
;         acc[ai][bj][m][n] = __builtin_amdgcn_mfma_f32_16x16x32_bf16(Bt[n][k], At[m][k], acc[ai][bj][m][n], 0, 0, 0); __builtin_amdgcn_s_setprio(0); } while (0)
; #define PG8_WAIT_V(n) asm volatile("s_waitcnt vmcnt(" #n ")" ::: "memory")
; #define PG8_WAIT_L(n) asm volatile("s_waitcnt lgkmcnt(" #n ")" ::: "memory")
; #define PG8_BAR __builtin_amdgcn_s_barrier()
; #define PG8_SCHED __builtin_amdgcn_sched_barrier(0)
; template <class Epi, class Sched, bool ALIGN_EPI = false, bool SP2 = false>
; __device__ __forceinline__ void gemm_phase(PG8_LAS unsigned char* lds, const Gemm g, const Sched& S, const Epi& E, const int wave0) {
;     ...
;             PG8_LDB(B0, 1, 0); PG8_LDB(B1, 1, 1); PG8_SCHED; PG8_LDA(At, 1, 0); PG8_STAGE(PG8_SA(0, 1), a2 + hstepA, voffA);
;             PG8_WAIT_V(8); PG8_WAIT_L(0); PG8_BAR; PG8_MMA(0, 0, At, B0); PG8_MMA(0, 1, At, B1); PG8_BAR; PG8_SCHED;
;             PG8_LDA(At, 1, 1); PG8_STAGE(PG8_SB(1, 0), b3, voffB); PG8_STAGE(PG8_SB(1, 1), b3 + hstepB, voffB); PG8_STAGE(PG8_SA(1, 0), a3, voffA);
;             PG8_WAIT_V(8); PG8_WAIT_L(0); PG8_BAR; PG8_MMA(1, 0, At, B0); PG8_MMA(1, 1, At, B1); PG8_BAR; PG8_SCHED;
	ds_read_b128 v[130:133], v254
	ds_read_b128 v[134:137], v254 offset:1024
	ds_read_b128 v[148:151], v254 offset:2048
	ds_read_b128 v[152:155], v254 offset:3072
	ds_read_b128 v[178:181], v255
	ds_read_b128 v[182:185], v255 offset:1024
	ds_read_b128 v[186:189], v255 offset:2048
	ds_read_b128 v[190:193], v255 offset:3072
	ds_read_b128 v[194:197], v159 offset:32768
	ds_read_b128 v[208:211], v159 offset:33792
	ds_read_b128 v[212:215], v159 offset:34816
	ds_read_b128 v[216:219], v159 offset:35840
	ds_read_b128 v[220:223], v159 offset:36864
	ds_read_b128 v[224:227], v159 offset:37888
	ds_read_b128 v[228:231], v159 offset:38912
	ds_read_b128 v[232:235], v159 offset:39936
	s_add_i32 s31, 0, 0x18000
	s_add_i32 s33, 0, 0x1c000
	s_add_u32 s16, s16, 0x40000
	s_addc_u32 s17, s17, 0
	s_mov_b32 m0, s25
	s_nop 0
	global_load_lds_dwordx4 v142, s[16:17]
	s_mov_b32 m0, s26
	s_nop 0
	global_load_lds_dwordx4 v140, s[16:17]
	s_waitcnt vmcnt(8)
	s_waitcnt lgkmcnt(0)
	s_barrier
	s_setprio 1
	s_waitcnt lgkmcnt(0)
	v_mfma_f32_16x16x32_bf16 v[126:129], v[130:133], v[194:197], v[126:129]
	v_mfma_f32_16x16x32_bf16 v[122:125], v[148:151], v[194:197], v[122:125]
	v_mfma_f32_16x16x32_bf16 v[110:113], v[130:133], v[212:215], v[110:113]
	v_mfma_f32_16x16x32_bf16 v[106:109], v[148:151], v[212:215], v[106:109]
	v_mfma_f32_16x16x32_bf16 v[94:97], v[130:133], v[220:223], v[94:97]
	v_mfma_f32_16x16x32_bf16 v[90:93], v[148:151], v[220:223], v[90:93]
	v_mfma_f32_16x16x32_bf16 v[78:81], v[130:133], v[228:231], v[78:81]
	v_mfma_f32_16x16x32_bf16 v[74:77], v[148:151], v[228:231], v[74:77]
	v_mfma_f32_16x16x32_bf16 v[126:129], v[134:137], v[208:211], v[126:129]
	v_mfma_f32_16x16x32_bf16 v[122:125], v[152:155], v[208:211], v[122:125]
	v_mfma_f32_16x16x32_bf16 v[110:113], v[134:137], v[216:219], v[110:113]
	v_mfma_f32_16x16x32_bf16 v[106:109], v[152:155], v[216:219], v[106:109]
	v_mfma_f32_16x16x32_bf16 v[94:97], v[134:137], v[224:227], v[94:97]
	v_mfma_f32_16x16x32_bf16 v[90:93], v[152:155], v[224:227], v[90:93]
	v_mfma_f32_16x16x32_bf16 v[78:81], v[134:137], v[232:235], v[78:81]
	v_mfma_f32_16x16x32_bf16 v[74:77], v[152:155], v[232:235], v[74:77]
	s_setprio 0
	s_setprio 1
	v_mfma_f32_16x16x32_bf16 v[118:121], v[178:181], v[194:197], v[118:121]
	v_mfma_f32_16x16x32_bf16 v[114:117], v[186:189], v[194:197], v[114:117]
	v_mfma_f32_16x16x32_bf16 v[102:105], v[178:181], v[212:215], v[102:105]
	v_mfma_f32_16x16x32_bf16 v[98:101], v[186:189], v[212:215], v[98:101]
	v_mfma_f32_16x16x32_bf16 v[86:89], v[178:181], v[220:223], v[86:89]
	v_mfma_f32_16x16x32_bf16 v[82:85], v[186:189], v[220:223], v[82:85]
	v_mfma_f32_16x16x32_bf16 v[70:73], v[178:181], v[228:231], v[70:73]
	v_mfma_f32_16x16x32_bf16 v[66:69], v[186:189], v[228:231], v[66:69]
	v_mfma_f32_16x16x32_bf16 v[118:121], v[182:185], v[208:211], v[118:121]
	v_mfma_f32_16x16x32_bf16 v[114:117], v[190:193], v[208:211], v[114:117]
	v_mfma_f32_16x16x32_bf16 v[102:105], v[182:185], v[216:219], v[102:105]
	v_mfma_f32_16x16x32_bf16 v[98:101], v[190:193], v[216:219], v[98:101]
	v_mfma_f32_16x16x32_bf16 v[86:89], v[182:185], v[224:227], v[86:89]
	v_mfma_f32_16x16x32_bf16 v[82:85], v[190:193], v[224:227], v[82:85]
	v_mfma_f32_16x16x32_bf16 v[70:73], v[182:185], v[232:235], v[70:73]
	v_mfma_f32_16x16x32_bf16 v[66:69], v[190:193], v[232:235], v[66:69]
	s_setprio 0
	s_barrier
	ds_read_b128 v[194:197], v159 offset:49152
	ds_read_b128 v[208:211], v159 offset:50176
	ds_read_b128 v[212:215], v159 offset:51200
	ds_read_b128 v[216:219], v159 offset:52224
	ds_read_b128 v[220:223], v159 offset:53248
	ds_read_b128 v[224:227], v159 offset:54272
	ds_read_b128 v[228:231], v159 offset:55296
	ds_read_b128 v[232:235], v159 offset:56320
	s_add_i32 s16, s31, s22
	s_add_u32 s36, s2, 0x80
	s_addc_u32 s37, s3, 0
	s_mov_b32 m0, s16
	s_nop 0
	global_load_lds_dwordx4 v64, s[36:37]
	s_add_i32 m0, s16, 0x2000
	s_add_u32 s2, s2, 0x40080
	s_addc_u32 s3, s3, 0
	s_add_i32 s16, s33, s22
	global_load_lds_dwordx4 v138, s[36:37]
	s_mov_b32 m0, s16
	s_nop 0
	global_load_lds_dwordx4 v64, s[2:3]
	s_add_i32 m0, s16, 0x2000
	s_nop 0
	global_load_lds_dwordx4 v138, s[2:3]
	s_add_u32 s100, s100, 0x80
	s_addc_u32 s101, s101, 0
	s_mov_b32 m0, s27
	s_nop 0
	global_load_lds_dwordx4 v142, s[100:101]
	s_mov_b32 m0, s28
	s_nop 0
	global_load_lds_dwordx4 v140, s[100:101]
	s_waitcnt vmcnt(8)
	s_waitcnt lgkmcnt(0)
	s_barrier
	s_setprio 1
	s_waitcnt lgkmcnt(0)
	v_mfma_f32_16x16x32_bf16 v[60:63], v[130:133], v[194:197], v[60:63]
	v_mfma_f32_16x16x32_bf16 v[56:59], v[148:151], v[194:197], v[56:59]
	v_mfma_f32_16x16x32_bf16 v[44:47], v[130:133], v[212:215], v[44:47]
	v_mfma_f32_16x16x32_bf16 v[40:43], v[148:151], v[212:215], v[40:43]
	v_mfma_f32_16x16x32_bf16 v[28:31], v[130:133], v[220:223], v[28:31]
	v_mfma_f32_16x16x32_bf16 v[24:27], v[148:151], v[220:223], v[24:27]
	v_mfma_f32_16x16x32_bf16 v[12:15], v[130:133], v[228:231], v[12:15]
	v_mfma_f32_16x16x32_bf16 v[8:11], v[148:151], v[228:231], v[8:11]
	v_mfma_f32_16x16x32_bf16 v[60:63], v[134:137], v[208:211], v[60:63]
	v_mfma_f32_16x16x32_bf16 v[56:59], v[152:155], v[208:211], v[56:59]
	v_mfma_f32_16x16x32_bf16 v[44:47], v[134:137], v[216:219], v[44:47]
	v_mfma_f32_16x16x32_bf16 v[40:43], v[152:155], v[216:219], v[40:43]
	v_mfma_f32_16x16x32_bf16 v[28:31], v[134:137], v[224:227], v[28:31]
	v_mfma_f32_16x16x32_bf16 v[24:27], v[152:155], v[224:227], v[24:27]
	v_mfma_f32_16x16x32_bf16 v[12:15], v[134:137], v[232:235], v[12:15]
	v_mfma_f32_16x16x32_bf16 v[8:11], v[152:155], v[232:235], v[8:11]
	s_setprio 0
	s_setprio 1
	v_mfma_f32_16x16x32_bf16 v[52:55], v[178:181], v[194:197], v[52:55]
	v_mfma_f32_16x16x32_bf16 v[48:51], v[186:189], v[194:197], v[48:51]
	v_mfma_f32_16x16x32_bf16 v[36:39], v[178:181], v[212:215], v[36:39]
	v_mfma_f32_16x16x32_bf16 v[32:35], v[186:189], v[212:215], v[32:35]
	v_mfma_f32_16x16x32_bf16 v[20:23], v[178:181], v[220:223], v[20:23]
	v_mfma_f32_16x16x32_bf16 v[16:19], v[186:189], v[220:223], v[16:19]
	v_mfma_f32_16x16x32_bf16 v[4:7], v[178:181], v[228:231], v[4:7]
	v_mfma_f32_16x16x32_bf16 v[0:3], v[186:189], v[228:231], v[0:3]
	v_mfma_f32_16x16x32_bf16 v[52:55], v[182:185], v[208:211], v[52:55]
	v_mfma_f32_16x16x32_bf16 v[48:51], v[190:193], v[208:211], v[48:51]
	v_mfma_f32_16x16x32_bf16 v[36:39], v[182:185], v[216:219], v[36:39]
	v_mfma_f32_16x16x32_bf16 v[32:35], v[190:193], v[216:219], v[32:35]
	v_mfma_f32_16x16x32_bf16 v[20:23], v[182:185], v[224:227], v[20:23]
	v_mfma_f32_16x16x32_bf16 v[16:19], v[190:193], v[224:227], v[16:19]
	v_mfma_f32_16x16x32_bf16 v[4:7], v[182:185], v[232:235], v[4:7]
	v_mfma_f32_16x16x32_bf16 v[0:3], v[190:193], v[232:235], v[0:3]
	s_setprio 0
	s_barrier
	s_add_i32 s19, s19, 2
	s_add_u32 s0, s0, 0x100
	s_addc_u32 s1, s1, 0
	s_add_u32 s13, s13, 0x100
	s_addc_u32 s18, s18, 0
	s_cmp_gt_u32 s19, 13
	s_cbranch_scc0 .LBB0_1178
	s_mov_b64 s[36:37], 0x80
	s_and_b64 vcc, exec, s[6:7]
	s_cbranch_vccz .LBB0_1181
	s_barrier

; #define PG8_STAGE(bufoff, gbase, voff) do { _Pragma("unroll") for (int _i = 0; _i < 2; ++_i) \
;         __builtin_amdgcn_global_load_lds((const unsigned*)((const char*)(gbase) + (voff)[_i]), (PG8_LAS unsigned*)(lds + (bufoff) + ldsw + _i * 8192), 16, 0, 0); } while (0)
; #define PG8_LDA(dst, b, h) do { _Pragma("unroll") for (int m = 0; m < 4; ++m) _Pragma("unroll") for (int k = 0; k < 2; ++k) dst[m][k] = *(const PG8_LAS bf16x8*)(lds + PG8_SA(b, h) + aoff + m * 2048 + k * 1024); } while (0)
; #define PG8_LDB(dst, b, h) do { _Pragma("unroll") for (int n = 0; n < 2; ++n) _Pragma("unroll") for (int k = 0; k < 2; ++k) dst[n][k] = *(const PG8_LAS bf16x8*)(lds + PG8_SB(b, h) + boff + n * 2048 + k * 1024); } while (0)
; #define PG8_MMA(ai, bj, At, Bt) do { __builtin_amdgcn_s_setprio(1); _Pragma("unroll") for (int m = 0; m < 4; ++m) _Pragma("unroll") for (int n = 0; n < 2; ++n) _Pragma("unroll") for (int k = 0; k < 2; ++k) \
;         acc[ai][bj][m][n] = __builtin_amdgcn_mfma_f32_16x16x32_bf16(Bt[n][k], At[m][k], acc[ai][bj][m][n], 0, 0, 0); __builtin_amdgcn_s_setprio(0); } while (0)
; #define PG8_WAIT_V(n) asm volatile("s_waitcnt vmcnt(" #n ")" ::: "memory")
; #define PG8_BAR __builtin_amdgcn_s_barrier()
; template <class Epi, class Sched, bool ALIGN_EPI = false, bool SP2 = false>
; __device__ __forceinline__ void gemm_phase(PG8_LAS unsigned char* lds, const Gemm g, const Sched& S, const Epi& E, const int wave0) {
;     ...
;         for (int t = 0; t < nt; t += 2) {
;             const bool last = (t == nt - 2);
;             const char* a1 = cA + (size_t)(t + 1) * kstep;
;             const char* a2 = last ? nA : cA + (size_t)(t + 2) * kstep; const char* b2 = last ? nB : cB + (size_t)(t + 2) * kstep;
;             const char* a3 = a2 + kstep; const char* b3 = b2 + kstep;
;             if (last && has_next) S.a_ready(nxt);
;             if constexpr (SP2) {
;             PG8_LDB(B0, 0, 0); PG8_LDB(B1, 0, 1); PG8_SCHED; PG8_LDA(At, 0, 0); PG8_STAGE(PG8_SA(1, 1), a1 + hstepA, voffA);
;             PG8_WAIT_V(8); PG8_WAIT_L(0); PG8_BAR; PG8_MMA(0, 0, At, B0); PG8_MMA(0, 1, At, B1); PG8_BAR; PG8_SCHED;
;             PG8_LDA(At, 0, 1); PG8_STAGE(PG8_SB(0, 0), b2, voffB); PG8_STAGE(PG8_SB(0, 1), b2 + hstepB, voffB); PG8_STAGE(PG8_SA(0, 0), a2, voffA);
;             PG8_WAIT_V(8); PG8_WAIT_L(0); PG8_BAR; PG8_MMA(1, 0, At, B0); PG8_MMA(1, 1, At, B1); PG8_BAR; PG8_SCHED;
.LBB0_1231:
	ds_read_b128 v[140:143], v252
	ds_read_b128 v[144:147], v252 offset:1024
	ds_read_b128 v[154:157], v252 offset:2048
	ds_read_b128 v[158:161], v252 offset:3072
	ds_read_b128 v[178:181], v253
	ds_read_b128 v[182:185], v253 offset:1024
	ds_read_b128 v[186:189], v253 offset:2048
	ds_read_b128 v[190:193], v253 offset:3072
	ds_read_b128 v[194:197], v153
	ds_read_b128 v[208:211], v153 offset:1024
	ds_read_b128 v[212:215], v153 offset:2048
	ds_read_b128 v[216:219], v153 offset:3072
	ds_read_b128 v[220:223], v153 offset:4096
	ds_read_b128 v[224:227], v153 offset:5120
	ds_read_b128 v[228:231], v153 offset:6144
	ds_read_b128 v[232:235], v153 offset:7168
	s_add_u32 s2, s0, 0xfffc0080
	s_addc_u32 s3, s1, -1
	s_add_i32 s31, 0, 0x10000
	s_cmp_eq_u32 s19, 12
	s_cselect_b32 s17, s43, s3
	s_cselect_b32 s16, s42, s2
	s_cselect_b32 s3, s9, s18
	s_cselect_b32 s2, s11, s13
	s_add_i32 s33, 0, 0x14000
	s_add_i32 m0, s23, 0xc000
	s_nop 0
	global_load_lds_dwordx4 v136, s[0:1]
	s_add_i32 m0, s23, 0xe000
	s_nop 0
	global_load_lds_dwordx4 v138, s[0:1]
	s_waitcnt vmcnt(8)
	s_waitcnt lgkmcnt(0)
	s_barrier
	s_setprio 1
	s_waitcnt lgkmcnt(0)
	v_mfma_f32_16x16x32_bf16 v[126:129], v[140:143], v[194:197], v[126:129]
	v_mfma_f32_16x16x32_bf16 v[122:125], v[154:157], v[194:197], v[122:125]
	v_mfma_f32_16x16x32_bf16 v[110:113], v[140:143], v[212:215], v[110:113]
	v_mfma_f32_16x16x32_bf16 v[106:109], v[154:157], v[212:215], v[106:109]
	v_mfma_f32_16x16x32_bf16 v[94:97], v[140:143], v[220:223], v[94:97]
	v_mfma_f32_16x16x32_bf16 v[90:93], v[154:157], v[220:223], v[90:93]
	v_mfma_f32_16x16x32_bf16 v[78:81], v[140:143], v[228:231], v[78:81]
	v_mfma_f32_16x16x32_bf16 v[74:77], v[154:157], v[228:231], v[74:77]
	v_mfma_f32_16x16x32_bf16 v[126:129], v[144:147], v[208:211], v[126:129]
	v_mfma_f32_16x16x32_bf16 v[122:125], v[158:161], v[208:211], v[122:125]
	v_mfma_f32_16x16x32_bf16 v[110:113], v[144:147], v[216:219], v[110:113]
	v_mfma_f32_16x16x32_bf16 v[106:109], v[158:161], v[216:219], v[106:109]
	v_mfma_f32_16x16x32_bf16 v[94:97], v[144:147], v[224:227], v[94:97]
	v_mfma_f32_16x16x32_bf16 v[90:93], v[158:161], v[224:227], v[90:93]
	v_mfma_f32_16x16x32_bf16 v[78:81], v[144:147], v[232:235], v[78:81]
	v_mfma_f32_16x16x32_bf16 v[74:77], v[158:161], v[232:235], v[74:77]
	s_setprio 0
	s_setprio 1
	v_mfma_f32_16x16x32_bf16 v[118:121], v[178:181], v[194:197], v[118:121]
	v_mfma_f32_16x16x32_bf16 v[114:117], v[186:189], v[194:197], v[114:117]
	v_mfma_f32_16x16x32_bf16 v[102:105], v[178:181], v[212:215], v[102:105]
	v_mfma_f32_16x16x32_bf16 v[98:101], v[186:189], v[212:215], v[98:101]
	v_mfma_f32_16x16x32_bf16 v[86:89], v[178:181], v[220:223], v[86:89]
	v_mfma_f32_16x16x32_bf16 v[82:85], v[186:189], v[220:223], v[82:85]
	v_mfma_f32_16x16x32_bf16 v[70:73], v[178:181], v[228:231], v[70:73]
	v_mfma_f32_16x16x32_bf16 v[66:69], v[186:189], v[228:231], v[66:69]
	v_mfma_f32_16x16x32_bf16 v[118:121], v[182:185], v[208:211], v[118:121]
	v_mfma_f32_16x16x32_bf16 v[114:117], v[190:193], v[208:211], v[114:117]
	v_mfma_f32_16x16x32_bf16 v[102:105], v[182:185], v[216:219], v[102:105]
	v_mfma_f32_16x16x32_bf16 v[98:101], v[190:193], v[216:219], v[98:101]
	v_mfma_f32_16x16x32_bf16 v[86:89], v[182:185], v[224:227], v[86:89]
	v_mfma_f32_16x16x32_bf16 v[82:85], v[190:193], v[224:227], v[82:85]
	v_mfma_f32_16x16x32_bf16 v[70:73], v[182:185], v[232:235], v[70:73]
	v_mfma_f32_16x16x32_bf16 v[66:69], v[190:193], v[232:235], v[66:69]
	s_setprio 0
	s_barrier
	ds_read_b128 v[194:197], v153 offset:16384
	ds_read_b128 v[208:211], v153 offset:17408
	ds_read_b128 v[212:215], v153 offset:18432
	ds_read_b128 v[216:219], v153 offset:19456
	ds_read_b128 v[220:223], v153 offset:20480
	ds_read_b128 v[224:227], v153 offset:21504
	ds_read_b128 v[228:231], v153 offset:22528
	ds_read_b128 v[232:235], v153 offset:23552
	s_add_i32 s31, s31, s22
	s_mov_b32 m0, s31
	s_nop 0
	global_load_lds_dwordx4 v64, s[2:3]
	s_add_i32 m0, s31, 0x2000
	s_add_u32 s34, s2, 0x40000
	s_addc_u32 s35, s3, 0
	s_add_i32 s31, s33, s22
	global_load_lds_dwordx4 v130, s[2:3]
	s_mov_b32 m0, s31
	s_mov_b64 s[100:101], s[16:17]
	global_load_lds_dwordx4 v64, s[34:35]
	s_add_i32 m0, s31, 0x2000
	s_nop 0
	global_load_lds_dwordx4 v130, s[34:35]
	s_mov_b32 m0, s23
	s_nop 0
	global_load_lds_dwordx4 v134, s[16:17]
	s_mov_b32 m0, s24
	s_nop 0
	global_load_lds_dwordx4 v132, s[16:17]
	s_waitcnt vmcnt(8)
	s_waitcnt lgkmcnt(0)
	s_barrier
	s_setprio 1
	s_waitcnt lgkmcnt(0)
	v_mfma_f32_16x16x32_bf16 v[60:63], v[140:143], v[194:197], v[60:63]
	v_mfma_f32_16x16x32_bf16 v[56:59], v[154:157], v[194:197], v[56:59]
	v_mfma_f32_16x16x32_bf16 v[44:47], v[140:143], v[212:215], v[44:47]
	v_mfma_f32_16x16x32_bf16 v[40:43], v[154:157], v[212:215], v[40:43]
	v_mfma_f32_16x16x32_bf16 v[28:31], v[140:143], v[220:223], v[28:31]
	v_mfma_f32_16x16x32_bf16 v[24:27], v[154:157], v[220:223], v[24:27]
	v_mfma_f32_16x16x32_bf16 v[12:15], v[140:143], v[228:231], v[12:15]
	v_mfma_f32_16x16x32_bf16 v[8:11], v[154:157], v[228:231], v[8:11]
	v_mfma_f32_16x16x32_bf16 v[60:63], v[144:147], v[208:211], v[60:63]
	v_mfma_f32_16x16x32_bf16 v[56:59], v[158:161], v[208:211], v[56:59]
	v_mfma_f32_16x16x32_bf16 v[44:47], v[144:147], v[216:219], v[44:47]
	v_mfma_f32_16x16x32_bf16 v[40:43], v[158:161], v[216:219], v[40:43]
	v_mfma_f32_16x16x32_bf16 v[28:31], v[144:147], v[224:227], v[28:31]
	v_mfma_f32_16x16x32_bf16 v[24:27], v[158:161], v[224:227], v[24:27]
	v_mfma_f32_16x16x32_bf16 v[12:15], v[144:147], v[232:235], v[12:15]
	v_mfma_f32_16x16x32_bf16 v[8:11], v[158:161], v[232:235], v[8:11]
	s_setprio 0
	s_setprio 1
	v_mfma_f32_16x16x32_bf16 v[52:55], v[178:181], v[194:197], v[52:55]
	v_mfma_f32_16x16x32_bf16 v[48:51], v[186:189], v[194:197], v[48:51]
	v_mfma_f32_16x16x32_bf16 v[36:39], v[178:181], v[212:215], v[36:39]
	v_mfma_f32_16x16x32_bf16 v[32:35], v[186:189], v[212:215], v[32:35]
	v_mfma_f32_16x16x32_bf16 v[20:23], v[178:181], v[220:223], v[20:23]
	v_mfma_f32_16x16x32_bf16 v[16:19], v[186:189], v[220:223], v[16:19]
	v_mfma_f32_16x16x32_bf16 v[4:7], v[178:181], v[228:231], v[4:7]
	v_mfma_f32_16x16x32_bf16 v[0:3], v[186:189], v[228:231], v[0:3]
	v_mfma_f32_16x16x32_bf16 v[52:55], v[182:185], v[208:211], v[52:55]
	v_mfma_f32_16x16x32_bf16 v[48:51], v[190:193], v[208:211], v[48:51]
	v_mfma_f32_16x16x32_bf16 v[36:39], v[182:185], v[216:219], v[36:39]
	v_mfma_f32_16x16x32_bf16 v[32:35], v[190:193], v[216:219], v[32:35]
	v_mfma_f32_16x16x32_bf16 v[20:23], v[182:185], v[224:227], v[20:23]
	v_mfma_f32_16x16x32_bf16 v[16:19], v[190:193], v[224:227], v[16:19]
	v_mfma_f32_16x16x32_bf16 v[4:7], v[182:185], v[232:235], v[4:7]
	v_mfma_f32_16x16x32_bf16 v[0:3], v[190:193], v[232:235], v[0:3]
	s_setprio 0
	s_barrier
; #define PG8_STAGE(bufoff, gbase, voff) do { _Pragma("unroll") for (int _i = 0; _i < 2; ++_i) \
;         __builtin_amdgcn_global_load_lds((const unsigned*)((const char*)(gbase) + (voff)[_i]), (PG8_LAS unsigned*)(lds + (bufoff) + ldsw + _i * 8192), 16, 0, 0); } while (0)
; #define PG8_LDA(dst, b, h) do { _Pragma("unroll") for (int m = 0; m < 4; ++m) _Pragma("unroll") for (int k = 0; k < 2; ++k) dst[m][k] = *(const PG8_LAS bf16x8*)(lds + PG8_SA(b, h) + aoff + m * 2048 + k * 1024); } while (0)
; #define PG8_LDB(dst, b, h) do { _Pragma("unroll") for (int n = 0; n < 2; ++n) _Pragma("unroll") for (int k = 0; k < 2; ++k) dst[n][k] = *(const PG8_LAS bf16x8*)(lds + PG8_SB(b, h) + boff + n * 2048 + k * 1024); } while (0)
; #define PG8_MMA(ai, bj, At, Bt) do { __builtin_amdgcn_s_setprio(1); _Pragma("unroll") for (int m = 0; m < 4; ++m) _Pragma("unroll") for (int n = 0; n < 2; ++n) _Pragma("unroll") for (int k = 0; k < 2; ++k) \
;         acc[ai][bj][m][n] = __builtin_amdgcn_mfma_f32_16x16x32_bf16(Bt[n][k], At[m][k], acc[ai][bj][m][n], 0, 0, 0); __builtin_amdgcn_s_setprio(0); } while (0)
; #define PG8_WAIT_V(n) asm volatile("s_waitcnt vmcnt(" #n ")" ::: "memory")
; #define PG8_WAIT_L(n) asm volatile("s_waitcnt lgkmcnt(" #n ")" ::: "memory")
; #define PG8_BAR __builtin_amdgcn_s_barrier()
; #define PG8_SCHED __builtin_amdgcn_sched_barrier(0)
; template <class Epi, class Sched, bool ALIGN_EPI = false, bool SP2 = false>
; __device__ __forceinline__ void gemm_phase(PG8_LAS unsigned char* lds, const Gemm g, const Sched& S, const Epi& E, const int wave0) {
;     ...
;             PG8_LDB(B0, 1, 0); PG8_LDB(B1, 1, 1); PG8_SCHED; PG8_LDA(At, 1, 0); PG8_STAGE(PG8_SA(0, 1), a2 + hstepA, voffA);
;             PG8_WAIT_V(8); PG8_WAIT_L(0); PG8_BAR; PG8_MMA(0, 0, At, B0); PG8_MMA(0, 1, At, B1); PG8_BAR; PG8_SCHED;
;             PG8_LDA(At, 1, 1); PG8_STAGE(PG8_SB(1, 0), b3, voffB); PG8_STAGE(PG8_SB(1, 1), b3 + hstepB, voffB); PG8_STAGE(PG8_SA(1, 0), a3, voffA);
;             PG8_WAIT_V(8); PG8_WAIT_L(0); PG8_BAR; PG8_MMA(1, 0, At, B0); PG8_MMA(1, 1, At, B1); PG8_BAR; PG8_SCHED;
	ds_read_b128 v[140:143], v254
	ds_read_b128 v[144:147], v254 offset:1024
	ds_read_b128 v[154:157], v254 offset:2048
	ds_read_b128 v[158:161], v254 offset:3072
	ds_read_b128 v[178:181], v255
	ds_read_b128 v[182:185], v255 offset:1024
	ds_read_b128 v[186:189], v255 offset:2048
	ds_read_b128 v[190:193], v255 offset:3072
	ds_read_b128 v[194:197], v153 offset:32768
	ds_read_b128 v[208:211], v153 offset:33792
	ds_read_b128 v[212:215], v153 offset:34816
	ds_read_b128 v[216:219], v153 offset:35840
	ds_read_b128 v[220:223], v153 offset:36864
	ds_read_b128 v[224:227], v153 offset:37888
	ds_read_b128 v[228:231], v153 offset:38912
	ds_read_b128 v[232:235], v153 offset:39936
	s_add_i32 s31, 0, 0x18000
	s_add_i32 s33, 0, 0x1c000
	s_add_u32 s16, s16, 0x40000
	s_addc_u32 s17, s17, 0
	s_mov_b32 m0, s25
	s_nop 0
	global_load_lds_dwordx4 v134, s[16:17]
	s_mov_b32 m0, s26
	s_nop 0
	global_load_lds_dwordx4 v132, s[16:17]
	s_waitcnt vmcnt(8)
	s_waitcnt lgkmcnt(0)
	s_barrier
	s_setprio 1
	s_waitcnt lgkmcnt(0)
	v_mfma_f32_16x16x32_bf16 v[126:129], v[140:143], v[194:197], v[126:129]
	v_mfma_f32_16x16x32_bf16 v[122:125], v[154:157], v[194:197], v[122:125]
	v_mfma_f32_16x16x32_bf16 v[110:113], v[140:143], v[212:215], v[110:113]
	v_mfma_f32_16x16x32_bf16 v[106:109], v[154:157], v[212:215], v[106:109]
	v_mfma_f32_16x16x32_bf16 v[94:97], v[140:143], v[220:223], v[94:97]
	v_mfma_f32_16x16x32_bf16 v[90:93], v[154:157], v[220:223], v[90:93]
	v_mfma_f32_16x16x32_bf16 v[78:81], v[140:143], v[228:231], v[78:81]
	v_mfma_f32_16x16x32_bf16 v[74:77], v[154:157], v[228:231], v[74:77]
	v_mfma_f32_16x16x32_bf16 v[126:129], v[144:147], v[208:211], v[126:129]
	v_mfma_f32_16x16x32_bf16 v[122:125], v[158:161], v[208:211], v[122:125]
	v_mfma_f32_16x16x32_bf16 v[110:113], v[144:147], v[216:219], v[110:113]
	v_mfma_f32_16x16x32_bf16 v[106:109], v[158:161], v[216:219], v[106:109]
	v_mfma_f32_16x16x32_bf16 v[94:97], v[144:147], v[224:227], v[94:97]
	v_mfma_f32_16x16x32_bf16 v[90:93], v[158:161], v[224:227], v[90:93]
	v_mfma_f32_16x16x32_bf16 v[78:81], v[144:147], v[232:235], v[78:81]
	v_mfma_f32_16x16x32_bf16 v[74:77], v[158:161], v[232:235], v[74:77]
	s_setprio 0
	s_setprio 1
	v_mfma_f32_16x16x32_bf16 v[118:121], v[178:181], v[194:197], v[118:121]
	v_mfma_f32_16x16x32_bf16 v[114:117], v[186:189], v[194:197], v[114:117]
	v_mfma_f32_16x16x32_bf16 v[102:105], v[178:181], v[212:215], v[102:105]
	v_mfma_f32_16x16x32_bf16 v[98:101], v[186:189], v[212:215], v[98:101]
	v_mfma_f32_16x16x32_bf16 v[86:89], v[178:181], v[220:223], v[86:89]
	v_mfma_f32_16x16x32_bf16 v[82:85], v[186:189], v[220:223], v[82:85]
	v_mfma_f32_16x16x32_bf16 v[70:73], v[178:181], v[228:231], v[70:73]
	v_mfma_f32_16x16x32_bf16 v[66:69], v[186:189], v[228:231], v[66:69]
	v_mfma_f32_16x16x32_bf16 v[118:121], v[182:185], v[208:211], v[118:121]
	v_mfma_f32_16x16x32_bf16 v[114:117], v[190:193], v[208:211], v[114:117]
	v_mfma_f32_16x16x32_bf16 v[102:105], v[182:185], v[216:219], v[102:105]
	v_mfma_f32_16x16x32_bf16 v[98:101], v[190:193], v[216:219], v[98:101]
	v_mfma_f32_16x16x32_bf16 v[86:89], v[182:185], v[224:227], v[86:89]
	v_mfma_f32_16x16x32_bf16 v[82:85], v[190:193], v[224:227], v[82:85]
	v_mfma_f32_16x16x32_bf16 v[70:73], v[182:185], v[232:235], v[70:73]
	v_mfma_f32_16x16x32_bf16 v[66:69], v[190:193], v[232:235], v[66:69]
	s_setprio 0
	s_barrier
	ds_read_b128 v[194:197], v153 offset:49152
	ds_read_b128 v[208:211], v153 offset:50176
	ds_read_b128 v[212:215], v153 offset:51200
	ds_read_b128 v[216:219], v153 offset:52224
	ds_read_b128 v[220:223], v153 offset:53248
	ds_read_b128 v[224:227], v153 offset:54272
	ds_read_b128 v[228:231], v153 offset:55296
	ds_read_b128 v[232:235], v153 offset:56320
	s_add_i32 s16, s31, s22
	s_add_u32 s36, s2, 0x80
	s_addc_u32 s37, s3, 0
	s_mov_b32 m0, s16
	s_nop 0
	global_load_lds_dwordx4 v64, s[36:37]
	s_add_i32 m0, s16, 0x2000
	s_add_u32 s2, s2, 0x40080
	s_addc_u32 s3, s3, 0
	s_add_i32 s16, s33, s22
	global_load_lds_dwordx4 v130, s[36:37]
	s_mov_b32 m0, s16
	s_nop 0
	global_load_lds_dwordx4 v64, s[2:3]
	s_add_i32 m0, s16, 0x2000
	s_nop 0
	global_load_lds_dwordx4 v130, s[2:3]
	s_add_u32 s100, s100, 0x80
	s_addc_u32 s101, s101, 0
	s_mov_b32 m0, s27
	s_nop 0
	global_load_lds_dwordx4 v134, s[100:101]
	s_mov_b32 m0, s28
	s_nop 0
	global_load_lds_dwordx4 v132, s[100:101]
	s_waitcnt vmcnt(8)
	s_waitcnt lgkmcnt(0)
	s_barrier
	s_setprio 1
	s_waitcnt lgkmcnt(0)
	v_mfma_f32_16x16x32_bf16 v[60:63], v[140:143], v[194:197], v[60:63]
	v_mfma_f32_16x16x32_bf16 v[56:59], v[154:157], v[194:197], v[56:59]
	v_mfma_f32_16x16x32_bf16 v[44:47], v[140:143], v[212:215], v[44:47]
	v_mfma_f32_16x16x32_bf16 v[40:43], v[154:157], v[212:215], v[40:43]
	v_mfma_f32_16x16x32_bf16 v[28:31], v[140:143], v[220:223], v[28:31]
	v_mfma_f32_16x16x32_bf16 v[24:27], v[154:157], v[220:223], v[24:27]
	v_mfma_f32_16x16x32_bf16 v[12:15], v[140:143], v[228:231], v[12:15]
	v_mfma_f32_16x16x32_bf16 v[8:11], v[154:157], v[228:231], v[8:11]
	v_mfma_f32_16x16x32_bf16 v[60:63], v[144:147], v[208:211], v[60:63]
	v_mfma_f32_16x16x32_bf16 v[56:59], v[158:161], v[208:211], v[56:59]
	v_mfma_f32_16x16x32_bf16 v[44:47], v[144:147], v[216:219], v[44:47]
	v_mfma_f32_16x16x32_bf16 v[40:43], v[158:161], v[216:219], v[40:43]
	v_mfma_f32_16x16x32_bf16 v[28:31], v[144:147], v[224:227], v[28:31]
	v_mfma_f32_16x16x32_bf16 v[24:27], v[158:161], v[224:227], v[24:27]
	v_mfma_f32_16x16x32_bf16 v[12:15], v[144:147], v[232:235], v[12:15]
	v_mfma_f32_16x16x32_bf16 v[8:11], v[158:161], v[232:235], v[8:11]
	s_setprio 0
	s_setprio 1
	v_mfma_f32_16x16x32_bf16 v[52:55], v[178:181], v[194:197], v[52:55]
	v_mfma_f32_16x16x32_bf16 v[48:51], v[186:189], v[194:197], v[48:51]
	v_mfma_f32_16x16x32_bf16 v[36:39], v[178:181], v[212:215], v[36:39]
	v_mfma_f32_16x16x32_bf16 v[32:35], v[186:189], v[212:215], v[32:35]
	v_mfma_f32_16x16x32_bf16 v[20:23], v[178:181], v[220:223], v[20:23]
	v_mfma_f32_16x16x32_bf16 v[16:19], v[186:189], v[220:223], v[16:19]
	v_mfma_f32_16x16x32_bf16 v[4:7], v[178:181], v[228:231], v[4:7]
	v_mfma_f32_16x16x32_bf16 v[0:3], v[186:189], v[228:231], v[0:3]
	v_mfma_f32_16x16x32_bf16 v[52:55], v[182:185], v[208:211], v[52:55]
	v_mfma_f32_16x16x32_bf16 v[48:51], v[190:193], v[208:211], v[48:51]
	v_mfma_f32_16x16x32_bf16 v[36:39], v[182:185], v[216:219], v[36:39]
	v_mfma_f32_16x16x32_bf16 v[32:35], v[190:193], v[216:219], v[32:35]
	v_mfma_f32_16x16x32_bf16 v[20:23], v[182:185], v[224:227], v[20:23]
	v_mfma_f32_16x16x32_bf16 v[16:19], v[190:193], v[224:227], v[16:19]
	v_mfma_f32_16x16x32_bf16 v[4:7], v[182:185], v[232:235], v[4:7]
	v_mfma_f32_16x16x32_bf16 v[0:3], v[190:193], v[232:235], v[0:3]
	s_setprio 0
	s_barrier
	s_add_i32 s19, s19, 2
	s_add_u32 s0, s0, 0x100
	s_addc_u32 s1, s1, 0
	s_add_u32 s13, s13, 0x100
	s_addc_u32 s18, s18, 0
	s_cmp_gt_u32 s19, 13
	s_cbranch_scc0 .LBB0_1231
	s_mov_b64 s[36:37], 0x80
	s_and_b64 vcc, exec, s[6:7]
	s_cbranch_vccz .LBB0_1234
	s_barrier

; #define PG8_STAGE(bufoff, gbase, voff) do { _Pragma("unroll") for (int _i = 0; _i < 2; ++_i) \
;         __builtin_amdgcn_global_load_lds((const unsigned*)((const char*)(gbase) + (voff)[_i]), (PG8_LAS unsigned*)(lds + (bufoff) + ldsw + _i * 8192), 16, 0, 0); } while (0)
; #define PG8_LDA(dst, b, h) do { _Pragma("unroll") for (int m = 0; m < 4; ++m) _Pragma("unroll") for (int k = 0; k < 2; ++k) dst[m][k] = *(const PG8_LAS bf16x8*)(lds + PG8_SA(b, h) + aoff + m * 2048 + k * 1024); } while (0)
; #define PG8_LDB(dst, b, h) do { _Pragma("unroll") for (int n = 0; n < 2; ++n) _Pragma("unroll") for (int k = 0; k < 2; ++k) dst[n][k] = *(const PG8_LAS bf16x8*)(lds + PG8_SB(b, h) + boff + n * 2048 + k * 1024); } while (0)
; #define PG8_MMA(ai, bj, At, Bt) do { __builtin_amdgcn_s_setprio(1); _Pragma("unroll") for (int m = 0; m < 4; ++m) _Pragma("unroll") for (int n = 0; n < 2; ++n) _Pragma("unroll") for (int k = 0; k < 2; ++k) \
;         acc[ai][bj][m][n] = __builtin_amdgcn_mfma_f32_16x16x32_bf16(Bt[n][k], At[m][k], acc[ai][bj][m][n], 0, 0, 0); __builtin_amdgcn_s_setprio(0); } while (0)
; #define PG8_WAIT_V(n) asm volatile("s_waitcnt vmcnt(" #n ")" ::: "memory")
; #define PG8_BAR __builtin_amdgcn_s_barrier()
; template <class Epi, class Sched, bool ALIGN_EPI = false, bool SP2 = false>
; __device__ __forceinline__ void gemm_phase(PG8_LAS unsigned char* lds, const Gemm g, const Sched& S, const Epi& E, const int wave0) {
;     ...
;         for (int t = 0; t < nt; t += 2) {
;             const bool last = (t == nt - 2);
;             const char* a1 = cA + (size_t)(t + 1) * kstep;
;             const char* a2 = last ? nA : cA + (size_t)(t + 2) * kstep; const char* b2 = last ? nB : cB + (size_t)(t + 2) * kstep;
;             const char* a3 = a2 + kstep; const char* b3 = b2 + kstep;
;             if (last && has_next) S.a_ready(nxt);
;             if constexpr (SP2) {
;             PG8_LDB(B0, 0, 0); PG8_LDB(B1, 0, 1); PG8_SCHED; PG8_LDA(At, 0, 0); PG8_STAGE(PG8_SA(1, 1), a1 + hstepA, voffA);
;             PG8_WAIT_V(8); PG8_WAIT_L(0); PG8_BAR; PG8_MMA(0, 0, At, B0); PG8_MMA(0, 1, At, B1); PG8_BAR; PG8_SCHED;
;             PG8_LDA(At, 0, 1); PG8_STAGE(PG8_SB(0, 0), b2, voffB); PG8_STAGE(PG8_SB(0, 1), b2 + hstepB, voffB); PG8_STAGE(PG8_SA(0, 0), a2, voffA);
;             PG8_WAIT_V(8); PG8_WAIT_L(0); PG8_BAR; PG8_MMA(1, 0, At, B0); PG8_MMA(1, 1, At, B1); PG8_BAR; PG8_SCHED;
.LBB0_1341:
	ds_read_b128 v[144:147], v252
	ds_read_b128 v[148:151], v252 offset:1024
	ds_read_b128 v[152:155], v252 offset:2048
	ds_read_b128 v[156:159], v252 offset:3072
	ds_read_b128 v[178:181], v253
	ds_read_b128 v[182:185], v253 offset:1024
	ds_read_b128 v[186:189], v253 offset:2048
	ds_read_b128 v[190:193], v253 offset:3072
	ds_read_b128 v[194:197], v143
	ds_read_b128 v[208:211], v143 offset:1024
	ds_read_b128 v[212:215], v143 offset:2048
	ds_read_b128 v[216:219], v143 offset:3072
	ds_read_b128 v[220:223], v143 offset:4096
	ds_read_b128 v[224:227], v143 offset:5120
	ds_read_b128 v[228:231], v143 offset:6144
	ds_read_b128 v[232:235], v143 offset:7168
	s_add_u32 s16, s0, 0xfff80080
	s_addc_u32 s17, s1, -1
	s_add_i32 s40, 0, 0x10000
	s_cmp_eq_u32 s37, 28
	s_cselect_b32 s19, s11, s17
	s_cselect_b32 s18, s33, s16
	s_cselect_b32 s17, s9, s36
	s_cselect_b32 s16, s34, s35
	s_add_i32 s42, 0, 0x14000
	s_add_i32 m0, s23, 0xc000
	s_nop 0
	global_load_lds_dwordx4 v136, s[0:1]
	s_add_i32 m0, s23, 0xe000
	s_nop 0
	global_load_lds_dwordx4 v138, s[0:1]
	s_waitcnt vmcnt(8)
	s_waitcnt lgkmcnt(0)
	s_barrier
	s_setprio 1
	s_waitcnt lgkmcnt(0)
	v_mfma_f32_16x16x32_bf16 v[126:129], v[144:147], v[194:197], v[126:129]
	v_mfma_f32_16x16x32_bf16 v[122:125], v[152:155], v[194:197], v[122:125]
	v_mfma_f32_16x16x32_bf16 v[118:121], v[144:147], v[212:215], v[118:121]
	v_mfma_f32_16x16x32_bf16 v[114:117], v[152:155], v[212:215], v[114:117]
	v_mfma_f32_16x16x32_bf16 v[102:105], v[144:147], v[220:223], v[102:105]
	v_mfma_f32_16x16x32_bf16 v[98:101], v[152:155], v[220:223], v[98:101]
	v_mfma_f32_16x16x32_bf16 v[86:89], v[144:147], v[228:231], v[86:89]
	v_mfma_f32_16x16x32_bf16 v[82:85], v[152:155], v[228:231], v[82:85]
	v_mfma_f32_16x16x32_bf16 v[126:129], v[148:151], v[208:211], v[126:129]
	v_mfma_f32_16x16x32_bf16 v[122:125], v[156:159], v[208:211], v[122:125]
	v_mfma_f32_16x16x32_bf16 v[118:121], v[148:151], v[216:219], v[118:121]
	v_mfma_f32_16x16x32_bf16 v[114:117], v[156:159], v[216:219], v[114:117]
	v_mfma_f32_16x16x32_bf16 v[102:105], v[148:151], v[224:227], v[102:105]
	v_mfma_f32_16x16x32_bf16 v[98:101], v[156:159], v[224:227], v[98:101]
	v_mfma_f32_16x16x32_bf16 v[86:89], v[148:151], v[232:235], v[86:89]
	v_mfma_f32_16x16x32_bf16 v[82:85], v[156:159], v[232:235], v[82:85]
	s_setprio 0
	s_setprio 1
	v_mfma_f32_16x16x32_bf16 v[110:113], v[178:181], v[194:197], v[110:113]
	v_mfma_f32_16x16x32_bf16 v[106:109], v[186:189], v[194:197], v[106:109]
	v_mfma_f32_16x16x32_bf16 v[94:97], v[178:181], v[212:215], v[94:97]
	v_mfma_f32_16x16x32_bf16 v[90:93], v[186:189], v[212:215], v[90:93]
	v_mfma_f32_16x16x32_bf16 v[78:81], v[178:181], v[220:223], v[78:81]
	v_mfma_f32_16x16x32_bf16 v[74:77], v[186:189], v[220:223], v[74:77]
	v_mfma_f32_16x16x32_bf16 v[70:73], v[178:181], v[228:231], v[70:73]
	v_mfma_f32_16x16x32_bf16 v[66:69], v[186:189], v[228:231], v[66:69]
	v_mfma_f32_16x16x32_bf16 v[110:113], v[182:185], v[208:211], v[110:113]
	v_mfma_f32_16x16x32_bf16 v[106:109], v[190:193], v[208:211], v[106:109]
	v_mfma_f32_16x16x32_bf16 v[94:97], v[182:185], v[216:219], v[94:97]
	v_mfma_f32_16x16x32_bf16 v[90:93], v[190:193], v[216:219], v[90:93]
	v_mfma_f32_16x16x32_bf16 v[78:81], v[182:185], v[224:227], v[78:81]
	v_mfma_f32_16x16x32_bf16 v[74:77], v[190:193], v[224:227], v[74:77]
	v_mfma_f32_16x16x32_bf16 v[70:73], v[182:185], v[232:235], v[70:73]
	v_mfma_f32_16x16x32_bf16 v[66:69], v[190:193], v[232:235], v[66:69]
	s_setprio 0
	s_barrier
	ds_read_b128 v[194:197], v143 offset:16384
	ds_read_b128 v[208:211], v143 offset:17408
	ds_read_b128 v[212:215], v143 offset:18432
	ds_read_b128 v[216:219], v143 offset:19456
	ds_read_b128 v[220:223], v143 offset:20480
	ds_read_b128 v[224:227], v143 offset:21504
	ds_read_b128 v[228:231], v143 offset:22528
	ds_read_b128 v[232:235], v143 offset:23552
	s_add_i32 s40, s40, s22
	s_mov_b32 m0, s40
	s_nop 0
	global_load_lds_dwordx4 v64, s[16:17]
	s_add_i32 m0, s40, 0x2000
	s_add_u32 s40, s16, 0x80000
	s_addc_u32 s41, s17, 0
	s_add_i32 s42, s42, s22
	global_load_lds_dwordx4 v130, s[16:17]
	s_mov_b32 m0, s42
	s_mov_b64 s[100:101], s[18:19]
	global_load_lds_dwordx4 v64, s[40:41]
	s_add_i32 m0, s42, 0x2000
	s_nop 0
	global_load_lds_dwordx4 v130, s[40:41]
	s_mov_b32 m0, s23
	s_nop 0
	global_load_lds_dwordx4 v134, s[18:19]
	s_mov_b32 m0, s24
	s_nop 0
	global_load_lds_dwordx4 v132, s[18:19]
	s_waitcnt vmcnt(8)
	s_waitcnt lgkmcnt(0)
	s_barrier
	s_setprio 1
	s_waitcnt lgkmcnt(0)
	v_mfma_f32_16x16x32_bf16 v[60:63], v[144:147], v[194:197], v[60:63]
	v_mfma_f32_16x16x32_bf16 v[56:59], v[152:155], v[194:197], v[56:59]
	v_mfma_f32_16x16x32_bf16 v[52:55], v[144:147], v[212:215], v[52:55]
	v_mfma_f32_16x16x32_bf16 v[48:51], v[152:155], v[212:215], v[48:51]
	v_mfma_f32_16x16x32_bf16 v[36:39], v[144:147], v[220:223], v[36:39]
	v_mfma_f32_16x16x32_bf16 v[32:35], v[152:155], v[220:223], v[32:35]
	v_mfma_f32_16x16x32_bf16 v[20:23], v[144:147], v[228:231], v[20:23]
	v_mfma_f32_16x16x32_bf16 v[16:19], v[152:155], v[228:231], v[16:19]
	v_mfma_f32_16x16x32_bf16 v[60:63], v[148:151], v[208:211], v[60:63]
	v_mfma_f32_16x16x32_bf16 v[56:59], v[156:159], v[208:211], v[56:59]
	v_mfma_f32_16x16x32_bf16 v[52:55], v[148:151], v[216:219], v[52:55]
	v_mfma_f32_16x16x32_bf16 v[48:51], v[156:159], v[216:219], v[48:51]
	v_mfma_f32_16x16x32_bf16 v[36:39], v[148:151], v[224:227], v[36:39]
	v_mfma_f32_16x16x32_bf16 v[32:35], v[156:159], v[224:227], v[32:35]
	v_mfma_f32_16x16x32_bf16 v[20:23], v[148:151], v[232:235], v[20:23]
	v_mfma_f32_16x16x32_bf16 v[16:19], v[156:159], v[232:235], v[16:19]
	s_setprio 0
	s_setprio 1
	v_mfma_f32_16x16x32_bf16 v[44:47], v[178:181], v[194:197], v[44:47]
	v_mfma_f32_16x16x32_bf16 v[40:43], v[186:189], v[194:197], v[40:43]
	v_mfma_f32_16x16x32_bf16 v[28:31], v[178:181], v[212:215], v[28:31]
	v_mfma_f32_16x16x32_bf16 v[24:27], v[186:189], v[212:215], v[24:27]
	v_mfma_f32_16x16x32_bf16 v[12:15], v[178:181], v[220:223], v[12:15]
	v_mfma_f32_16x16x32_bf16 v[8:11], v[186:189], v[220:223], v[8:11]
	v_mfma_f32_16x16x32_bf16 v[4:7], v[178:181], v[228:231], v[4:7]
	v_mfma_f32_16x16x32_bf16 v[0:3], v[186:189], v[228:231], v[0:3]
	v_mfma_f32_16x16x32_bf16 v[44:47], v[182:185], v[208:211], v[44:47]
	v_mfma_f32_16x16x32_bf16 v[40:43], v[190:193], v[208:211], v[40:43]
	v_mfma_f32_16x16x32_bf16 v[28:31], v[182:185], v[216:219], v[28:31]
	v_mfma_f32_16x16x32_bf16 v[24:27], v[190:193], v[216:219], v[24:27]
	v_mfma_f32_16x16x32_bf16 v[12:15], v[182:185], v[224:227], v[12:15]
	v_mfma_f32_16x16x32_bf16 v[8:11], v[190:193], v[224:227], v[8:11]
	v_mfma_f32_16x16x32_bf16 v[4:7], v[182:185], v[232:235], v[4:7]
	v_mfma_f32_16x16x32_bf16 v[0:3], v[190:193], v[232:235], v[0:3]
	s_setprio 0
	s_barrier
; #define PG8_STAGE(bufoff, gbase, voff) do { _Pragma("unroll") for (int _i = 0; _i < 2; ++_i) \
;         __builtin_amdgcn_global_load_lds((const unsigned*)((const char*)(gbase) + (voff)[_i]), (PG8_LAS unsigned*)(lds + (bufoff) + ldsw + _i * 8192), 16, 0, 0); } while (0)
; #define PG8_LDA(dst, b, h) do { _Pragma("unroll") for (int m = 0; m < 4; ++m) _Pragma("unroll") for (int k = 0; k < 2; ++k) dst[m][k] = *(const PG8_LAS bf16x8*)(lds + PG8_SA(b, h) + aoff + m * 2048 + k * 1024); } while (0)
; #define PG8_LDB(dst, b, h) do { _Pragma("unroll") for (int n = 0; n < 2; ++n) _Pragma("unroll") for (int k = 0; k < 2; ++k) dst[n][k] = *(const PG8_LAS bf16x8*)(lds + PG8_SB(b, h) + boff + n * 2048 + k * 1024); } while (0)
; #define PG8_MMA(ai, bj, At, Bt) do { __builtin_amdgcn_s_setprio(1); _Pragma("unroll") for (int m = 0; m < 4; ++m) _Pragma("unroll") for (int n = 0; n < 2; ++n) _Pragma("unroll") for (int k = 0; k < 2; ++k) \
;         acc[ai][bj][m][n] = __builtin_amdgcn_mfma_f32_16x16x32_bf16(Bt[n][k], At[m][k], acc[ai][bj][m][n], 0, 0, 0); __builtin_amdgcn_s_setprio(0); } while (0)
; #define PG8_WAIT_V(n) asm volatile("s_waitcnt vmcnt(" #n ")" ::: "memory")
; #define PG8_WAIT_L(n) asm volatile("s_waitcnt lgkmcnt(" #n ")" ::: "memory")
; #define PG8_BAR __builtin_amdgcn_s_barrier()
; #define PG8_SCHED __builtin_amdgcn_sched_barrier(0)
; template <class Epi, class Sched, bool ALIGN_EPI = false, bool SP2 = false>
; __device__ __forceinline__ void gemm_phase(PG8_LAS unsigned char* lds, const Gemm g, const Sched& S, const Epi& E, const int wave0) {
;     ...
;             PG8_LDB(B0, 1, 0); PG8_LDB(B1, 1, 1); PG8_SCHED; PG8_LDA(At, 1, 0); PG8_STAGE(PG8_SA(0, 1), a2 + hstepA, voffA);
;             PG8_WAIT_V(8); PG8_WAIT_L(0); PG8_BAR; PG8_MMA(0, 0, At, B0); PG8_MMA(0, 1, At, B1); PG8_BAR; PG8_SCHED;
;             PG8_LDA(At, 1, 1); PG8_STAGE(PG8_SB(1, 0), b3, voffB); PG8_STAGE(PG8_SB(1, 1), b3 + hstepB, voffB); PG8_STAGE(PG8_SA(1, 0), a3, voffA);
;             PG8_WAIT_V(8); PG8_WAIT_L(0); PG8_BAR; PG8_MMA(1, 0, At, B0); PG8_MMA(1, 1, At, B1); PG8_BAR; PG8_SCHED;
	ds_read_b128 v[144:147], v254
	ds_read_b128 v[148:151], v254 offset:1024
	ds_read_b128 v[152:155], v254 offset:2048
	ds_read_b128 v[156:159], v254 offset:3072
	ds_read_b128 v[178:181], v255
	ds_read_b128 v[182:185], v255 offset:1024
	ds_read_b128 v[186:189], v255 offset:2048
	ds_read_b128 v[190:193], v255 offset:3072
	ds_read_b128 v[194:197], v143 offset:32768
	ds_read_b128 v[208:211], v143 offset:33792
	ds_read_b128 v[212:215], v143 offset:34816
	ds_read_b128 v[216:219], v143 offset:35840
	ds_read_b128 v[220:223], v143 offset:36864
	ds_read_b128 v[224:227], v143 offset:37888
	ds_read_b128 v[228:231], v143 offset:38912
	ds_read_b128 v[232:235], v143 offset:39936
	s_add_i32 s40, 0, 0x18000
	s_add_i32 s41, 0, 0x1c000
	s_add_u32 s18, s18, 0x80000
	s_addc_u32 s19, s19, 0
	s_mov_b32 m0, s25
	s_nop 0
	global_load_lds_dwordx4 v134, s[18:19]
	s_mov_b32 m0, s26
	s_nop 0
	global_load_lds_dwordx4 v132, s[18:19]
	s_waitcnt vmcnt(8)
	s_waitcnt lgkmcnt(0)
	s_barrier
	s_setprio 1
	s_waitcnt lgkmcnt(0)
	v_mfma_f32_16x16x32_bf16 v[126:129], v[144:147], v[194:197], v[126:129]
	v_mfma_f32_16x16x32_bf16 v[122:125], v[152:155], v[194:197], v[122:125]
	v_mfma_f32_16x16x32_bf16 v[118:121], v[144:147], v[212:215], v[118:121]
	v_mfma_f32_16x16x32_bf16 v[114:117], v[152:155], v[212:215], v[114:117]
	v_mfma_f32_16x16x32_bf16 v[102:105], v[144:147], v[220:223], v[102:105]
	v_mfma_f32_16x16x32_bf16 v[98:101], v[152:155], v[220:223], v[98:101]
	v_mfma_f32_16x16x32_bf16 v[86:89], v[144:147], v[228:231], v[86:89]
	v_mfma_f32_16x16x32_bf16 v[82:85], v[152:155], v[228:231], v[82:85]
	v_mfma_f32_16x16x32_bf16 v[126:129], v[148:151], v[208:211], v[126:129]
	v_mfma_f32_16x16x32_bf16 v[122:125], v[156:159], v[208:211], v[122:125]
	v_mfma_f32_16x16x32_bf16 v[118:121], v[148:151], v[216:219], v[118:121]
	v_mfma_f32_16x16x32_bf16 v[114:117], v[156:159], v[216:219], v[114:117]
	v_mfma_f32_16x16x32_bf16 v[102:105], v[148:151], v[224:227], v[102:105]
	v_mfma_f32_16x16x32_bf16 v[98:101], v[156:159], v[224:227], v[98:101]
	v_mfma_f32_16x16x32_bf16 v[86:89], v[148:151], v[232:235], v[86:89]
	v_mfma_f32_16x16x32_bf16 v[82:85], v[156:159], v[232:235], v[82:85]
	s_setprio 0
	s_setprio 1
	v_mfma_f32_16x16x32_bf16 v[110:113], v[178:181], v[194:197], v[110:113]
	v_mfma_f32_16x16x32_bf16 v[106:109], v[186:189], v[194:197], v[106:109]
	v_mfma_f32_16x16x32_bf16 v[94:97], v[178:181], v[212:215], v[94:97]
	v_mfma_f32_16x16x32_bf16 v[90:93], v[186:189], v[212:215], v[90:93]
	v_mfma_f32_16x16x32_bf16 v[78:81], v[178:181], v[220:223], v[78:81]
	v_mfma_f32_16x16x32_bf16 v[74:77], v[186:189], v[220:223], v[74:77]
	v_mfma_f32_16x16x32_bf16 v[70:73], v[178:181], v[228:231], v[70:73]
	v_mfma_f32_16x16x32_bf16 v[66:69], v[186:189], v[228:231], v[66:69]
	v_mfma_f32_16x16x32_bf16 v[110:113], v[182:185], v[208:211], v[110:113]
	v_mfma_f32_16x16x32_bf16 v[106:109], v[190:193], v[208:211], v[106:109]
	v_mfma_f32_16x16x32_bf16 v[94:97], v[182:185], v[216:219], v[94:97]
	v_mfma_f32_16x16x32_bf16 v[90:93], v[190:193], v[216:219], v[90:93]
	v_mfma_f32_16x16x32_bf16 v[78:81], v[182:185], v[224:227], v[78:81]
	v_mfma_f32_16x16x32_bf16 v[74:77], v[190:193], v[224:227], v[74:77]
	v_mfma_f32_16x16x32_bf16 v[70:73], v[182:185], v[232:235], v[70:73]
	v_mfma_f32_16x16x32_bf16 v[66:69], v[190:193], v[232:235], v[66:69]
	s_setprio 0
	s_barrier
	ds_read_b128 v[194:197], v143 offset:49152
	ds_read_b128 v[208:211], v143 offset:50176
	ds_read_b128 v[212:215], v143 offset:51200
	ds_read_b128 v[216:219], v143 offset:52224
	ds_read_b128 v[220:223], v143 offset:53248
	ds_read_b128 v[224:227], v143 offset:54272
	ds_read_b128 v[228:231], v143 offset:55296
	ds_read_b128 v[232:235], v143 offset:56320
	s_add_i32 s18, s40, s22
	s_add_u32 s44, s16, 0x80
	s_addc_u32 s45, s17, 0
	s_mov_b32 m0, s18
	s_nop 0
	global_load_lds_dwordx4 v64, s[44:45]
	s_add_i32 m0, s18, 0x2000
	s_add_u32 s16, s16, 0x80080
	s_addc_u32 s17, s17, 0
	s_add_i32 s18, s41, s22
	global_load_lds_dwordx4 v130, s[44:45]
	s_mov_b32 m0, s18
	s_nop 0
	global_load_lds_dwordx4 v64, s[16:17]
	s_add_i32 m0, s18, 0x2000
	s_nop 0
	global_load_lds_dwordx4 v130, s[16:17]
	s_add_u32 s100, s100, 0x80
	s_addc_u32 s101, s101, 0
	s_mov_b32 m0, s27
	s_nop 0
	global_load_lds_dwordx4 v134, s[100:101]
	s_mov_b32 m0, s28
	s_nop 0
	global_load_lds_dwordx4 v132, s[100:101]
	s_waitcnt vmcnt(8)
	s_waitcnt lgkmcnt(0)
	s_barrier
	s_setprio 1
	s_waitcnt lgkmcnt(0)
	v_mfma_f32_16x16x32_bf16 v[60:63], v[144:147], v[194:197], v[60:63]
	v_mfma_f32_16x16x32_bf16 v[56:59], v[152:155], v[194:197], v[56:59]
	v_mfma_f32_16x16x32_bf16 v[52:55], v[144:147], v[212:215], v[52:55]
	v_mfma_f32_16x16x32_bf16 v[48:51], v[152:155], v[212:215], v[48:51]
	v_mfma_f32_16x16x32_bf16 v[36:39], v[144:147], v[220:223], v[36:39]
	v_mfma_f32_16x16x32_bf16 v[32:35], v[152:155], v[220:223], v[32:35]
	v_mfma_f32_16x16x32_bf16 v[20:23], v[144:147], v[228:231], v[20:23]
	v_mfma_f32_16x16x32_bf16 v[16:19], v[152:155], v[228:231], v[16:19]
	v_mfma_f32_16x16x32_bf16 v[60:63], v[148:151], v[208:211], v[60:63]
	v_mfma_f32_16x16x32_bf16 v[56:59], v[156:159], v[208:211], v[56:59]
	v_mfma_f32_16x16x32_bf16 v[52:55], v[148:151], v[216:219], v[52:55]
	v_mfma_f32_16x16x32_bf16 v[48:51], v[156:159], v[216:219], v[48:51]
	v_mfma_f32_16x16x32_bf16 v[36:39], v[148:151], v[224:227], v[36:39]
	v_mfma_f32_16x16x32_bf16 v[32:35], v[156:159], v[224:227], v[32:35]
	v_mfma_f32_16x16x32_bf16 v[20:23], v[148:151], v[232:235], v[20:23]
	v_mfma_f32_16x16x32_bf16 v[16:19], v[156:159], v[232:235], v[16:19]
	s_setprio 0
	s_setprio 1
	v_mfma_f32_16x16x32_bf16 v[44:47], v[178:181], v[194:197], v[44:47]
	v_mfma_f32_16x16x32_bf16 v[40:43], v[186:189], v[194:197], v[40:43]
	v_mfma_f32_16x16x32_bf16 v[28:31], v[178:181], v[212:215], v[28:31]
	v_mfma_f32_16x16x32_bf16 v[24:27], v[186:189], v[212:215], v[24:27]
	v_mfma_f32_16x16x32_bf16 v[12:15], v[178:181], v[220:223], v[12:15]
	v_mfma_f32_16x16x32_bf16 v[8:11], v[186:189], v[220:223], v[8:11]
	v_mfma_f32_16x16x32_bf16 v[4:7], v[178:181], v[228:231], v[4:7]
	v_mfma_f32_16x16x32_bf16 v[0:3], v[186:189], v[228:231], v[0:3]
	v_mfma_f32_16x16x32_bf16 v[44:47], v[182:185], v[208:211], v[44:47]
	v_mfma_f32_16x16x32_bf16 v[40:43], v[190:193], v[208:211], v[40:43]
	v_mfma_f32_16x16x32_bf16 v[28:31], v[182:185], v[216:219], v[28:31]
	v_mfma_f32_16x16x32_bf16 v[24:27], v[190:193], v[216:219], v[24:27]
	v_mfma_f32_16x16x32_bf16 v[12:15], v[182:185], v[224:227], v[12:15]
	v_mfma_f32_16x16x32_bf16 v[8:11], v[190:193], v[224:227], v[8:11]
	v_mfma_f32_16x16x32_bf16 v[4:7], v[182:185], v[232:235], v[4:7]
	v_mfma_f32_16x16x32_bf16 v[0:3], v[190:193], v[232:235], v[0:3]
	s_setprio 0
	s_barrier
	s_add_i32 s37, s37, 2
	s_add_u32 s0, s0, 0x100
	s_addc_u32 s1, s1, 0
	s_add_u32 s35, s35, 0x100
	s_addc_u32 s36, s36, 0
	s_cmp_gt_u32 s37, 29
	s_cbranch_scc0 .LBB0_1341
	s_mov_b64 s[44:45], 0x80
	s_and_b64 vcc, exec, s[6:7]
	s_mov_b64 s[34:35], 0x45000
	s_cbranch_vccz .LBB0_1344
	s_barrier

; #define PG8_STAGE(bufoff, gbase, voff) do { _Pragma("unroll") for (int _i = 0; _i < 2; ++_i) \
;         __builtin_amdgcn_global_load_lds((const unsigned*)((const char*)(gbase) + (voff)[_i]), (PG8_LAS unsigned*)(lds + (bufoff) + ldsw + _i * 8192), 16, 0, 0); } while (0)
; #define PG8_LDA(dst, b, h) do { _Pragma("unroll") for (int m = 0; m < 4; ++m) _Pragma("unroll") for (int k = 0; k < 2; ++k) dst[m][k] = *(const PG8_LAS bf16x8*)(lds + PG8_SA(b, h) + aoff + m * 2048 + k * 1024); } while (0)
; #define PG8_LDB(dst, b, h) do { _Pragma("unroll") for (int n = 0; n < 2; ++n) _Pragma("unroll") for (int k = 0; k < 2; ++k) dst[n][k] = *(const PG8_LAS bf16x8*)(lds + PG8_SB(b, h) + boff + n * 2048 + k * 1024); } while (0)
; #define PG8_MMA(ai, bj, At, Bt) do { __builtin_amdgcn_s_setprio(1); _Pragma("unroll") for (int m = 0; m < 4; ++m) _Pragma("unroll") for (int n = 0; n < 2; ++n) _Pragma("unroll") for (int k = 0; k < 2; ++k) \
;         acc[ai][bj][m][n] = __builtin_amdgcn_mfma_f32_16x16x32_bf16(Bt[n][k], At[m][k], acc[ai][bj][m][n], 0, 0, 0); __builtin_amdgcn_s_setprio(0); } while (0)
; #define PG8_WAIT_V(n) asm volatile("s_waitcnt vmcnt(" #n ")" ::: "memory")
; #define PG8_BAR __builtin_amdgcn_s_barrier()
; template <class Epi, class Sched, bool ALIGN_EPI = false, bool SP2 = false>
; __device__ __forceinline__ void gemm_phase(PG8_LAS unsigned char* lds, const Gemm g, const Sched& S, const Epi& E, const int wave0) {
;     ...
;         for (int t = 0; t < nt; t += 2) {
;             const bool last = (t == nt - 2);
;             const char* a1 = cA + (size_t)(t + 1) * kstep;
;             const char* a2 = last ? nA : cA + (size_t)(t + 2) * kstep; const char* b2 = last ? nB : cB + (size_t)(t + 2) * kstep;
;             const char* a3 = a2 + kstep; const char* b3 = b2 + kstep;
;             if (last && has_next) S.a_ready(nxt);
;             if constexpr (SP2) {
;             PG8_LDB(B0, 0, 0); PG8_LDB(B1, 0, 1); PG8_SCHED; PG8_LDA(At, 0, 0); PG8_STAGE(PG8_SA(1, 1), a1 + hstepA, voffA);
;             PG8_WAIT_V(8); PG8_WAIT_L(0); PG8_BAR; PG8_MMA(0, 0, At, B0); PG8_MMA(0, 1, At, B1); PG8_BAR; PG8_SCHED;
;             PG8_LDA(At, 0, 1); PG8_STAGE(PG8_SB(0, 0), b2, voffB); PG8_STAGE(PG8_SB(0, 1), b2 + hstepB, voffB); PG8_STAGE(PG8_SA(0, 0), a2, voffA);
;             PG8_WAIT_V(8); PG8_WAIT_L(0); PG8_BAR; PG8_MMA(1, 0, At, B0); PG8_MMA(1, 1, At, B1); PG8_BAR; PG8_SCHED;
.LBB0_1360:
	ds_read_b128 v[144:147], v252
	ds_read_b128 v[148:151], v252 offset:1024
	ds_read_b128 v[152:155], v252 offset:2048
	ds_read_b128 v[156:159], v252 offset:3072
	ds_read_b128 v[178:181], v253
	ds_read_b128 v[182:185], v253 offset:1024
	ds_read_b128 v[186:189], v253 offset:2048
	ds_read_b128 v[190:193], v253 offset:3072
	ds_read_b128 v[194:197], v143
	ds_read_b128 v[208:211], v143 offset:1024
	ds_read_b128 v[212:215], v143 offset:2048
	ds_read_b128 v[216:219], v143 offset:3072
	ds_read_b128 v[220:223], v143 offset:4096
	ds_read_b128 v[224:227], v143 offset:5120
	ds_read_b128 v[228:231], v143 offset:6144
	ds_read_b128 v[232:235], v143 offset:7168
	s_add_u32 s16, s0, 0xfff80080
	s_addc_u32 s17, s1, -1
	s_add_i32 s42, 0, 0x10000
	s_cmp_eq_u32 s41, 12
	s_cselect_b32 s19, s5, s17
	s_cselect_b32 s18, s4, s16
	s_cselect_b32 s17, s11, s27
	s_cselect_b32 s16, s13, s15
	s_add_i32 s44, 0, 0x14000
	s_add_i32 m0, s23, 0xc000
	s_nop 0
	global_load_lds_dwordx4 v136, s[0:1]
	s_add_i32 m0, s23, 0xe000
	s_nop 0
	global_load_lds_dwordx4 v138, s[0:1]
	s_waitcnt vmcnt(8)
	s_waitcnt lgkmcnt(0)
	s_barrier
	s_setprio 1
	s_waitcnt lgkmcnt(0)
	v_mfma_f32_16x16x32_bf16 v[126:129], v[144:147], v[194:197], v[126:129]
	v_mfma_f32_16x16x32_bf16 v[122:125], v[152:155], v[194:197], v[122:125]
	v_mfma_f32_16x16x32_bf16 v[118:121], v[144:147], v[212:215], v[118:121]
	v_mfma_f32_16x16x32_bf16 v[114:117], v[152:155], v[212:215], v[114:117]
	v_mfma_f32_16x16x32_bf16 v[102:105], v[144:147], v[220:223], v[102:105]
	v_mfma_f32_16x16x32_bf16 v[98:101], v[152:155], v[220:223], v[98:101]
	v_mfma_f32_16x16x32_bf16 v[86:89], v[144:147], v[228:231], v[86:89]
	v_mfma_f32_16x16x32_bf16 v[82:85], v[152:155], v[228:231], v[82:85]
	v_mfma_f32_16x16x32_bf16 v[126:129], v[148:151], v[208:211], v[126:129]
	v_mfma_f32_16x16x32_bf16 v[122:125], v[156:159], v[208:211], v[122:125]
	v_mfma_f32_16x16x32_bf16 v[118:121], v[148:151], v[216:219], v[118:121]
	v_mfma_f32_16x16x32_bf16 v[114:117], v[156:159], v[216:219], v[114:117]
	v_mfma_f32_16x16x32_bf16 v[102:105], v[148:151], v[224:227], v[102:105]
	v_mfma_f32_16x16x32_bf16 v[98:101], v[156:159], v[224:227], v[98:101]
	v_mfma_f32_16x16x32_bf16 v[86:89], v[148:151], v[232:235], v[86:89]
	v_mfma_f32_16x16x32_bf16 v[82:85], v[156:159], v[232:235], v[82:85]
	s_setprio 0
	s_setprio 1
	v_mfma_f32_16x16x32_bf16 v[110:113], v[178:181], v[194:197], v[110:113]
	v_mfma_f32_16x16x32_bf16 v[106:109], v[186:189], v[194:197], v[106:109]
	v_mfma_f32_16x16x32_bf16 v[94:97], v[178:181], v[212:215], v[94:97]
	v_mfma_f32_16x16x32_bf16 v[90:93], v[186:189], v[212:215], v[90:93]
	v_mfma_f32_16x16x32_bf16 v[78:81], v[178:181], v[220:223], v[78:81]
	v_mfma_f32_16x16x32_bf16 v[74:77], v[186:189], v[220:223], v[74:77]
	v_mfma_f32_16x16x32_bf16 v[70:73], v[178:181], v[228:231], v[70:73]
	v_mfma_f32_16x16x32_bf16 v[66:69], v[186:189], v[228:231], v[66:69]
	v_mfma_f32_16x16x32_bf16 v[110:113], v[182:185], v[208:211], v[110:113]
	v_mfma_f32_16x16x32_bf16 v[106:109], v[190:193], v[208:211], v[106:109]
	v_mfma_f32_16x16x32_bf16 v[94:97], v[182:185], v[216:219], v[94:97]
	v_mfma_f32_16x16x32_bf16 v[90:93], v[190:193], v[216:219], v[90:93]
	v_mfma_f32_16x16x32_bf16 v[78:81], v[182:185], v[224:227], v[78:81]
	v_mfma_f32_16x16x32_bf16 v[74:77], v[190:193], v[224:227], v[74:77]
	v_mfma_f32_16x16x32_bf16 v[70:73], v[182:185], v[232:235], v[70:73]
	v_mfma_f32_16x16x32_bf16 v[66:69], v[190:193], v[232:235], v[66:69]
	s_setprio 0
	s_barrier
	ds_read_b128 v[194:197], v143 offset:16384
	ds_read_b128 v[208:211], v143 offset:17408
	ds_read_b128 v[212:215], v143 offset:18432
	ds_read_b128 v[216:219], v143 offset:19456
	ds_read_b128 v[220:223], v143 offset:20480
	ds_read_b128 v[224:227], v143 offset:21504
	ds_read_b128 v[228:231], v143 offset:22528
	ds_read_b128 v[232:235], v143 offset:23552
	s_add_i32 s42, s42, s22
	s_mov_b32 m0, s42
	s_nop 0
	global_load_lds_dwordx4 v64, s[16:17]
	s_add_i32 m0, s42, 0x2000
	s_add_u32 s42, s16, 0x80000
	s_addc_u32 s43, s17, 0
	s_add_i32 s44, s44, s22
	global_load_lds_dwordx4 v130, s[16:17]
	s_mov_b32 m0, s44
	s_mov_b64 s[100:101], s[18:19]
	global_load_lds_dwordx4 v64, s[42:43]
	s_add_i32 m0, s44, 0x2000
	s_nop 0
	global_load_lds_dwordx4 v130, s[42:43]
	s_mov_b32 m0, s23
	s_nop 0
	global_load_lds_dwordx4 v134, s[18:19]
	s_mov_b32 m0, s24
	s_nop 0
	global_load_lds_dwordx4 v132, s[18:19]
	s_waitcnt vmcnt(8)
	s_waitcnt lgkmcnt(0)
	s_barrier
	s_setprio 1
	s_waitcnt lgkmcnt(0)
	v_mfma_f32_16x16x32_bf16 v[60:63], v[144:147], v[194:197], v[60:63]
	v_mfma_f32_16x16x32_bf16 v[56:59], v[152:155], v[194:197], v[56:59]
	v_mfma_f32_16x16x32_bf16 v[52:55], v[144:147], v[212:215], v[52:55]
	v_mfma_f32_16x16x32_bf16 v[48:51], v[152:155], v[212:215], v[48:51]
	v_mfma_f32_16x16x32_bf16 v[36:39], v[144:147], v[220:223], v[36:39]
	v_mfma_f32_16x16x32_bf16 v[32:35], v[152:155], v[220:223], v[32:35]
	v_mfma_f32_16x16x32_bf16 v[20:23], v[144:147], v[228:231], v[20:23]
	v_mfma_f32_16x16x32_bf16 v[16:19], v[152:155], v[228:231], v[16:19]
	v_mfma_f32_16x16x32_bf16 v[60:63], v[148:151], v[208:211], v[60:63]
	v_mfma_f32_16x16x32_bf16 v[56:59], v[156:159], v[208:211], v[56:59]
	v_mfma_f32_16x16x32_bf16 v[52:55], v[148:151], v[216:219], v[52:55]
	v_mfma_f32_16x16x32_bf16 v[48:51], v[156:159], v[216:219], v[48:51]
	v_mfma_f32_16x16x32_bf16 v[36:39], v[148:151], v[224:227], v[36:39]
	v_mfma_f32_16x16x32_bf16 v[32:35], v[156:159], v[224:227], v[32:35]
	v_mfma_f32_16x16x32_bf16 v[20:23], v[148:151], v[232:235], v[20:23]
	v_mfma_f32_16x16x32_bf16 v[16:19], v[156:159], v[232:235], v[16:19]
	s_setprio 0
	s_setprio 1
	v_mfma_f32_16x16x32_bf16 v[44:47], v[178:181], v[194:197], v[44:47]
	v_mfma_f32_16x16x32_bf16 v[40:43], v[186:189], v[194:197], v[40:43]
	v_mfma_f32_16x16x32_bf16 v[28:31], v[178:181], v[212:215], v[28:31]
	v_mfma_f32_16x16x32_bf16 v[24:27], v[186:189], v[212:215], v[24:27]
	v_mfma_f32_16x16x32_bf16 v[12:15], v[178:181], v[220:223], v[12:15]
	v_mfma_f32_16x16x32_bf16 v[8:11], v[186:189], v[220:223], v[8:11]
	v_mfma_f32_16x16x32_bf16 v[4:7], v[178:181], v[228:231], v[4:7]
	v_mfma_f32_16x16x32_bf16 v[0:3], v[186:189], v[228:231], v[0:3]
	v_mfma_f32_16x16x32_bf16 v[44:47], v[182:185], v[208:211], v[44:47]
	v_mfma_f32_16x16x32_bf16 v[40:43], v[190:193], v[208:211], v[40:43]
	v_mfma_f32_16x16x32_bf16 v[28:31], v[182:185], v[216:219], v[28:31]
	v_mfma_f32_16x16x32_bf16 v[24:27], v[190:193], v[216:219], v[24:27]
	v_mfma_f32_16x16x32_bf16 v[12:15], v[182:185], v[224:227], v[12:15]
	v_mfma_f32_16x16x32_bf16 v[8:11], v[190:193], v[224:227], v[8:11]
	v_mfma_f32_16x16x32_bf16 v[4:7], v[182:185], v[232:235], v[4:7]
	v_mfma_f32_16x16x32_bf16 v[0:3], v[190:193], v[232:235], v[0:3]
	s_setprio 0
	s_barrier
; #define PG8_STAGE(bufoff, gbase, voff) do { _Pragma("unroll") for (int _i = 0; _i < 2; ++_i) \
;         __builtin_amdgcn_global_load_lds((const unsigned*)((const char*)(gbase) + (voff)[_i]), (PG8_LAS unsigned*)(lds + (bufoff) + ldsw + _i * 8192), 16, 0, 0); } while (0)
; #define PG8_LDA(dst, b, h) do { _Pragma("unroll") for (int m = 0; m < 4; ++m) _Pragma("unroll") for (int k = 0; k < 2; ++k) dst[m][k] = *(const PG8_LAS bf16x8*)(lds + PG8_SA(b, h) + aoff + m * 2048 + k * 1024); } while (0)
; #define PG8_LDB(dst, b, h) do { _Pragma("unroll") for (int n = 0; n < 2; ++n) _Pragma("unroll") for (int k = 0; k < 2; ++k) dst[n][k] = *(const PG8_LAS bf16x8*)(lds + PG8_SB(b, h) + boff + n * 2048 + k * 1024); } while (0)
; #define PG8_MMA(ai, bj, At, Bt) do { __builtin_amdgcn_s_setprio(1); _Pragma("unroll") for (int m = 0; m < 4; ++m) _Pragma("unroll") for (int n = 0; n < 2; ++n) _Pragma("unroll") for (int k = 0; k < 2; ++k) \
;         acc[ai][bj][m][n] = __builtin_amdgcn_mfma_f32_16x16x32_bf16(Bt[n][k], At[m][k], acc[ai][bj][m][n], 0, 0, 0); __builtin_amdgcn_s_setprio(0); } while (0)
; #define PG8_WAIT_V(n) asm volatile("s_waitcnt vmcnt(" #n ")" ::: "memory")
; #define PG8_WAIT_L(n) asm volatile("s_waitcnt lgkmcnt(" #n ")" ::: "memory")
; #define PG8_BAR __builtin_amdgcn_s_barrier()
; #define PG8_SCHED __builtin_amdgcn_sched_barrier(0)
; template <class Epi, class Sched, bool ALIGN_EPI = false, bool SP2 = false>
; __device__ __forceinline__ void gemm_phase(PG8_LAS unsigned char* lds, const Gemm g, const Sched& S, const Epi& E, const int wave0) {
;     ...
;             PG8_LDB(B0, 1, 0); PG8_LDB(B1, 1, 1); PG8_SCHED; PG8_LDA(At, 1, 0); PG8_STAGE(PG8_SA(0, 1), a2 + hstepA, voffA);
;             PG8_WAIT_V(8); PG8_WAIT_L(0); PG8_BAR; PG8_MMA(0, 0, At, B0); PG8_MMA(0, 1, At, B1); PG8_BAR; PG8_SCHED;
;             PG8_LDA(At, 1, 1); PG8_STAGE(PG8_SB(1, 0), b3, voffB); PG8_STAGE(PG8_SB(1, 1), b3 + hstepB, voffB); PG8_STAGE(PG8_SA(1, 0), a3, voffA);
;             PG8_WAIT_V(8); PG8_WAIT_L(0); PG8_BAR; PG8_MMA(1, 0, At, B0); PG8_MMA(1, 1, At, B1); PG8_BAR; PG8_SCHED;
	ds_read_b128 v[144:147], v254
	ds_read_b128 v[148:151], v254 offset:1024
	ds_read_b128 v[152:155], v254 offset:2048
	ds_read_b128 v[156:159], v254 offset:3072
	ds_read_b128 v[178:181], v255
	ds_read_b128 v[182:185], v255 offset:1024
	ds_read_b128 v[186:189], v255 offset:2048
	ds_read_b128 v[190:193], v255 offset:3072
	ds_read_b128 v[194:197], v143 offset:32768
	ds_read_b128 v[208:211], v143 offset:33792
	ds_read_b128 v[212:215], v143 offset:34816
	ds_read_b128 v[216:219], v143 offset:35840
	ds_read_b128 v[220:223], v143 offset:36864
	ds_read_b128 v[224:227], v143 offset:37888
	ds_read_b128 v[228:231], v143 offset:38912
	ds_read_b128 v[232:235], v143 offset:39936
	s_add_i32 s42, 0, 0x18000
	s_add_i32 s43, 0, 0x1c000
	s_add_u32 s18, s18, 0x80000
	s_addc_u32 s19, s19, 0
	s_mov_b32 m0, s25
	s_nop 0
	global_load_lds_dwordx4 v134, s[18:19]
	s_mov_b32 m0, s33
	s_nop 0
	global_load_lds_dwordx4 v132, s[18:19]
	s_waitcnt vmcnt(8)
	s_waitcnt lgkmcnt(0)
	s_barrier
	s_setprio 1
	s_waitcnt lgkmcnt(0)
	v_mfma_f32_16x16x32_bf16 v[126:129], v[144:147], v[194:197], v[126:129]
	v_mfma_f32_16x16x32_bf16 v[122:125], v[152:155], v[194:197], v[122:125]
	v_mfma_f32_16x16x32_bf16 v[118:121], v[144:147], v[212:215], v[118:121]
	v_mfma_f32_16x16x32_bf16 v[114:117], v[152:155], v[212:215], v[114:117]
	v_mfma_f32_16x16x32_bf16 v[102:105], v[144:147], v[220:223], v[102:105]
	v_mfma_f32_16x16x32_bf16 v[98:101], v[152:155], v[220:223], v[98:101]
	v_mfma_f32_16x16x32_bf16 v[86:89], v[144:147], v[228:231], v[86:89]
	v_mfma_f32_16x16x32_bf16 v[82:85], v[152:155], v[228:231], v[82:85]
	v_mfma_f32_16x16x32_bf16 v[126:129], v[148:151], v[208:211], v[126:129]
	v_mfma_f32_16x16x32_bf16 v[122:125], v[156:159], v[208:211], v[122:125]
	v_mfma_f32_16x16x32_bf16 v[118:121], v[148:151], v[216:219], v[118:121]
	v_mfma_f32_16x16x32_bf16 v[114:117], v[156:159], v[216:219], v[114:117]
	v_mfma_f32_16x16x32_bf16 v[102:105], v[148:151], v[224:227], v[102:105]
	v_mfma_f32_16x16x32_bf16 v[98:101], v[156:159], v[224:227], v[98:101]
	v_mfma_f32_16x16x32_bf16 v[86:89], v[148:151], v[232:235], v[86:89]
	v_mfma_f32_16x16x32_bf16 v[82:85], v[156:159], v[232:235], v[82:85]
	s_setprio 0
	s_setprio 1
	v_mfma_f32_16x16x32_bf16 v[110:113], v[178:181], v[194:197], v[110:113]
	v_mfma_f32_16x16x32_bf16 v[106:109], v[186:189], v[194:197], v[106:109]
	v_mfma_f32_16x16x32_bf16 v[94:97], v[178:181], v[212:215], v[94:97]
	v_mfma_f32_16x16x32_bf16 v[90:93], v[186:189], v[212:215], v[90:93]
	v_mfma_f32_16x16x32_bf16 v[78:81], v[178:181], v[220:223], v[78:81]
	v_mfma_f32_16x16x32_bf16 v[74:77], v[186:189], v[220:223], v[74:77]
	v_mfma_f32_16x16x32_bf16 v[70:73], v[178:181], v[228:231], v[70:73]
	v_mfma_f32_16x16x32_bf16 v[66:69], v[186:189], v[228:231], v[66:69]
	v_mfma_f32_16x16x32_bf16 v[110:113], v[182:185], v[208:211], v[110:113]
	v_mfma_f32_16x16x32_bf16 v[106:109], v[190:193], v[208:211], v[106:109]
	v_mfma_f32_16x16x32_bf16 v[94:97], v[182:185], v[216:219], v[94:97]
	v_mfma_f32_16x16x32_bf16 v[90:93], v[190:193], v[216:219], v[90:93]
	v_mfma_f32_16x16x32_bf16 v[78:81], v[182:185], v[224:227], v[78:81]
	v_mfma_f32_16x16x32_bf16 v[74:77], v[190:193], v[224:227], v[74:77]
	v_mfma_f32_16x16x32_bf16 v[70:73], v[182:185], v[232:235], v[70:73]
	v_mfma_f32_16x16x32_bf16 v[66:69], v[190:193], v[232:235], v[66:69]
	s_setprio 0
	s_barrier
	ds_read_b128 v[194:197], v143 offset:49152
	ds_read_b128 v[208:211], v143 offset:50176
	ds_read_b128 v[212:215], v143 offset:51200
	ds_read_b128 v[216:219], v143 offset:52224
	ds_read_b128 v[220:223], v143 offset:53248
	ds_read_b128 v[224:227], v143 offset:54272
	ds_read_b128 v[228:231], v143 offset:55296
	ds_read_b128 v[232:235], v143 offset:56320
	s_add_i32 s18, s42, s22
	s_add_u32 s46, s16, 0x80
	s_addc_u32 s47, s17, 0
	s_mov_b32 m0, s18
	s_nop 0
	global_load_lds_dwordx4 v64, s[46:47]
	s_add_i32 m0, s18, 0x2000
	s_add_u32 s16, s16, 0x80080
	s_addc_u32 s17, s17, 0
	s_add_i32 s18, s43, s22
	global_load_lds_dwordx4 v130, s[46:47]
	s_mov_b32 m0, s18
	s_nop 0
	global_load_lds_dwordx4 v64, s[16:17]
	s_add_i32 m0, s18, 0x2000
	s_nop 0
	global_load_lds_dwordx4 v130, s[16:17]
	s_add_u32 s100, s100, 0x80
	s_addc_u32 s101, s101, 0
	s_mov_b32 m0, s34
	s_nop 0
	global_load_lds_dwordx4 v134, s[100:101]
	s_mov_b32 m0, s35
	s_nop 0
	global_load_lds_dwordx4 v132, s[100:101]
	s_waitcnt vmcnt(8)
	s_waitcnt lgkmcnt(0)
	s_barrier
	s_setprio 1
	s_waitcnt lgkmcnt(0)
	v_mfma_f32_16x16x32_bf16 v[60:63], v[144:147], v[194:197], v[60:63]
	v_mfma_f32_16x16x32_bf16 v[56:59], v[152:155], v[194:197], v[56:59]
	v_mfma_f32_16x16x32_bf16 v[52:55], v[144:147], v[212:215], v[52:55]
	v_mfma_f32_16x16x32_bf16 v[48:51], v[152:155], v[212:215], v[48:51]
	v_mfma_f32_16x16x32_bf16 v[36:39], v[144:147], v[220:223], v[36:39]
	v_mfma_f32_16x16x32_bf16 v[32:35], v[152:155], v[220:223], v[32:35]
	v_mfma_f32_16x16x32_bf16 v[20:23], v[144:147], v[228:231], v[20:23]
	v_mfma_f32_16x16x32_bf16 v[16:19], v[152:155], v[228:231], v[16:19]
	v_mfma_f32_16x16x32_bf16 v[60:63], v[148:151], v[208:211], v[60:63]
	v_mfma_f32_16x16x32_bf16 v[56:59], v[156:159], v[208:211], v[56:59]
	v_mfma_f32_16x16x32_bf16 v[52:55], v[148:151], v[216:219], v[52:55]
	v_mfma_f32_16x16x32_bf16 v[48:51], v[156:159], v[216:219], v[48:51]
	v_mfma_f32_16x16x32_bf16 v[36:39], v[148:151], v[224:227], v[36:39]
	v_mfma_f32_16x16x32_bf16 v[32:35], v[156:159], v[224:227], v[32:35]
	v_mfma_f32_16x16x32_bf16 v[20:23], v[148:151], v[232:235], v[20:23]
	v_mfma_f32_16x16x32_bf16 v[16:19], v[156:159], v[232:235], v[16:19]
	s_setprio 0
	s_setprio 1
	v_mfma_f32_16x16x32_bf16 v[44:47], v[178:181], v[194:197], v[44:47]
	v_mfma_f32_16x16x32_bf16 v[40:43], v[186:189], v[194:197], v[40:43]
	v_mfma_f32_16x16x32_bf16 v[28:31], v[178:181], v[212:215], v[28:31]
	v_mfma_f32_16x16x32_bf16 v[24:27], v[186:189], v[212:215], v[24:27]
	v_mfma_f32_16x16x32_bf16 v[12:15], v[178:181], v[220:223], v[12:15]
	v_mfma_f32_16x16x32_bf16 v[8:11], v[186:189], v[220:223], v[8:11]
	v_mfma_f32_16x16x32_bf16 v[4:7], v[178:181], v[228:231], v[4:7]
	v_mfma_f32_16x16x32_bf16 v[0:3], v[186:189], v[228:231], v[0:3]
	v_mfma_f32_16x16x32_bf16 v[44:47], v[182:185], v[208:211], v[44:47]
	v_mfma_f32_16x16x32_bf16 v[40:43], v[190:193], v[208:211], v[40:43]
	v_mfma_f32_16x16x32_bf16 v[28:31], v[182:185], v[216:219], v[28:31]
	v_mfma_f32_16x16x32_bf16 v[24:27], v[190:193], v[216:219], v[24:27]
	v_mfma_f32_16x16x32_bf16 v[12:15], v[182:185], v[224:227], v[12:15]
	v_mfma_f32_16x16x32_bf16 v[8:11], v[190:193], v[224:227], v[8:11]
	v_mfma_f32_16x16x32_bf16 v[4:7], v[182:185], v[232:235], v[4:7]
	v_mfma_f32_16x16x32_bf16 v[0:3], v[190:193], v[232:235], v[0:3]
	s_setprio 0
	s_barrier
	s_add_i32 s41, s41, 2
	s_add_u32 s0, s0, 0x100
	s_addc_u32 s1, s1, 0
	s_add_u32 s15, s15, 0x100
	s_addc_u32 s27, s27, 0
	s_cmp_gt_u32 s41, 13
	s_cbranch_scc0 .LBB0_1360
	s_mov_b64 s[46:47], 0x80
	s_and_b64 vcc, exec, s[8:9]
	s_cbranch_vccz .LBB0_1363
	s_barrier

; #define PG8_STAGE(bufoff, gbase, voff) do { _Pragma("unroll") for (int _i = 0; _i < 2; ++_i) \
;         __builtin_amdgcn_global_load_lds((const unsigned*)((const char*)(gbase) + (voff)[_i]), (PG8_LAS unsigned*)(lds + (bufoff) + ldsw + _i * 8192), 16, 0, 0); } while (0)
; #define PG8_LDA(dst, b, h) do { _Pragma("unroll") for (int m = 0; m < 4; ++m) _Pragma("unroll") for (int k = 0; k < 2; ++k) dst[m][k] = *(const PG8_LAS bf16x8*)(lds + PG8_SA(b, h) + aoff + m * 2048 + k * 1024); } while (0)
; #define PG8_LDB(dst, b, h) do { _Pragma("unroll") for (int n = 0; n < 2; ++n) _Pragma("unroll") for (int k = 0; k < 2; ++k) dst[n][k] = *(const PG8_LAS bf16x8*)(lds + PG8_SB(b, h) + boff + n * 2048 + k * 1024); } while (0)
; #define PG8_MMA(ai, bj, At, Bt) do { __builtin_amdgcn_s_setprio(1); _Pragma("unroll") for (int m = 0; m < 4; ++m) _Pragma("unroll") for (int n = 0; n < 2; ++n) _Pragma("unroll") for (int k = 0; k < 2; ++k) \
;         acc[ai][bj][m][n] = __builtin_amdgcn_mfma_f32_16x16x32_bf16(Bt[n][k], At[m][k], acc[ai][bj][m][n], 0, 0, 0); __builtin_amdgcn_s_setprio(0); } while (0)
; #define PG8_WAIT_V(n) asm volatile("s_waitcnt vmcnt(" #n ")" ::: "memory")
; #define PG8_BAR __builtin_amdgcn_s_barrier()
; template <class Epi, class Sched, bool ALIGN_EPI = false, bool SP2 = false>
; __device__ __forceinline__ void gemm_phase(PG8_LAS unsigned char* lds, const Gemm g, const Sched& S, const Epi& E, const int wave0) {
;     ...
;         for (int t = 0; t < nt; t += 2) {
;             const bool last = (t == nt - 2);
;             const char* a1 = cA + (size_t)(t + 1) * kstep;
;             const char* a2 = last ? nA : cA + (size_t)(t + 2) * kstep; const char* b2 = last ? nB : cB + (size_t)(t + 2) * kstep;
;             const char* a3 = a2 + kstep; const char* b3 = b2 + kstep;
;             if (last && has_next) S.a_ready(nxt);
;             if constexpr (SP2) {
;             PG8_LDB(B0, 0, 0); PG8_LDB(B1, 0, 1); PG8_SCHED; PG8_LDA(At, 0, 0); PG8_STAGE(PG8_SA(1, 1), a1 + hstepA, voffA);
;             PG8_WAIT_V(8); PG8_WAIT_L(0); PG8_BAR; PG8_MMA(0, 0, At, B0); PG8_MMA(0, 1, At, B1); PG8_BAR; PG8_SCHED;
;             PG8_LDA(At, 0, 1); PG8_STAGE(PG8_SB(0, 0), b2, voffB); PG8_STAGE(PG8_SB(0, 1), b2 + hstepB, voffB); PG8_STAGE(PG8_SA(0, 0), a2, voffA);
;             PG8_WAIT_V(8); PG8_WAIT_L(0); PG8_BAR; PG8_MMA(1, 0, At, B0); PG8_MMA(1, 1, At, B1); PG8_BAR; PG8_SCHED;
.LBB0_1571:
	ds_read_b128 v[140:143], v252
	ds_read_b128 v[148:151], v252 offset:1024
	ds_read_b128 v[152:155], v252 offset:2048
	ds_read_b128 v[156:159], v252 offset:3072
	ds_read_b128 v[178:181], v253
	ds_read_b128 v[182:185], v253 offset:1024
	ds_read_b128 v[186:189], v253 offset:2048
	ds_read_b128 v[190:193], v253 offset:3072
	ds_read_b128 v[194:197], v147
	ds_read_b128 v[208:211], v147 offset:1024
	ds_read_b128 v[212:215], v147 offset:2048
	ds_read_b128 v[216:219], v147 offset:3072
	ds_read_b128 v[220:223], v147 offset:4096
	ds_read_b128 v[224:227], v147 offset:5120
	ds_read_b128 v[228:231], v147 offset:6144
	ds_read_b128 v[232:235], v147 offset:7168
	s_add_u32 s16, s0, 0xfff80080
	s_addc_u32 s17, s1, -1
	s_add_i32 s46, 0, 0x10000
	s_cmp_eq_u32 s45, 28
	s_cselect_b32 s19, s9, s17
	s_cselect_b32 s18, s33, s16
	s_cselect_b32 s17, s7, s44
	s_cselect_b32 s16, s36, s37
	s_add_i32 s48, 0, 0x14000
	s_add_i32 m0, s15, 0xc000
	s_nop 0
	global_load_lds_dwordx4 v136, s[0:1]
	s_add_i32 m0, s15, 0xe000
	s_nop 0
	global_load_lds_dwordx4 v138, s[0:1]
	s_waitcnt vmcnt(8)
	s_waitcnt lgkmcnt(0)
	s_barrier
	s_setprio 1
	s_waitcnt lgkmcnt(0)
	v_mfma_f32_16x16x32_bf16 v[126:129], v[140:143], v[194:197], v[126:129]
	v_mfma_f32_16x16x32_bf16 v[122:125], v[152:155], v[194:197], v[122:125]
	v_mfma_f32_16x16x32_bf16 v[110:113], v[140:143], v[212:215], v[110:113]
	v_mfma_f32_16x16x32_bf16 v[106:109], v[152:155], v[212:215], v[106:109]
	v_mfma_f32_16x16x32_bf16 v[94:97], v[140:143], v[220:223], v[94:97]
	v_mfma_f32_16x16x32_bf16 v[90:93], v[152:155], v[220:223], v[90:93]
	v_mfma_f32_16x16x32_bf16 v[78:81], v[140:143], v[228:231], v[78:81]
	v_mfma_f32_16x16x32_bf16 v[74:77], v[152:155], v[228:231], v[74:77]
	v_mfma_f32_16x16x32_bf16 v[126:129], v[148:151], v[208:211], v[126:129]
	v_mfma_f32_16x16x32_bf16 v[122:125], v[156:159], v[208:211], v[122:125]
	v_mfma_f32_16x16x32_bf16 v[110:113], v[148:151], v[216:219], v[110:113]
	v_mfma_f32_16x16x32_bf16 v[106:109], v[156:159], v[216:219], v[106:109]
	v_mfma_f32_16x16x32_bf16 v[94:97], v[148:151], v[224:227], v[94:97]
	v_mfma_f32_16x16x32_bf16 v[90:93], v[156:159], v[224:227], v[90:93]
	v_mfma_f32_16x16x32_bf16 v[78:81], v[148:151], v[232:235], v[78:81]
	v_mfma_f32_16x16x32_bf16 v[74:77], v[156:159], v[232:235], v[74:77]
	s_setprio 0
	s_setprio 1
	v_mfma_f32_16x16x32_bf16 v[118:121], v[178:181], v[194:197], v[118:121]
	v_mfma_f32_16x16x32_bf16 v[114:117], v[186:189], v[194:197], v[114:117]
	v_mfma_f32_16x16x32_bf16 v[102:105], v[178:181], v[212:215], v[102:105]
	v_mfma_f32_16x16x32_bf16 v[98:101], v[186:189], v[212:215], v[98:101]
	v_mfma_f32_16x16x32_bf16 v[86:89], v[178:181], v[220:223], v[86:89]
	v_mfma_f32_16x16x32_bf16 v[82:85], v[186:189], v[220:223], v[82:85]
	v_mfma_f32_16x16x32_bf16 v[70:73], v[178:181], v[228:231], v[70:73]
	v_mfma_f32_16x16x32_bf16 v[66:69], v[186:189], v[228:231], v[66:69]
	v_mfma_f32_16x16x32_bf16 v[118:121], v[182:185], v[208:211], v[118:121]
	v_mfma_f32_16x16x32_bf16 v[114:117], v[190:193], v[208:211], v[114:117]
	v_mfma_f32_16x16x32_bf16 v[102:105], v[182:185], v[216:219], v[102:105]
	v_mfma_f32_16x16x32_bf16 v[98:101], v[190:193], v[216:219], v[98:101]
	v_mfma_f32_16x16x32_bf16 v[86:89], v[182:185], v[224:227], v[86:89]
	v_mfma_f32_16x16x32_bf16 v[82:85], v[190:193], v[224:227], v[82:85]
	v_mfma_f32_16x16x32_bf16 v[70:73], v[182:185], v[232:235], v[70:73]
	v_mfma_f32_16x16x32_bf16 v[66:69], v[190:193], v[232:235], v[66:69]
	s_setprio 0
	s_barrier
	ds_read_b128 v[194:197], v147 offset:16384
	ds_read_b128 v[208:211], v147 offset:17408
	ds_read_b128 v[212:215], v147 offset:18432
	ds_read_b128 v[216:219], v147 offset:19456
	ds_read_b128 v[220:223], v147 offset:20480
	ds_read_b128 v[224:227], v147 offset:21504
	ds_read_b128 v[228:231], v147 offset:22528
	ds_read_b128 v[232:235], v147 offset:23552
	s_add_i32 s46, s46, s28
	s_mov_b32 m0, s46
	s_nop 0
	global_load_lds_dwordx4 v64, s[16:17]
	s_add_i32 m0, s46, 0x2000
	s_add_u32 s46, s16, 0x80000
	s_addc_u32 s47, s17, 0
	s_add_i32 s48, s48, s28
	global_load_lds_dwordx4 v130, s[16:17]
	s_mov_b32 m0, s48
	s_mov_b64 s[100:101], s[18:19]
	global_load_lds_dwordx4 v64, s[46:47]
	s_add_i32 m0, s48, 0x2000
	s_nop 0
	global_load_lds_dwordx4 v130, s[46:47]
	s_mov_b32 m0, s15
	s_nop 0
	global_load_lds_dwordx4 v134, s[18:19]
	s_mov_b32 m0, s27
	s_nop 0
	global_load_lds_dwordx4 v132, s[18:19]
	s_waitcnt vmcnt(8)
	s_waitcnt lgkmcnt(0)
	s_barrier
	s_setprio 1
	s_waitcnt lgkmcnt(0)
	v_mfma_f32_16x16x32_bf16 v[60:63], v[140:143], v[194:197], v[60:63]
	v_mfma_f32_16x16x32_bf16 v[56:59], v[152:155], v[194:197], v[56:59]
	v_mfma_f32_16x16x32_bf16 v[44:47], v[140:143], v[212:215], v[44:47]
	v_mfma_f32_16x16x32_bf16 v[40:43], v[152:155], v[212:215], v[40:43]
	v_mfma_f32_16x16x32_bf16 v[28:31], v[140:143], v[220:223], v[28:31]
	v_mfma_f32_16x16x32_bf16 v[24:27], v[152:155], v[220:223], v[24:27]
	v_mfma_f32_16x16x32_bf16 v[12:15], v[140:143], v[228:231], v[12:15]
	v_mfma_f32_16x16x32_bf16 v[8:11], v[152:155], v[228:231], v[8:11]
	v_mfma_f32_16x16x32_bf16 v[60:63], v[148:151], v[208:211], v[60:63]
	v_mfma_f32_16x16x32_bf16 v[56:59], v[156:159], v[208:211], v[56:59]
	v_mfma_f32_16x16x32_bf16 v[44:47], v[148:151], v[216:219], v[44:47]
	v_mfma_f32_16x16x32_bf16 v[40:43], v[156:159], v[216:219], v[40:43]
	v_mfma_f32_16x16x32_bf16 v[28:31], v[148:151], v[224:227], v[28:31]
	v_mfma_f32_16x16x32_bf16 v[24:27], v[156:159], v[224:227], v[24:27]
	v_mfma_f32_16x16x32_bf16 v[12:15], v[148:151], v[232:235], v[12:15]
	v_mfma_f32_16x16x32_bf16 v[8:11], v[156:159], v[232:235], v[8:11]
	s_setprio 0
	s_setprio 1
	v_mfma_f32_16x16x32_bf16 v[52:55], v[178:181], v[194:197], v[52:55]
	v_mfma_f32_16x16x32_bf16 v[48:51], v[186:189], v[194:197], v[48:51]
	v_mfma_f32_16x16x32_bf16 v[36:39], v[178:181], v[212:215], v[36:39]
	v_mfma_f32_16x16x32_bf16 v[32:35], v[186:189], v[212:215], v[32:35]
	v_mfma_f32_16x16x32_bf16 v[20:23], v[178:181], v[220:223], v[20:23]
	v_mfma_f32_16x16x32_bf16 v[16:19], v[186:189], v[220:223], v[16:19]
	v_mfma_f32_16x16x32_bf16 v[4:7], v[178:181], v[228:231], v[4:7]
	v_mfma_f32_16x16x32_bf16 v[0:3], v[186:189], v[228:231], v[0:3]
	v_mfma_f32_16x16x32_bf16 v[52:55], v[182:185], v[208:211], v[52:55]
	v_mfma_f32_16x16x32_bf16 v[48:51], v[190:193], v[208:211], v[48:51]
	v_mfma_f32_16x16x32_bf16 v[36:39], v[182:185], v[216:219], v[36:39]
	v_mfma_f32_16x16x32_bf16 v[32:35], v[190:193], v[216:219], v[32:35]
	v_mfma_f32_16x16x32_bf16 v[20:23], v[182:185], v[224:227], v[20:23]
	v_mfma_f32_16x16x32_bf16 v[16:19], v[190:193], v[224:227], v[16:19]
	v_mfma_f32_16x16x32_bf16 v[4:7], v[182:185], v[232:235], v[4:7]
	v_mfma_f32_16x16x32_bf16 v[0:3], v[190:193], v[232:235], v[0:3]
	s_setprio 0
	s_barrier
; #define PG8_STAGE(bufoff, gbase, voff) do { _Pragma("unroll") for (int _i = 0; _i < 2; ++_i) \
;         __builtin_amdgcn_global_load_lds((const unsigned*)((const char*)(gbase) + (voff)[_i]), (PG8_LAS unsigned*)(lds + (bufoff) + ldsw + _i * 8192), 16, 0, 0); } while (0)
; #define PG8_LDA(dst, b, h) do { _Pragma("unroll") for (int m = 0; m < 4; ++m) _Pragma("unroll") for (int k = 0; k < 2; ++k) dst[m][k] = *(const PG8_LAS bf16x8*)(lds + PG8_SA(b, h) + aoff + m * 2048 + k * 1024); } while (0)
; #define PG8_LDB(dst, b, h) do { _Pragma("unroll") for (int n = 0; n < 2; ++n) _Pragma("unroll") for (int k = 0; k < 2; ++k) dst[n][k] = *(const PG8_LAS bf16x8*)(lds + PG8_SB(b, h) + boff + n * 2048 + k * 1024); } while (0)
; #define PG8_MMA(ai, bj, At, Bt) do { __builtin_amdgcn_s_setprio(1); _Pragma("unroll") for (int m = 0; m < 4; ++m) _Pragma("unroll") for (int n = 0; n < 2; ++n) _Pragma("unroll") for (int k = 0; k < 2; ++k) \
;         acc[ai][bj][m][n] = __builtin_amdgcn_mfma_f32_16x16x32_bf16(Bt[n][k], At[m][k], acc[ai][bj][m][n], 0, 0, 0); __builtin_amdgcn_s_setprio(0); } while (0)
; #define PG8_WAIT_V(n) asm volatile("s_waitcnt vmcnt(" #n ")" ::: "memory")
; #define PG8_WAIT_L(n) asm volatile("s_waitcnt lgkmcnt(" #n ")" ::: "memory")
; #define PG8_BAR __builtin_amdgcn_s_barrier()
; #define PG8_SCHED __builtin_amdgcn_sched_barrier(0)
; template <class Epi, class Sched, bool ALIGN_EPI = false, bool SP2 = false>
; __device__ __forceinline__ void gemm_phase(PG8_LAS unsigned char* lds, const Gemm g, const Sched& S, const Epi& E, const int wave0) {
;     ...
;             PG8_LDB(B0, 1, 0); PG8_LDB(B1, 1, 1); PG8_SCHED; PG8_LDA(At, 1, 0); PG8_STAGE(PG8_SA(0, 1), a2 + hstepA, voffA);
;             PG8_WAIT_V(8); PG8_WAIT_L(0); PG8_BAR; PG8_MMA(0, 0, At, B0); PG8_MMA(0, 1, At, B1); PG8_BAR; PG8_SCHED;
;             PG8_LDA(At, 1, 1); PG8_STAGE(PG8_SB(1, 0), b3, voffB); PG8_STAGE(PG8_SB(1, 1), b3 + hstepB, voffB); PG8_STAGE(PG8_SA(1, 0), a3, voffA);
;             PG8_WAIT_V(8); PG8_WAIT_L(0); PG8_BAR; PG8_MMA(1, 0, At, B0); PG8_MMA(1, 1, At, B1); PG8_BAR; PG8_SCHED;
	ds_read_b128 v[140:143], v254
	ds_read_b128 v[148:151], v254 offset:1024
	ds_read_b128 v[152:155], v254 offset:2048
	ds_read_b128 v[156:159], v254 offset:3072
	ds_read_b128 v[178:181], v255
	ds_read_b128 v[182:185], v255 offset:1024
	ds_read_b128 v[186:189], v255 offset:2048
	ds_read_b128 v[190:193], v255 offset:3072
	ds_read_b128 v[194:197], v147 offset:32768
	ds_read_b128 v[208:211], v147 offset:33792
	ds_read_b128 v[212:215], v147 offset:34816
	ds_read_b128 v[216:219], v147 offset:35840
	ds_read_b128 v[220:223], v147 offset:36864
	ds_read_b128 v[224:227], v147 offset:37888
	ds_read_b128 v[228:231], v147 offset:38912
	ds_read_b128 v[232:235], v147 offset:39936
	s_add_i32 s46, 0, 0x18000
	s_add_i32 s47, 0, 0x1c000
	s_add_u32 s18, s18, 0x80000
	s_addc_u32 s19, s19, 0
	s_mov_b32 m0, s29
	s_nop 0
	global_load_lds_dwordx4 v134, s[18:19]
	s_mov_b32 m0, s30
	s_nop 0
	global_load_lds_dwordx4 v132, s[18:19]
	s_waitcnt vmcnt(8)
	s_waitcnt lgkmcnt(0)
	s_barrier
	s_setprio 1
	s_waitcnt lgkmcnt(0)
	v_mfma_f32_16x16x32_bf16 v[126:129], v[140:143], v[194:197], v[126:129]
	v_mfma_f32_16x16x32_bf16 v[122:125], v[152:155], v[194:197], v[122:125]
	v_mfma_f32_16x16x32_bf16 v[110:113], v[140:143], v[212:215], v[110:113]
	v_mfma_f32_16x16x32_bf16 v[106:109], v[152:155], v[212:215], v[106:109]
	v_mfma_f32_16x16x32_bf16 v[94:97], v[140:143], v[220:223], v[94:97]
	v_mfma_f32_16x16x32_bf16 v[90:93], v[152:155], v[220:223], v[90:93]
	v_mfma_f32_16x16x32_bf16 v[78:81], v[140:143], v[228:231], v[78:81]
	v_mfma_f32_16x16x32_bf16 v[74:77], v[152:155], v[228:231], v[74:77]
	v_mfma_f32_16x16x32_bf16 v[126:129], v[148:151], v[208:211], v[126:129]
	v_mfma_f32_16x16x32_bf16 v[122:125], v[156:159], v[208:211], v[122:125]
	v_mfma_f32_16x16x32_bf16 v[110:113], v[148:151], v[216:219], v[110:113]
	v_mfma_f32_16x16x32_bf16 v[106:109], v[156:159], v[216:219], v[106:109]
	v_mfma_f32_16x16x32_bf16 v[94:97], v[148:151], v[224:227], v[94:97]
	v_mfma_f32_16x16x32_bf16 v[90:93], v[156:159], v[224:227], v[90:93]
	v_mfma_f32_16x16x32_bf16 v[78:81], v[148:151], v[232:235], v[78:81]
	v_mfma_f32_16x16x32_bf16 v[74:77], v[156:159], v[232:235], v[74:77]
	s_setprio 0
	s_setprio 1
	v_mfma_f32_16x16x32_bf16 v[118:121], v[178:181], v[194:197], v[118:121]
	v_mfma_f32_16x16x32_bf16 v[114:117], v[186:189], v[194:197], v[114:117]
	v_mfma_f32_16x16x32_bf16 v[102:105], v[178:181], v[212:215], v[102:105]
	v_mfma_f32_16x16x32_bf16 v[98:101], v[186:189], v[212:215], v[98:101]
	v_mfma_f32_16x16x32_bf16 v[86:89], v[178:181], v[220:223], v[86:89]
	v_mfma_f32_16x16x32_bf16 v[82:85], v[186:189], v[220:223], v[82:85]
	v_mfma_f32_16x16x32_bf16 v[70:73], v[178:181], v[228:231], v[70:73]
	v_mfma_f32_16x16x32_bf16 v[66:69], v[186:189], v[228:231], v[66:69]
	v_mfma_f32_16x16x32_bf16 v[118:121], v[182:185], v[208:211], v[118:121]
	v_mfma_f32_16x16x32_bf16 v[114:117], v[190:193], v[208:211], v[114:117]
	v_mfma_f32_16x16x32_bf16 v[102:105], v[182:185], v[216:219], v[102:105]
	v_mfma_f32_16x16x32_bf16 v[98:101], v[190:193], v[216:219], v[98:101]
	v_mfma_f32_16x16x32_bf16 v[86:89], v[182:185], v[224:227], v[86:89]
	v_mfma_f32_16x16x32_bf16 v[82:85], v[190:193], v[224:227], v[82:85]
	v_mfma_f32_16x16x32_bf16 v[70:73], v[182:185], v[232:235], v[70:73]
	v_mfma_f32_16x16x32_bf16 v[66:69], v[190:193], v[232:235], v[66:69]
	s_setprio 0
	s_barrier
	ds_read_b128 v[194:197], v147 offset:49152
	ds_read_b128 v[208:211], v147 offset:50176
	ds_read_b128 v[212:215], v147 offset:51200
	ds_read_b128 v[216:219], v147 offset:52224
	ds_read_b128 v[220:223], v147 offset:53248
	ds_read_b128 v[224:227], v147 offset:54272
	ds_read_b128 v[228:231], v147 offset:55296
	ds_read_b128 v[232:235], v147 offset:56320
	s_add_i32 s18, s46, s28
	s_add_u32 s50, s16, 0x80
	s_addc_u32 s51, s17, 0
	s_mov_b32 m0, s18
	s_nop 0
	global_load_lds_dwordx4 v64, s[50:51]
	s_add_i32 m0, s18, 0x2000
	s_add_u32 s16, s16, 0x80080
	s_addc_u32 s17, s17, 0
	s_add_i32 s18, s47, s28
	global_load_lds_dwordx4 v130, s[50:51]
	s_mov_b32 m0, s18
	s_nop 0
	global_load_lds_dwordx4 v64, s[16:17]
	s_add_i32 m0, s18, 0x2000
	s_nop 0
	global_load_lds_dwordx4 v130, s[16:17]
	s_add_u32 s100, s100, 0x80
	s_addc_u32 s101, s101, 0
	s_mov_b32 m0, s31
	s_nop 0
	global_load_lds_dwordx4 v134, s[100:101]
	s_mov_b32 m0, s34
	s_nop 0
	global_load_lds_dwordx4 v132, s[100:101]
	s_waitcnt vmcnt(8)
	s_waitcnt lgkmcnt(0)
	s_barrier
	s_setprio 1
	s_waitcnt lgkmcnt(0)
	v_mfma_f32_16x16x32_bf16 v[60:63], v[140:143], v[194:197], v[60:63]
	v_mfma_f32_16x16x32_bf16 v[56:59], v[152:155], v[194:197], v[56:59]
	v_mfma_f32_16x16x32_bf16 v[44:47], v[140:143], v[212:215], v[44:47]
	v_mfma_f32_16x16x32_bf16 v[40:43], v[152:155], v[212:215], v[40:43]
	v_mfma_f32_16x16x32_bf16 v[28:31], v[140:143], v[220:223], v[28:31]
	v_mfma_f32_16x16x32_bf16 v[24:27], v[152:155], v[220:223], v[24:27]
	v_mfma_f32_16x16x32_bf16 v[12:15], v[140:143], v[228:231], v[12:15]
	v_mfma_f32_16x16x32_bf16 v[8:11], v[152:155], v[228:231], v[8:11]
	v_mfma_f32_16x16x32_bf16 v[60:63], v[148:151], v[208:211], v[60:63]
	v_mfma_f32_16x16x32_bf16 v[56:59], v[156:159], v[208:211], v[56:59]
	v_mfma_f32_16x16x32_bf16 v[44:47], v[148:151], v[216:219], v[44:47]
	v_mfma_f32_16x16x32_bf16 v[40:43], v[156:159], v[216:219], v[40:43]
	v_mfma_f32_16x16x32_bf16 v[28:31], v[148:151], v[224:227], v[28:31]
	v_mfma_f32_16x16x32_bf16 v[24:27], v[156:159], v[224:227], v[24:27]
	v_mfma_f32_16x16x32_bf16 v[12:15], v[148:151], v[232:235], v[12:15]
	v_mfma_f32_16x16x32_bf16 v[8:11], v[156:159], v[232:235], v[8:11]
	s_setprio 0
	s_setprio 1
	v_mfma_f32_16x16x32_bf16 v[52:55], v[178:181], v[194:197], v[52:55]
	v_mfma_f32_16x16x32_bf16 v[48:51], v[186:189], v[194:197], v[48:51]
	v_mfma_f32_16x16x32_bf16 v[36:39], v[178:181], v[212:215], v[36:39]
	v_mfma_f32_16x16x32_bf16 v[32:35], v[186:189], v[212:215], v[32:35]
	v_mfma_f32_16x16x32_bf16 v[20:23], v[178:181], v[220:223], v[20:23]
	v_mfma_f32_16x16x32_bf16 v[16:19], v[186:189], v[220:223], v[16:19]
	v_mfma_f32_16x16x32_bf16 v[4:7], v[178:181], v[228:231], v[4:7]
	v_mfma_f32_16x16x32_bf16 v[0:3], v[186:189], v[228:231], v[0:3]
	v_mfma_f32_16x16x32_bf16 v[52:55], v[182:185], v[208:211], v[52:55]
	v_mfma_f32_16x16x32_bf16 v[48:51], v[190:193], v[208:211], v[48:51]
	v_mfma_f32_16x16x32_bf16 v[36:39], v[182:185], v[216:219], v[36:39]
	v_mfma_f32_16x16x32_bf16 v[32:35], v[190:193], v[216:219], v[32:35]
	v_mfma_f32_16x16x32_bf16 v[20:23], v[182:185], v[224:227], v[20:23]
	v_mfma_f32_16x16x32_bf16 v[16:19], v[190:193], v[224:227], v[16:19]
	v_mfma_f32_16x16x32_bf16 v[4:7], v[182:185], v[232:235], v[4:7]
	v_mfma_f32_16x16x32_bf16 v[0:3], v[190:193], v[232:235], v[0:3]
	s_setprio 0
	s_barrier
	s_add_i32 s45, s45, 2
	s_add_u32 s0, s0, 0x100
	s_addc_u32 s1, s1, 0
	s_add_u32 s37, s37, 0x100
	s_addc_u32 s44, s44, 0
	s_cmp_gt_u32 s45, 29
	s_cbranch_scc0 .LBB0_1571
	s_mov_b64 s[50:51], 0x80
	s_and_b64 vcc, exec, s[4:5]
	s_cbranch_vccz .LBB0_1574
	s_barrier

; #define PG8_STAGE(bufoff, gbase, voff) do { _Pragma("unroll") for (int _i = 0; _i < 2; ++_i) \
;         __builtin_amdgcn_global_load_lds((const unsigned*)((const char*)(gbase) + (voff)[_i]), (PG8_LAS unsigned*)(lds + (bufoff) + ldsw + _i * 8192), 16, 0, 0); } while (0)
; #define PG8_LDA(dst, b, h) do { _Pragma("unroll") for (int m = 0; m < 4; ++m) _Pragma("unroll") for (int k = 0; k < 2; ++k) dst[m][k] = *(const PG8_LAS bf16x8*)(lds + PG8_SA(b, h) + aoff + m * 2048 + k * 1024); } while (0)
; #define PG8_LDB(dst, b, h) do { _Pragma("unroll") for (int n = 0; n < 2; ++n) _Pragma("unroll") for (int k = 0; k < 2; ++k) dst[n][k] = *(const PG8_LAS bf16x8*)(lds + PG8_SB(b, h) + boff + n * 2048 + k * 1024); } while (0)
; #define PG8_MMA(ai, bj, At, Bt) do { __builtin_amdgcn_s_setprio(1); _Pragma("unroll") for (int m = 0; m < 4; ++m) _Pragma("unroll") for (int n = 0; n < 2; ++n) _Pragma("unroll") for (int k = 0; k < 2; ++k) \
;         acc[ai][bj][m][n] = __builtin_amdgcn_mfma_f32_16x16x32_bf16(Bt[n][k], At[m][k], acc[ai][bj][m][n], 0, 0, 0); __builtin_amdgcn_s_setprio(0); } while (0)
; #define PG8_WAIT_V(n) asm volatile("s_waitcnt vmcnt(" #n ")" ::: "memory")
; #define PG8_BAR __builtin_amdgcn_s_barrier()
; template <class Epi, class Sched, bool ALIGN_EPI = false, bool SP2 = false>
; __device__ __forceinline__ void gemm_phase(PG8_LAS unsigned char* lds, const Gemm g, const Sched& S, const Epi& E, const int wave0) {
;     ...
;         for (int t = 0; t < nt; t += 2) {
;             const bool last = (t == nt - 2);
;             const char* a1 = cA + (size_t)(t + 1) * kstep;
;             const char* a2 = last ? nA : cA + (size_t)(t + 2) * kstep; const char* b2 = last ? nB : cB + (size_t)(t + 2) * kstep;
;             const char* a3 = a2 + kstep; const char* b3 = b2 + kstep;
;             if (last && has_next) S.a_ready(nxt);
;             if constexpr (SP2) {
;             PG8_LDB(B0, 0, 0); PG8_LDB(B1, 0, 1); PG8_SCHED; PG8_LDA(At, 0, 0); PG8_STAGE(PG8_SA(1, 1), a1 + hstepA, voffA);
;             PG8_WAIT_V(8); PG8_WAIT_L(0); PG8_BAR; PG8_MMA(0, 0, At, B0); PG8_MMA(0, 1, At, B1); PG8_BAR; PG8_SCHED;
;             PG8_LDA(At, 0, 1); PG8_STAGE(PG8_SB(0, 0), b2, voffB); PG8_STAGE(PG8_SB(0, 1), b2 + hstepB, voffB); PG8_STAGE(PG8_SA(0, 0), a2, voffA);
;             PG8_WAIT_V(8); PG8_WAIT_L(0); PG8_BAR; PG8_MMA(1, 0, At, B0); PG8_MMA(1, 1, At, B1); PG8_BAR; PG8_SCHED;
.LBB0_1685:
	ds_read_b128 v[144:147], v252
	ds_read_b128 v[148:151], v252 offset:1024
	ds_read_b128 v[152:155], v252 offset:2048
	ds_read_b128 v[156:159], v252 offset:3072
	ds_read_b128 v[178:181], v253
	ds_read_b128 v[182:185], v253 offset:1024
	ds_read_b128 v[186:189], v253 offset:2048
	ds_read_b128 v[190:193], v253 offset:3072
	ds_read_b128 v[194:197], v143
	ds_read_b128 v[208:211], v143 offset:1024
	ds_read_b128 v[212:215], v143 offset:2048
	ds_read_b128 v[216:219], v143 offset:3072
	ds_read_b128 v[220:223], v143 offset:4096
	ds_read_b128 v[224:227], v143 offset:5120
	ds_read_b128 v[228:231], v143 offset:6144
	ds_read_b128 v[232:235], v143 offset:7168
	s_add_u32 s16, s0, 0xffe00080
	s_addc_u32 s17, s1, -1
	s_add_i32 s43, 0, 0x10000
	s_cmpk_eq_i32 s42, 0x7c
	s_cselect_b32 s19, s11, s17
	s_cselect_b32 s18, s34, s16
	s_cselect_b32 s17, s9, s37
	s_cselect_b32 s16, s35, s36
	s_add_i32 s46, 0, 0x14000
	s_add_i32 m0, s21, 0xc000
	s_nop 0
	global_load_lds_dwordx4 v136, s[0:1]
	s_add_i32 m0, s21, 0xe000
	s_nop 0
	global_load_lds_dwordx4 v138, s[0:1]
	s_waitcnt vmcnt(8)
	s_waitcnt lgkmcnt(0)
	s_barrier
	s_setprio 1
	s_waitcnt lgkmcnt(0)
	v_mfma_f32_16x16x32_bf16 v[126:129], v[144:147], v[194:197], v[126:129]
	v_mfma_f32_16x16x32_bf16 v[122:125], v[152:155], v[194:197], v[122:125]
	v_mfma_f32_16x16x32_bf16 v[118:121], v[144:147], v[212:215], v[118:121]
	v_mfma_f32_16x16x32_bf16 v[114:117], v[152:155], v[212:215], v[114:117]
	v_mfma_f32_16x16x32_bf16 v[102:105], v[144:147], v[220:223], v[102:105]
	v_mfma_f32_16x16x32_bf16 v[98:101], v[152:155], v[220:223], v[98:101]
	v_mfma_f32_16x16x32_bf16 v[86:89], v[144:147], v[228:231], v[86:89]
	v_mfma_f32_16x16x32_bf16 v[82:85], v[152:155], v[228:231], v[82:85]
	v_mfma_f32_16x16x32_bf16 v[126:129], v[148:151], v[208:211], v[126:129]
	v_mfma_f32_16x16x32_bf16 v[122:125], v[156:159], v[208:211], v[122:125]
	v_mfma_f32_16x16x32_bf16 v[118:121], v[148:151], v[216:219], v[118:121]
	v_mfma_f32_16x16x32_bf16 v[114:117], v[156:159], v[216:219], v[114:117]
	v_mfma_f32_16x16x32_bf16 v[102:105], v[148:151], v[224:227], v[102:105]
	v_mfma_f32_16x16x32_bf16 v[98:101], v[156:159], v[224:227], v[98:101]
	v_mfma_f32_16x16x32_bf16 v[86:89], v[148:151], v[232:235], v[86:89]
	v_mfma_f32_16x16x32_bf16 v[82:85], v[156:159], v[232:235], v[82:85]
	s_setprio 0
	s_setprio 1
	v_mfma_f32_16x16x32_bf16 v[110:113], v[178:181], v[194:197], v[110:113]
	v_mfma_f32_16x16x32_bf16 v[106:109], v[186:189], v[194:197], v[106:109]
	v_mfma_f32_16x16x32_bf16 v[94:97], v[178:181], v[212:215], v[94:97]
	v_mfma_f32_16x16x32_bf16 v[90:93], v[186:189], v[212:215], v[90:93]
	v_mfma_f32_16x16x32_bf16 v[78:81], v[178:181], v[220:223], v[78:81]
	v_mfma_f32_16x16x32_bf16 v[74:77], v[186:189], v[220:223], v[74:77]
	v_mfma_f32_16x16x32_bf16 v[70:73], v[178:181], v[228:231], v[70:73]
	v_mfma_f32_16x16x32_bf16 v[66:69], v[186:189], v[228:231], v[66:69]
	v_mfma_f32_16x16x32_bf16 v[110:113], v[182:185], v[208:211], v[110:113]
	v_mfma_f32_16x16x32_bf16 v[106:109], v[190:193], v[208:211], v[106:109]
	v_mfma_f32_16x16x32_bf16 v[94:97], v[182:185], v[216:219], v[94:97]
	v_mfma_f32_16x16x32_bf16 v[90:93], v[190:193], v[216:219], v[90:93]
	v_mfma_f32_16x16x32_bf16 v[78:81], v[182:185], v[224:227], v[78:81]
	v_mfma_f32_16x16x32_bf16 v[74:77], v[190:193], v[224:227], v[74:77]
	v_mfma_f32_16x16x32_bf16 v[70:73], v[182:185], v[232:235], v[70:73]
	v_mfma_f32_16x16x32_bf16 v[66:69], v[190:193], v[232:235], v[66:69]
	s_setprio 0
	s_barrier
	ds_read_b128 v[194:197], v143 offset:16384
	ds_read_b128 v[208:211], v143 offset:17408
	ds_read_b128 v[212:215], v143 offset:18432
	ds_read_b128 v[216:219], v143 offset:19456
	ds_read_b128 v[220:223], v143 offset:20480
	ds_read_b128 v[224:227], v143 offset:21504
	ds_read_b128 v[228:231], v143 offset:22528
	ds_read_b128 v[232:235], v143 offset:23552
	s_add_i32 s43, s43, s20
	s_mov_b32 m0, s43
	s_nop 0
	global_load_lds_dwordx4 v64, s[16:17]
	s_add_i32 m0, s43, 0x2000
	s_add_u32 s44, s16, 0x200000
	s_addc_u32 s45, s17, 0
	s_add_i32 s43, s46, s20
	global_load_lds_dwordx4 v130, s[16:17]
	s_mov_b32 m0, s43
	s_mov_b64 s[100:101], s[18:19]
	global_load_lds_dwordx4 v64, s[44:45]
	s_add_i32 m0, s43, 0x2000
	s_nop 0
	global_load_lds_dwordx4 v130, s[44:45]
	s_mov_b32 m0, s21
	s_nop 0
	global_load_lds_dwordx4 v134, s[18:19]
	s_mov_b32 m0, s25
	s_nop 0
	global_load_lds_dwordx4 v132, s[18:19]
	s_waitcnt vmcnt(8)
	s_waitcnt lgkmcnt(0)
	s_barrier
	s_setprio 1
	s_waitcnt lgkmcnt(0)
	v_mfma_f32_16x16x32_bf16 v[60:63], v[144:147], v[194:197], v[60:63]
	v_mfma_f32_16x16x32_bf16 v[56:59], v[152:155], v[194:197], v[56:59]
	v_mfma_f32_16x16x32_bf16 v[52:55], v[144:147], v[212:215], v[52:55]
	v_mfma_f32_16x16x32_bf16 v[48:51], v[152:155], v[212:215], v[48:51]
	v_mfma_f32_16x16x32_bf16 v[36:39], v[144:147], v[220:223], v[36:39]
	v_mfma_f32_16x16x32_bf16 v[32:35], v[152:155], v[220:223], v[32:35]
	v_mfma_f32_16x16x32_bf16 v[20:23], v[144:147], v[228:231], v[20:23]
	v_mfma_f32_16x16x32_bf16 v[16:19], v[152:155], v[228:231], v[16:19]
	v_mfma_f32_16x16x32_bf16 v[60:63], v[148:151], v[208:211], v[60:63]
	v_mfma_f32_16x16x32_bf16 v[56:59], v[156:159], v[208:211], v[56:59]
	v_mfma_f32_16x16x32_bf16 v[52:55], v[148:151], v[216:219], v[52:55]
	v_mfma_f32_16x16x32_bf16 v[48:51], v[156:159], v[216:219], v[48:51]
	v_mfma_f32_16x16x32_bf16 v[36:39], v[148:151], v[224:227], v[36:39]
	v_mfma_f32_16x16x32_bf16 v[32:35], v[156:159], v[224:227], v[32:35]
	v_mfma_f32_16x16x32_bf16 v[20:23], v[148:151], v[232:235], v[20:23]
	v_mfma_f32_16x16x32_bf16 v[16:19], v[156:159], v[232:235], v[16:19]
	s_setprio 0
	s_setprio 1
	v_mfma_f32_16x16x32_bf16 v[44:47], v[178:181], v[194:197], v[44:47]
	v_mfma_f32_16x16x32_bf16 v[40:43], v[186:189], v[194:197], v[40:43]
	v_mfma_f32_16x16x32_bf16 v[28:31], v[178:181], v[212:215], v[28:31]
	v_mfma_f32_16x16x32_bf16 v[24:27], v[186:189], v[212:215], v[24:27]
	v_mfma_f32_16x16x32_bf16 v[12:15], v[178:181], v[220:223], v[12:15]
	v_mfma_f32_16x16x32_bf16 v[8:11], v[186:189], v[220:223], v[8:11]
	v_mfma_f32_16x16x32_bf16 v[4:7], v[178:181], v[228:231], v[4:7]
	v_mfma_f32_16x16x32_bf16 v[0:3], v[186:189], v[228:231], v[0:3]
	v_mfma_f32_16x16x32_bf16 v[44:47], v[182:185], v[208:211], v[44:47]
	v_mfma_f32_16x16x32_bf16 v[40:43], v[190:193], v[208:211], v[40:43]
	v_mfma_f32_16x16x32_bf16 v[28:31], v[182:185], v[216:219], v[28:31]
	v_mfma_f32_16x16x32_bf16 v[24:27], v[190:193], v[216:219], v[24:27]
	v_mfma_f32_16x16x32_bf16 v[12:15], v[182:185], v[224:227], v[12:15]
	v_mfma_f32_16x16x32_bf16 v[8:11], v[190:193], v[224:227], v[8:11]
	v_mfma_f32_16x16x32_bf16 v[4:7], v[182:185], v[232:235], v[4:7]
	v_mfma_f32_16x16x32_bf16 v[0:3], v[190:193], v[232:235], v[0:3]
	s_setprio 0
	s_barrier
; #define PG8_STAGE(bufoff, gbase, voff) do { _Pragma("unroll") for (int _i = 0; _i < 2; ++_i) \
;         __builtin_amdgcn_global_load_lds((const unsigned*)((const char*)(gbase) + (voff)[_i]), (PG8_LAS unsigned*)(lds + (bufoff) + ldsw + _i * 8192), 16, 0, 0); } while (0)
; #define PG8_LDA(dst, b, h) do { _Pragma("unroll") for (int m = 0; m < 4; ++m) _Pragma("unroll") for (int k = 0; k < 2; ++k) dst[m][k] = *(const PG8_LAS bf16x8*)(lds + PG8_SA(b, h) + aoff + m * 2048 + k * 1024); } while (0)
; #define PG8_LDB(dst, b, h) do { _Pragma("unroll") for (int n = 0; n < 2; ++n) _Pragma("unroll") for (int k = 0; k < 2; ++k) dst[n][k] = *(const PG8_LAS bf16x8*)(lds + PG8_SB(b, h) + boff + n * 2048 + k * 1024); } while (0)
; #define PG8_MMA(ai, bj, At, Bt) do { __builtin_amdgcn_s_setprio(1); _Pragma("unroll") for (int m = 0; m < 4; ++m) _Pragma("unroll") for (int n = 0; n < 2; ++n) _Pragma("unroll") for (int k = 0; k < 2; ++k) \
;         acc[ai][bj][m][n] = __builtin_amdgcn_mfma_f32_16x16x32_bf16(Bt[n][k], At[m][k], acc[ai][bj][m][n], 0, 0, 0); __builtin_amdgcn_s_setprio(0); } while (0)
; #define PG8_WAIT_V(n) asm volatile("s_waitcnt vmcnt(" #n ")" ::: "memory")
; #define PG8_WAIT_L(n) asm volatile("s_waitcnt lgkmcnt(" #n ")" ::: "memory")
; #define PG8_BAR __builtin_amdgcn_s_barrier()
; #define PG8_SCHED __builtin_amdgcn_sched_barrier(0)
; template <class Epi, class Sched, bool ALIGN_EPI = false, bool SP2 = false>
; __device__ __forceinline__ void gemm_phase(PG8_LAS unsigned char* lds, const Gemm g, const Sched& S, const Epi& E, const int wave0) {
;     ...
;             PG8_LDB(B0, 1, 0); PG8_LDB(B1, 1, 1); PG8_SCHED; PG8_LDA(At, 1, 0); PG8_STAGE(PG8_SA(0, 1), a2 + hstepA, voffA);
;             PG8_WAIT_V(8); PG8_WAIT_L(0); PG8_BAR; PG8_MMA(0, 0, At, B0); PG8_MMA(0, 1, At, B1); PG8_BAR; PG8_SCHED;
;             PG8_LDA(At, 1, 1); PG8_STAGE(PG8_SB(1, 0), b3, voffB); PG8_STAGE(PG8_SB(1, 1), b3 + hstepB, voffB); PG8_STAGE(PG8_SA(1, 0), a3, voffA);
;             PG8_WAIT_V(8); PG8_WAIT_L(0); PG8_BAR; PG8_MMA(1, 0, At, B0); PG8_MMA(1, 1, At, B1); PG8_BAR; PG8_SCHED;
	ds_read_b128 v[144:147], v254
	ds_read_b128 v[148:151], v254 offset:1024
	ds_read_b128 v[152:155], v254 offset:2048
	ds_read_b128 v[156:159], v254 offset:3072
	ds_read_b128 v[178:181], v255
	ds_read_b128 v[182:185], v255 offset:1024
	ds_read_b128 v[186:189], v255 offset:2048
	ds_read_b128 v[190:193], v255 offset:3072
	ds_read_b128 v[194:197], v143 offset:32768
	ds_read_b128 v[208:211], v143 offset:33792
	ds_read_b128 v[212:215], v143 offset:34816
	ds_read_b128 v[216:219], v143 offset:35840
	ds_read_b128 v[220:223], v143 offset:36864
	ds_read_b128 v[224:227], v143 offset:37888
	ds_read_b128 v[228:231], v143 offset:38912
	ds_read_b128 v[232:235], v143 offset:39936
	s_add_i32 s43, 0, 0x18000
	s_add_i32 s44, 0, 0x1c000
	s_add_u32 s18, s18, 0x200000
	s_addc_u32 s19, s19, 0
	s_mov_b32 m0, s26
	s_nop 0
	global_load_lds_dwordx4 v134, s[18:19]
	s_mov_b32 m0, s27
	s_nop 0
	global_load_lds_dwordx4 v132, s[18:19]
	s_waitcnt vmcnt(8)
	s_waitcnt lgkmcnt(0)
	s_barrier
	s_setprio 1
	s_waitcnt lgkmcnt(0)
	v_mfma_f32_16x16x32_bf16 v[126:129], v[144:147], v[194:197], v[126:129]
	v_mfma_f32_16x16x32_bf16 v[122:125], v[152:155], v[194:197], v[122:125]
	v_mfma_f32_16x16x32_bf16 v[118:121], v[144:147], v[212:215], v[118:121]
	v_mfma_f32_16x16x32_bf16 v[114:117], v[152:155], v[212:215], v[114:117]
	v_mfma_f32_16x16x32_bf16 v[102:105], v[144:147], v[220:223], v[102:105]
	v_mfma_f32_16x16x32_bf16 v[98:101], v[152:155], v[220:223], v[98:101]
	v_mfma_f32_16x16x32_bf16 v[86:89], v[144:147], v[228:231], v[86:89]
	v_mfma_f32_16x16x32_bf16 v[82:85], v[152:155], v[228:231], v[82:85]
	v_mfma_f32_16x16x32_bf16 v[126:129], v[148:151], v[208:211], v[126:129]
	v_mfma_f32_16x16x32_bf16 v[122:125], v[156:159], v[208:211], v[122:125]
	v_mfma_f32_16x16x32_bf16 v[118:121], v[148:151], v[216:219], v[118:121]
	v_mfma_f32_16x16x32_bf16 v[114:117], v[156:159], v[216:219], v[114:117]
	v_mfma_f32_16x16x32_bf16 v[102:105], v[148:151], v[224:227], v[102:105]
	v_mfma_f32_16x16x32_bf16 v[98:101], v[156:159], v[224:227], v[98:101]
	v_mfma_f32_16x16x32_bf16 v[86:89], v[148:151], v[232:235], v[86:89]
	v_mfma_f32_16x16x32_bf16 v[82:85], v[156:159], v[232:235], v[82:85]
	s_setprio 0
	s_setprio 1
	v_mfma_f32_16x16x32_bf16 v[110:113], v[178:181], v[194:197], v[110:113]
	v_mfma_f32_16x16x32_bf16 v[106:109], v[186:189], v[194:197], v[106:109]
	v_mfma_f32_16x16x32_bf16 v[94:97], v[178:181], v[212:215], v[94:97]
	v_mfma_f32_16x16x32_bf16 v[90:93], v[186:189], v[212:215], v[90:93]
	v_mfma_f32_16x16x32_bf16 v[78:81], v[178:181], v[220:223], v[78:81]
	v_mfma_f32_16x16x32_bf16 v[74:77], v[186:189], v[220:223], v[74:77]
	v_mfma_f32_16x16x32_bf16 v[70:73], v[178:181], v[228:231], v[70:73]
	v_mfma_f32_16x16x32_bf16 v[66:69], v[186:189], v[228:231], v[66:69]
	v_mfma_f32_16x16x32_bf16 v[110:113], v[182:185], v[208:211], v[110:113]
	v_mfma_f32_16x16x32_bf16 v[106:109], v[190:193], v[208:211], v[106:109]
	v_mfma_f32_16x16x32_bf16 v[94:97], v[182:185], v[216:219], v[94:97]
	v_mfma_f32_16x16x32_bf16 v[90:93], v[190:193], v[216:219], v[90:93]
	v_mfma_f32_16x16x32_bf16 v[78:81], v[182:185], v[224:227], v[78:81]
	v_mfma_f32_16x16x32_bf16 v[74:77], v[190:193], v[224:227], v[74:77]
	v_mfma_f32_16x16x32_bf16 v[70:73], v[182:185], v[232:235], v[70:73]
	v_mfma_f32_16x16x32_bf16 v[66:69], v[190:193], v[232:235], v[66:69]
	s_setprio 0
	s_barrier
	ds_read_b128 v[194:197], v143 offset:49152
	ds_read_b128 v[208:211], v143 offset:50176
	ds_read_b128 v[212:215], v143 offset:51200
	ds_read_b128 v[216:219], v143 offset:52224
	ds_read_b128 v[220:223], v143 offset:53248
	ds_read_b128 v[224:227], v143 offset:54272
	ds_read_b128 v[228:231], v143 offset:55296
	ds_read_b128 v[232:235], v143 offset:56320
	s_add_i32 s18, s43, s20
	s_add_u32 s48, s16, 0x80
	s_addc_u32 s49, s17, 0
	s_mov_b32 m0, s18
	s_nop 0
	global_load_lds_dwordx4 v64, s[48:49]
	s_add_i32 m0, s18, 0x2000
	s_add_u32 s16, s16, 0x200080
	s_addc_u32 s17, s17, 0
	s_add_i32 s18, s44, s20
	global_load_lds_dwordx4 v130, s[48:49]
	s_mov_b32 m0, s18
	s_nop 0
	global_load_lds_dwordx4 v64, s[16:17]
	s_add_i32 m0, s18, 0x2000
	s_nop 0
	global_load_lds_dwordx4 v130, s[16:17]
	s_add_u32 s100, s100, 0x80
	s_addc_u32 s101, s101, 0
	s_mov_b32 m0, s28
	s_nop 0
	global_load_lds_dwordx4 v134, s[100:101]
	s_mov_b32 m0, s29
	s_nop 0
	global_load_lds_dwordx4 v132, s[100:101]
	s_waitcnt vmcnt(8)
	s_waitcnt lgkmcnt(0)
	s_barrier
	s_setprio 1
	s_waitcnt lgkmcnt(0)
	v_mfma_f32_16x16x32_bf16 v[60:63], v[144:147], v[194:197], v[60:63]
	v_mfma_f32_16x16x32_bf16 v[56:59], v[152:155], v[194:197], v[56:59]
	v_mfma_f32_16x16x32_bf16 v[52:55], v[144:147], v[212:215], v[52:55]
	v_mfma_f32_16x16x32_bf16 v[48:51], v[152:155], v[212:215], v[48:51]
	v_mfma_f32_16x16x32_bf16 v[36:39], v[144:147], v[220:223], v[36:39]
	v_mfma_f32_16x16x32_bf16 v[32:35], v[152:155], v[220:223], v[32:35]
	v_mfma_f32_16x16x32_bf16 v[20:23], v[144:147], v[228:231], v[20:23]
	v_mfma_f32_16x16x32_bf16 v[16:19], v[152:155], v[228:231], v[16:19]
	v_mfma_f32_16x16x32_bf16 v[60:63], v[148:151], v[208:211], v[60:63]
	v_mfma_f32_16x16x32_bf16 v[56:59], v[156:159], v[208:211], v[56:59]
	v_mfma_f32_16x16x32_bf16 v[52:55], v[148:151], v[216:219], v[52:55]
	v_mfma_f32_16x16x32_bf16 v[48:51], v[156:159], v[216:219], v[48:51]
	v_mfma_f32_16x16x32_bf16 v[36:39], v[148:151], v[224:227], v[36:39]
	v_mfma_f32_16x16x32_bf16 v[32:35], v[156:159], v[224:227], v[32:35]
	v_mfma_f32_16x16x32_bf16 v[20:23], v[148:151], v[232:235], v[20:23]
	v_mfma_f32_16x16x32_bf16 v[16:19], v[156:159], v[232:235], v[16:19]
	s_setprio 0
	s_setprio 1
	v_mfma_f32_16x16x32_bf16 v[44:47], v[178:181], v[194:197], v[44:47]
	v_mfma_f32_16x16x32_bf16 v[40:43], v[186:189], v[194:197], v[40:43]
	v_mfma_f32_16x16x32_bf16 v[28:31], v[178:181], v[212:215], v[28:31]
	v_mfma_f32_16x16x32_bf16 v[24:27], v[186:189], v[212:215], v[24:27]
	v_mfma_f32_16x16x32_bf16 v[12:15], v[178:181], v[220:223], v[12:15]
	v_mfma_f32_16x16x32_bf16 v[8:11], v[186:189], v[220:223], v[8:11]
	v_mfma_f32_16x16x32_bf16 v[4:7], v[178:181], v[228:231], v[4:7]
	v_mfma_f32_16x16x32_bf16 v[0:3], v[186:189], v[228:231], v[0:3]
	v_mfma_f32_16x16x32_bf16 v[44:47], v[182:185], v[208:211], v[44:47]
	v_mfma_f32_16x16x32_bf16 v[40:43], v[190:193], v[208:211], v[40:43]
	v_mfma_f32_16x16x32_bf16 v[28:31], v[182:185], v[216:219], v[28:31]
	v_mfma_f32_16x16x32_bf16 v[24:27], v[190:193], v[216:219], v[24:27]
	v_mfma_f32_16x16x32_bf16 v[12:15], v[182:185], v[224:227], v[12:15]
	v_mfma_f32_16x16x32_bf16 v[8:11], v[190:193], v[224:227], v[8:11]
	v_mfma_f32_16x16x32_bf16 v[4:7], v[182:185], v[232:235], v[4:7]
	v_mfma_f32_16x16x32_bf16 v[0:3], v[190:193], v[232:235], v[0:3]
	s_setprio 0
	s_barrier
	s_add_i32 s42, s42, 2
	s_add_u32 s0, s0, 0x100
	s_addc_u32 s1, s1, 0
	s_add_u32 s36, s36, 0x100
	s_addc_u32 s37, s37, 0
	s_cmpk_gt_u32 s42, 0x7d
	s_cbranch_scc0 .LBB0_1685
	s_mov_b64 s[48:49], 0x80
	s_and_b64 vcc, exec, s[6:7]
	s_mov_b64 s[34:35], 0x45000
	s_cbranch_vccz .LBB0_1688
	s_barrier

; #define PG8_STAGE(bufoff, gbase, voff) do { _Pragma("unroll") for (int _i = 0; _i < 2; ++_i) \
;         __builtin_amdgcn_global_load_lds((const unsigned*)((const char*)(gbase) + (voff)[_i]), (PG8_LAS unsigned*)(lds + (bufoff) + ldsw + _i * 8192), 16, 0, 0); } while (0)
; #define PG8_LDA(dst, b, h) do { _Pragma("unroll") for (int m = 0; m < 4; ++m) _Pragma("unroll") for (int k = 0; k < 2; ++k) dst[m][k] = *(const PG8_LAS bf16x8*)(lds + PG8_SA(b, h) + aoff + m * 2048 + k * 1024); } while (0)
; #define PG8_LDB(dst, b, h) do { _Pragma("unroll") for (int n = 0; n < 2; ++n) _Pragma("unroll") for (int k = 0; k < 2; ++k) dst[n][k] = *(const PG8_LAS bf16x8*)(lds + PG8_SB(b, h) + boff + n * 2048 + k * 1024); } while (0)
; #define PG8_MMA(ai, bj, At, Bt) do { __builtin_amdgcn_s_setprio(1); _Pragma("unroll") for (int m = 0; m < 4; ++m) _Pragma("unroll") for (int n = 0; n < 2; ++n) _Pragma("unroll") for (int k = 0; k < 2; ++k) \
;         acc[ai][bj][m][n] = __builtin_amdgcn_mfma_f32_16x16x32_bf16(Bt[n][k], At[m][k], acc[ai][bj][m][n], 0, 0, 0); __builtin_amdgcn_s_setprio(0); } while (0)
; #define PG8_WAIT_V(n) asm volatile("s_waitcnt vmcnt(" #n ")" ::: "memory")
; #define PG8_BAR __builtin_amdgcn_s_barrier()
; template <class Epi, class Sched, bool ALIGN_EPI = false, bool SP2 = false>
; __device__ __forceinline__ void gemm_phase(PG8_LAS unsigned char* lds, const Gemm g, const Sched& S, const Epi& E, const int wave0) {
;     ...
;         for (int t = 0; t < nt; t += 2) {
;             const bool last = (t == nt - 2);
;             const char* a1 = cA + (size_t)(t + 1) * kstep;
;             const char* a2 = last ? nA : cA + (size_t)(t + 2) * kstep; const char* b2 = last ? nB : cB + (size_t)(t + 2) * kstep;
;             const char* a3 = a2 + kstep; const char* b3 = b2 + kstep;
;             if (last && has_next) S.a_ready(nxt);
;             if constexpr (SP2) {
;             PG8_LDB(B0, 0, 0); PG8_LDB(B1, 0, 1); PG8_SCHED; PG8_LDA(At, 0, 0); PG8_STAGE(PG8_SA(1, 1), a1 + hstepA, voffA);
;             PG8_WAIT_V(8); PG8_WAIT_L(0); PG8_BAR; PG8_MMA(0, 0, At, B0); PG8_MMA(0, 1, At, B1); PG8_BAR; PG8_SCHED;
;             PG8_LDA(At, 0, 1); PG8_STAGE(PG8_SB(0, 0), b2, voffB); PG8_STAGE(PG8_SB(0, 1), b2 + hstepB, voffB); PG8_STAGE(PG8_SA(0, 0), a2, voffA);
;             PG8_WAIT_V(8); PG8_WAIT_L(0); PG8_BAR; PG8_MMA(1, 0, At, B0); PG8_MMA(1, 1, At, B1); PG8_BAR; PG8_SCHED;
.LBB0_1702:
	ds_read_b128 v[144:147], v252
	ds_read_b128 v[148:151], v252 offset:1024
	ds_read_b128 v[152:155], v252 offset:2048
	ds_read_b128 v[156:159], v252 offset:3072
	ds_read_b128 v[178:181], v253
	ds_read_b128 v[182:185], v253 offset:1024
	ds_read_b128 v[186:189], v253 offset:2048
	ds_read_b128 v[190:193], v253 offset:3072
	ds_read_b128 v[194:197], v143
	ds_read_b128 v[208:211], v143 offset:1024
	ds_read_b128 v[212:215], v143 offset:2048
	ds_read_b128 v[216:219], v143 offset:3072
	ds_read_b128 v[220:223], v143 offset:4096
	ds_read_b128 v[224:227], v143 offset:5120
	ds_read_b128 v[228:231], v143 offset:6144
	ds_read_b128 v[232:235], v143 offset:7168
	s_add_u32 s18, s16, 0xffe00080
	s_addc_u32 s19, s17, -1
	s_add_i32 s44, 0, 0x10000
	s_cmp_eq_u32 s43, 12
	s_cselect_b32 s21, s9, s19
	s_cselect_b32 s20, s11, s18
	s_cselect_b32 s19, s13, s42
	s_cselect_b32 s18, s38, s39
	s_add_i32 s46, 0, 0x14000
	s_add_i32 m0, s28, 0xc000
	s_nop 0
	global_load_lds_dwordx4 v136, s[16:17]
	s_add_i32 m0, s28, 0xe000
	s_nop 0
	global_load_lds_dwordx4 v138, s[16:17]
	s_waitcnt vmcnt(8)
	s_waitcnt lgkmcnt(0)
	s_barrier
	s_setprio 1
	s_waitcnt lgkmcnt(0)
	v_mfma_f32_16x16x32_bf16 v[126:129], v[144:147], v[194:197], v[126:129]
	v_mfma_f32_16x16x32_bf16 v[122:125], v[152:155], v[194:197], v[122:125]
	v_mfma_f32_16x16x32_bf16 v[118:121], v[144:147], v[212:215], v[118:121]
	v_mfma_f32_16x16x32_bf16 v[114:117], v[152:155], v[212:215], v[114:117]
	v_mfma_f32_16x16x32_bf16 v[102:105], v[144:147], v[220:223], v[102:105]
	v_mfma_f32_16x16x32_bf16 v[98:101], v[152:155], v[220:223], v[98:101]
	v_mfma_f32_16x16x32_bf16 v[86:89], v[144:147], v[228:231], v[86:89]
	v_mfma_f32_16x16x32_bf16 v[82:85], v[152:155], v[228:231], v[82:85]
	v_mfma_f32_16x16x32_bf16 v[126:129], v[148:151], v[208:211], v[126:129]
	v_mfma_f32_16x16x32_bf16 v[122:125], v[156:159], v[208:211], v[122:125]
	v_mfma_f32_16x16x32_bf16 v[118:121], v[148:151], v[216:219], v[118:121]
	v_mfma_f32_16x16x32_bf16 v[114:117], v[156:159], v[216:219], v[114:117]
	v_mfma_f32_16x16x32_bf16 v[102:105], v[148:151], v[224:227], v[102:105]
	v_mfma_f32_16x16x32_bf16 v[98:101], v[156:159], v[224:227], v[98:101]
	v_mfma_f32_16x16x32_bf16 v[86:89], v[148:151], v[232:235], v[86:89]
	v_mfma_f32_16x16x32_bf16 v[82:85], v[156:159], v[232:235], v[82:85]
	s_setprio 0
	s_setprio 1
	v_mfma_f32_16x16x32_bf16 v[110:113], v[178:181], v[194:197], v[110:113]
	v_mfma_f32_16x16x32_bf16 v[106:109], v[186:189], v[194:197], v[106:109]
	v_mfma_f32_16x16x32_bf16 v[94:97], v[178:181], v[212:215], v[94:97]
	v_mfma_f32_16x16x32_bf16 v[90:93], v[186:189], v[212:215], v[90:93]
	v_mfma_f32_16x16x32_bf16 v[78:81], v[178:181], v[220:223], v[78:81]
	v_mfma_f32_16x16x32_bf16 v[74:77], v[186:189], v[220:223], v[74:77]
	v_mfma_f32_16x16x32_bf16 v[70:73], v[178:181], v[228:231], v[70:73]
	v_mfma_f32_16x16x32_bf16 v[66:69], v[186:189], v[228:231], v[66:69]
	v_mfma_f32_16x16x32_bf16 v[110:113], v[182:185], v[208:211], v[110:113]
	v_mfma_f32_16x16x32_bf16 v[106:109], v[190:193], v[208:211], v[106:109]
	v_mfma_f32_16x16x32_bf16 v[94:97], v[182:185], v[216:219], v[94:97]
	v_mfma_f32_16x16x32_bf16 v[90:93], v[190:193], v[216:219], v[90:93]
	v_mfma_f32_16x16x32_bf16 v[78:81], v[182:185], v[224:227], v[78:81]
	v_mfma_f32_16x16x32_bf16 v[74:77], v[190:193], v[224:227], v[74:77]
	v_mfma_f32_16x16x32_bf16 v[70:73], v[182:185], v[232:235], v[70:73]
	v_mfma_f32_16x16x32_bf16 v[66:69], v[190:193], v[232:235], v[66:69]
	s_setprio 0
	s_barrier
	ds_read_b128 v[194:197], v143 offset:16384
	ds_read_b128 v[208:211], v143 offset:17408
	ds_read_b128 v[212:215], v143 offset:18432
	ds_read_b128 v[216:219], v143 offset:19456
	ds_read_b128 v[220:223], v143 offset:20480
	ds_read_b128 v[224:227], v143 offset:21504
	ds_read_b128 v[228:231], v143 offset:22528
	ds_read_b128 v[232:235], v143 offset:23552
	s_add_i32 s44, s44, s25
	s_mov_b32 m0, s44
	s_nop 0
	global_load_lds_dwordx4 v64, s[18:19]
	s_add_i32 m0, s44, 0x2000
	s_add_u32 s44, s18, 0x200000
	s_addc_u32 s45, s19, 0
	s_add_i32 s46, s46, s25
	global_load_lds_dwordx4 v130, s[18:19]
	s_mov_b32 m0, s46
	s_mov_b64 s[100:101], s[20:21]
	global_load_lds_dwordx4 v64, s[44:45]
	s_add_i32 m0, s46, 0x2000
	s_nop 0
	global_load_lds_dwordx4 v130, s[44:45]
	s_mov_b32 m0, s28
	s_nop 0
	global_load_lds_dwordx4 v134, s[20:21]
	s_mov_b32 m0, s29
	s_nop 0
	global_load_lds_dwordx4 v132, s[20:21]
	s_waitcnt vmcnt(8)
	s_waitcnt lgkmcnt(0)
	s_barrier
	s_setprio 1
	s_waitcnt lgkmcnt(0)
	v_mfma_f32_16x16x32_bf16 v[60:63], v[144:147], v[194:197], v[60:63]
	v_mfma_f32_16x16x32_bf16 v[56:59], v[152:155], v[194:197], v[56:59]
	v_mfma_f32_16x16x32_bf16 v[52:55], v[144:147], v[212:215], v[52:55]
	v_mfma_f32_16x16x32_bf16 v[48:51], v[152:155], v[212:215], v[48:51]
	v_mfma_f32_16x16x32_bf16 v[36:39], v[144:147], v[220:223], v[36:39]
	v_mfma_f32_16x16x32_bf16 v[32:35], v[152:155], v[220:223], v[32:35]
	v_mfma_f32_16x16x32_bf16 v[20:23], v[144:147], v[228:231], v[20:23]
	v_mfma_f32_16x16x32_bf16 v[16:19], v[152:155], v[228:231], v[16:19]
	v_mfma_f32_16x16x32_bf16 v[60:63], v[148:151], v[208:211], v[60:63]
	v_mfma_f32_16x16x32_bf16 v[56:59], v[156:159], v[208:211], v[56:59]
	v_mfma_f32_16x16x32_bf16 v[52:55], v[148:151], v[216:219], v[52:55]
	v_mfma_f32_16x16x32_bf16 v[48:51], v[156:159], v[216:219], v[48:51]
	v_mfma_f32_16x16x32_bf16 v[36:39], v[148:151], v[224:227], v[36:39]
	v_mfma_f32_16x16x32_bf16 v[32:35], v[156:159], v[224:227], v[32:35]
	v_mfma_f32_16x16x32_bf16 v[20:23], v[148:151], v[232:235], v[20:23]
	v_mfma_f32_16x16x32_bf16 v[16:19], v[156:159], v[232:235], v[16:19]
	s_setprio 0
	s_setprio 1
	v_mfma_f32_16x16x32_bf16 v[44:47], v[178:181], v[194:197], v[44:47]
	v_mfma_f32_16x16x32_bf16 v[40:43], v[186:189], v[194:197], v[40:43]
	v_mfma_f32_16x16x32_bf16 v[28:31], v[178:181], v[212:215], v[28:31]
	v_mfma_f32_16x16x32_bf16 v[24:27], v[186:189], v[212:215], v[24:27]
	v_mfma_f32_16x16x32_bf16 v[12:15], v[178:181], v[220:223], v[12:15]
	v_mfma_f32_16x16x32_bf16 v[8:11], v[186:189], v[220:223], v[8:11]
	v_mfma_f32_16x16x32_bf16 v[4:7], v[178:181], v[228:231], v[4:7]
	v_mfma_f32_16x16x32_bf16 v[0:3], v[186:189], v[228:231], v[0:3]
	v_mfma_f32_16x16x32_bf16 v[44:47], v[182:185], v[208:211], v[44:47]
	v_mfma_f32_16x16x32_bf16 v[40:43], v[190:193], v[208:211], v[40:43]
	v_mfma_f32_16x16x32_bf16 v[28:31], v[182:185], v[216:219], v[28:31]
	v_mfma_f32_16x16x32_bf16 v[24:27], v[190:193], v[216:219], v[24:27]
	v_mfma_f32_16x16x32_bf16 v[12:15], v[182:185], v[224:227], v[12:15]
	v_mfma_f32_16x16x32_bf16 v[8:11], v[190:193], v[224:227], v[8:11]
	v_mfma_f32_16x16x32_bf16 v[4:7], v[182:185], v[232:235], v[4:7]
	v_mfma_f32_16x16x32_bf16 v[0:3], v[190:193], v[232:235], v[0:3]
	s_setprio 0
	s_barrier
; #define PG8_STAGE(bufoff, gbase, voff) do { _Pragma("unroll") for (int _i = 0; _i < 2; ++_i) \
;         __builtin_amdgcn_global_load_lds((const unsigned*)((const char*)(gbase) + (voff)[_i]), (PG8_LAS unsigned*)(lds + (bufoff) + ldsw + _i * 8192), 16, 0, 0); } while (0)
; #define PG8_LDA(dst, b, h) do { _Pragma("unroll") for (int m = 0; m < 4; ++m) _Pragma("unroll") for (int k = 0; k < 2; ++k) dst[m][k] = *(const PG8_LAS bf16x8*)(lds + PG8_SA(b, h) + aoff + m * 2048 + k * 1024); } while (0)
; #define PG8_LDB(dst, b, h) do { _Pragma("unroll") for (int n = 0; n < 2; ++n) _Pragma("unroll") for (int k = 0; k < 2; ++k) dst[n][k] = *(const PG8_LAS bf16x8*)(lds + PG8_SB(b, h) + boff + n * 2048 + k * 1024); } while (0)
; #define PG8_MMA(ai, bj, At, Bt) do { __builtin_amdgcn_s_setprio(1); _Pragma("unroll") for (int m = 0; m < 4; ++m) _Pragma("unroll") for (int n = 0; n < 2; ++n) _Pragma("unroll") for (int k = 0; k < 2; ++k) \
;         acc[ai][bj][m][n] = __builtin_amdgcn_mfma_f32_16x16x32_bf16(Bt[n][k], At[m][k], acc[ai][bj][m][n], 0, 0, 0); __builtin_amdgcn_s_setprio(0); } while (0)
; #define PG8_WAIT_V(n) asm volatile("s_waitcnt vmcnt(" #n ")" ::: "memory")
; #define PG8_WAIT_L(n) asm volatile("s_waitcnt lgkmcnt(" #n ")" ::: "memory")
; #define PG8_BAR __builtin_amdgcn_s_barrier()
; #define PG8_SCHED __builtin_amdgcn_sched_barrier(0)
; template <class Epi, class Sched, bool ALIGN_EPI = false, bool SP2 = false>
; __device__ __forceinline__ void gemm_phase(PG8_LAS unsigned char* lds, const Gemm g, const Sched& S, const Epi& E, const int wave0) {
;     ...
;             PG8_LDB(B0, 1, 0); PG8_LDB(B1, 1, 1); PG8_SCHED; PG8_LDA(At, 1, 0); PG8_STAGE(PG8_SA(0, 1), a2 + hstepA, voffA);
;             PG8_WAIT_V(8); PG8_WAIT_L(0); PG8_BAR; PG8_MMA(0, 0, At, B0); PG8_MMA(0, 1, At, B1); PG8_BAR; PG8_SCHED;
;             PG8_LDA(At, 1, 1); PG8_STAGE(PG8_SB(1, 0), b3, voffB); PG8_STAGE(PG8_SB(1, 1), b3 + hstepB, voffB); PG8_STAGE(PG8_SA(1, 0), a3, voffA);
;             PG8_WAIT_V(8); PG8_WAIT_L(0); PG8_BAR; PG8_MMA(1, 0, At, B0); PG8_MMA(1, 1, At, B1); PG8_BAR; PG8_SCHED;
	ds_read_b128 v[144:147], v254
	ds_read_b128 v[148:151], v254 offset:1024
	ds_read_b128 v[152:155], v254 offset:2048
	ds_read_b128 v[156:159], v254 offset:3072
	ds_read_b128 v[178:181], v255
	ds_read_b128 v[182:185], v255 offset:1024
	ds_read_b128 v[186:189], v255 offset:2048
	ds_read_b128 v[190:193], v255 offset:3072
	ds_read_b128 v[194:197], v143 offset:32768
	ds_read_b128 v[208:211], v143 offset:33792
	ds_read_b128 v[212:215], v143 offset:34816
	ds_read_b128 v[216:219], v143 offset:35840
	ds_read_b128 v[220:223], v143 offset:36864
	ds_read_b128 v[224:227], v143 offset:37888
	ds_read_b128 v[228:231], v143 offset:38912
	ds_read_b128 v[232:235], v143 offset:39936
	s_add_i32 s44, 0, 0x18000
	s_add_i32 s45, 0, 0x1c000
	s_add_u32 s20, s20, 0x200000
	s_addc_u32 s21, s21, 0
	s_mov_b32 m0, s30
	s_nop 0
	global_load_lds_dwordx4 v134, s[20:21]
	s_mov_b32 m0, s31
	s_nop 0
	global_load_lds_dwordx4 v132, s[20:21]
	s_waitcnt vmcnt(8)
	s_waitcnt lgkmcnt(0)
	s_barrier
	s_setprio 1
	s_waitcnt lgkmcnt(0)
	v_mfma_f32_16x16x32_bf16 v[126:129], v[144:147], v[194:197], v[126:129]
	v_mfma_f32_16x16x32_bf16 v[122:125], v[152:155], v[194:197], v[122:125]
	v_mfma_f32_16x16x32_bf16 v[118:121], v[144:147], v[212:215], v[118:121]
	v_mfma_f32_16x16x32_bf16 v[114:117], v[152:155], v[212:215], v[114:117]
	v_mfma_f32_16x16x32_bf16 v[102:105], v[144:147], v[220:223], v[102:105]
	v_mfma_f32_16x16x32_bf16 v[98:101], v[152:155], v[220:223], v[98:101]
	v_mfma_f32_16x16x32_bf16 v[86:89], v[144:147], v[228:231], v[86:89]
	v_mfma_f32_16x16x32_bf16 v[82:85], v[152:155], v[228:231], v[82:85]
	v_mfma_f32_16x16x32_bf16 v[126:129], v[148:151], v[208:211], v[126:129]
	v_mfma_f32_16x16x32_bf16 v[122:125], v[156:159], v[208:211], v[122:125]
	v_mfma_f32_16x16x32_bf16 v[118:121], v[148:151], v[216:219], v[118:121]
	v_mfma_f32_16x16x32_bf16 v[114:117], v[156:159], v[216:219], v[114:117]
	v_mfma_f32_16x16x32_bf16 v[102:105], v[148:151], v[224:227], v[102:105]
	v_mfma_f32_16x16x32_bf16 v[98:101], v[156:159], v[224:227], v[98:101]
	v_mfma_f32_16x16x32_bf16 v[86:89], v[148:151], v[232:235], v[86:89]
	v_mfma_f32_16x16x32_bf16 v[82:85], v[156:159], v[232:235], v[82:85]
	s_setprio 0
	s_setprio 1
	v_mfma_f32_16x16x32_bf16 v[110:113], v[178:181], v[194:197], v[110:113]
	v_mfma_f32_16x16x32_bf16 v[106:109], v[186:189], v[194:197], v[106:109]
	v_mfma_f32_16x16x32_bf16 v[94:97], v[178:181], v[212:215], v[94:97]
	v_mfma_f32_16x16x32_bf16 v[90:93], v[186:189], v[212:215], v[90:93]
	v_mfma_f32_16x16x32_bf16 v[78:81], v[178:181], v[220:223], v[78:81]
	v_mfma_f32_16x16x32_bf16 v[74:77], v[186:189], v[220:223], v[74:77]
	v_mfma_f32_16x16x32_bf16 v[70:73], v[178:181], v[228:231], v[70:73]
	v_mfma_f32_16x16x32_bf16 v[66:69], v[186:189], v[228:231], v[66:69]
	v_mfma_f32_16x16x32_bf16 v[110:113], v[182:185], v[208:211], v[110:113]
	v_mfma_f32_16x16x32_bf16 v[106:109], v[190:193], v[208:211], v[106:109]
	v_mfma_f32_16x16x32_bf16 v[94:97], v[182:185], v[216:219], v[94:97]
	v_mfma_f32_16x16x32_bf16 v[90:93], v[190:193], v[216:219], v[90:93]
	v_mfma_f32_16x16x32_bf16 v[78:81], v[182:185], v[224:227], v[78:81]
	v_mfma_f32_16x16x32_bf16 v[74:77], v[190:193], v[224:227], v[74:77]
	v_mfma_f32_16x16x32_bf16 v[70:73], v[182:185], v[232:235], v[70:73]
	v_mfma_f32_16x16x32_bf16 v[66:69], v[190:193], v[232:235], v[66:69]
	s_setprio 0
	s_barrier
	ds_read_b128 v[194:197], v143 offset:49152
	ds_read_b128 v[208:211], v143 offset:50176
	ds_read_b128 v[212:215], v143 offset:51200
	ds_read_b128 v[216:219], v143 offset:52224
	ds_read_b128 v[220:223], v143 offset:53248
	ds_read_b128 v[224:227], v143 offset:54272
	ds_read_b128 v[228:231], v143 offset:55296
	ds_read_b128 v[232:235], v143 offset:56320
	s_add_i32 s20, s44, s25
	s_add_u32 s48, s18, 0x80
	s_addc_u32 s49, s19, 0
	s_mov_b32 m0, s20
	s_nop 0
	global_load_lds_dwordx4 v64, s[48:49]
	s_add_i32 m0, s20, 0x2000
	s_add_u32 s18, s18, 0x200080
	s_addc_u32 s19, s19, 0
	s_add_i32 s20, s45, s25
	global_load_lds_dwordx4 v130, s[48:49]
	s_mov_b32 m0, s20
	s_nop 0
	global_load_lds_dwordx4 v64, s[18:19]
	s_add_i32 m0, s20, 0x2000
	s_nop 0
	global_load_lds_dwordx4 v130, s[18:19]
	s_add_u32 s100, s100, 0x80
	s_addc_u32 s101, s101, 0
	s_mov_b32 m0, s33
	s_nop 0
	global_load_lds_dwordx4 v134, s[100:101]
	s_mov_b32 m0, s34
	s_nop 0
	global_load_lds_dwordx4 v132, s[100:101]
	s_waitcnt vmcnt(8)
	s_waitcnt lgkmcnt(0)
	s_barrier
	s_setprio 1
	s_waitcnt lgkmcnt(0)
	v_mfma_f32_16x16x32_bf16 v[60:63], v[144:147], v[194:197], v[60:63]
	v_mfma_f32_16x16x32_bf16 v[56:59], v[152:155], v[194:197], v[56:59]
	v_mfma_f32_16x16x32_bf16 v[52:55], v[144:147], v[212:215], v[52:55]
	v_mfma_f32_16x16x32_bf16 v[48:51], v[152:155], v[212:215], v[48:51]
	v_mfma_f32_16x16x32_bf16 v[36:39], v[144:147], v[220:223], v[36:39]
	v_mfma_f32_16x16x32_bf16 v[32:35], v[152:155], v[220:223], v[32:35]
	v_mfma_f32_16x16x32_bf16 v[20:23], v[144:147], v[228:231], v[20:23]
	v_mfma_f32_16x16x32_bf16 v[16:19], v[152:155], v[228:231], v[16:19]
	v_mfma_f32_16x16x32_bf16 v[60:63], v[148:151], v[208:211], v[60:63]
	v_mfma_f32_16x16x32_bf16 v[56:59], v[156:159], v[208:211], v[56:59]
	v_mfma_f32_16x16x32_bf16 v[52:55], v[148:151], v[216:219], v[52:55]
	v_mfma_f32_16x16x32_bf16 v[48:51], v[156:159], v[216:219], v[48:51]
	v_mfma_f32_16x16x32_bf16 v[36:39], v[148:151], v[224:227], v[36:39]
	v_mfma_f32_16x16x32_bf16 v[32:35], v[156:159], v[224:227], v[32:35]
	v_mfma_f32_16x16x32_bf16 v[20:23], v[148:151], v[232:235], v[20:23]
	v_mfma_f32_16x16x32_bf16 v[16:19], v[156:159], v[232:235], v[16:19]
	s_setprio 0
	s_setprio 1
	v_mfma_f32_16x16x32_bf16 v[44:47], v[178:181], v[194:197], v[44:47]
	v_mfma_f32_16x16x32_bf16 v[40:43], v[186:189], v[194:197], v[40:43]
	v_mfma_f32_16x16x32_bf16 v[28:31], v[178:181], v[212:215], v[28:31]
	v_mfma_f32_16x16x32_bf16 v[24:27], v[186:189], v[212:215], v[24:27]
	v_mfma_f32_16x16x32_bf16 v[12:15], v[178:181], v[220:223], v[12:15]
	v_mfma_f32_16x16x32_bf16 v[8:11], v[186:189], v[220:223], v[8:11]
	v_mfma_f32_16x16x32_bf16 v[4:7], v[178:181], v[228:231], v[4:7]
	v_mfma_f32_16x16x32_bf16 v[0:3], v[186:189], v[228:231], v[0:3]
	v_mfma_f32_16x16x32_bf16 v[44:47], v[182:185], v[208:211], v[44:47]
	v_mfma_f32_16x16x32_bf16 v[40:43], v[190:193], v[208:211], v[40:43]
	v_mfma_f32_16x16x32_bf16 v[28:31], v[182:185], v[216:219], v[28:31]
	v_mfma_f32_16x16x32_bf16 v[24:27], v[190:193], v[216:219], v[24:27]
	v_mfma_f32_16x16x32_bf16 v[12:15], v[182:185], v[224:227], v[12:15]
	v_mfma_f32_16x16x32_bf16 v[8:11], v[190:193], v[224:227], v[8:11]
	v_mfma_f32_16x16x32_bf16 v[4:7], v[182:185], v[232:235], v[4:7]
	v_mfma_f32_16x16x32_bf16 v[0:3], v[190:193], v[232:235], v[0:3]
	s_setprio 0
	s_barrier
	s_add_i32 s43, s43, 2
	s_add_u32 s16, s16, 0x100
	s_addc_u32 s17, s17, 0
	s_add_u32 s39, s39, 0x100
	s_addc_u32 s42, s42, 0
	s_cmp_gt_u32 s43, 13
	s_cbranch_scc0 .LBB0_1702
	s_mov_b64 s[48:49], 0x80
	s_and_b64 vcc, exec, s[6:7]
	s_cbranch_vccz .LBB0_1705
	s_barrier
